# v55 + sc1 (L1 bypass) on the K-loop LDS-DMA loads
# baseline (speedup 1.0000x reference)
.LBB0_261:
	s_add_u32 s0, s76, 0xfff80080
	s_addc_u32 s1, s77, -1
	s_and_b64 s[84:85], s[84:85], exec
	s_cselect_b32 vcc_hi, s22, s1
	s_cselect_b32 vcc_lo, s23, s0
	s_cselect_b32 s85, s49, s58
	s_cselect_b32 s84, s57, s51
	s_add_i32 s0, 0, 0x10000
	s_add_i32 s1, 0, 0x14000
	v_add_u32_e32 v158, s0, v176
	v_add_u32_e32 v174, s1, v176
	ds_read_b128 v[146:149], v158
	ds_read_b128 v[150:153], v158 offset:1024
	ds_read_b128 v[154:157], v158 offset:2048
	ds_read_b128 v[158:161], v158 offset:3072
	ds_read_b128 v[162:165], v174
	ds_read_b128 v[166:169], v174 offset:1024
	ds_read_b128 v[170:173], v174 offset:2048
	ds_read_b128 v[178:181], v174 offset:3072
	s_add_i32 m0, s21, 0xc000
	ds_read_b128 v[182:185], v177
	ds_read_b128 v[186:189], v177 offset:1024
	ds_read_b128 v[190:193], v177 offset:2048
	ds_read_b128 v[204:207], v177 offset:3072
	ds_read_b128 v[208:211], v177 offset:4096
	ds_read_b128 v[212:215], v177 offset:5120
	ds_read_b128 v[216:219], v177 offset:6144
	ds_read_b128 v[220:223], v177 offset:7168
	global_load_lds_dwordx4 v138, s[76:77] sc1
	s_add_i32 m0, s21, 0xe000
	s_nop 0
	global_load_lds_dwordx4 v140, s[76:77] sc1
	s_waitcnt vmcnt(8)
	s_waitcnt lgkmcnt(0)
	s_barrier
	s_waitcnt lgkmcnt(0)
	v_mfma_f32_16x16x32_bf16 v[126:129], v[146:149], v[182:185], v[126:129]
	v_mfma_f32_16x16x32_bf16 v[126:129], v[150:153], v[186:189], v[126:129]
	v_mfma_f32_16x16x32_bf16 v[122:125], v[158:161], v[186:189], v[122:125]
	v_mfma_f32_16x16x32_bf16 v[122:125], v[154:157], v[182:185], v[122:125]
	v_mfma_f32_16x16x32_bf16 v[118:121], v[162:165], v[182:185], v[118:121]
	v_mfma_f32_16x16x32_bf16 v[118:121], v[166:169], v[186:189], v[118:121]
	v_mfma_f32_16x16x32_bf16 v[114:117], v[178:181], v[186:189], v[114:117]
	v_mfma_f32_16x16x32_bf16 v[114:117], v[170:173], v[182:185], v[114:117]
	v_mfma_f32_16x16x32_bf16 v[98:101], v[170:173], v[190:193], v[98:101]
	v_mfma_f32_16x16x32_bf16 v[98:101], v[178:181], v[204:207], v[98:101]
	v_mfma_f32_16x16x32_bf16 v[102:105], v[166:169], v[204:207], v[102:105]
	v_mfma_f32_16x16x32_bf16 v[102:105], v[162:165], v[190:193], v[102:105]
	v_mfma_f32_16x16x32_bf16 v[106:109], v[154:157], v[190:193], v[106:109]
	v_mfma_f32_16x16x32_bf16 v[106:109], v[158:161], v[204:207], v[106:109]
	v_mfma_f32_16x16x32_bf16 v[110:113], v[150:153], v[204:207], v[110:113]
	v_mfma_f32_16x16x32_bf16 v[110:113], v[146:149], v[190:193], v[110:113]
	v_mfma_f32_16x16x32_bf16 v[94:97], v[146:149], v[208:211], v[94:97]
	v_mfma_f32_16x16x32_bf16 v[94:97], v[150:153], v[212:215], v[94:97]
	v_mfma_f32_16x16x32_bf16 v[90:93], v[158:161], v[212:215], v[90:93]
	v_mfma_f32_16x16x32_bf16 v[90:93], v[154:157], v[208:211], v[90:93]
	v_mfma_f32_16x16x32_bf16 v[86:89], v[162:165], v[208:211], v[86:89]
	v_mfma_f32_16x16x32_bf16 v[86:89], v[166:169], v[212:215], v[86:89]
	v_mfma_f32_16x16x32_bf16 v[82:85], v[178:181], v[212:215], v[82:85]
	v_mfma_f32_16x16x32_bf16 v[82:85], v[170:173], v[208:211], v[82:85]
	v_mfma_f32_16x16x32_bf16 v[66:69], v[170:173], v[216:219], v[66:69]
	v_mfma_f32_16x16x32_bf16 v[66:69], v[178:181], v[220:223], v[66:69]
	v_mfma_f32_16x16x32_bf16 v[70:73], v[166:169], v[220:223], v[70:73]
	v_mfma_f32_16x16x32_bf16 v[70:73], v[162:165], v[216:219], v[70:73]
	v_mfma_f32_16x16x32_bf16 v[74:77], v[154:157], v[216:219], v[74:77]
	v_mfma_f32_16x16x32_bf16 v[74:77], v[158:161], v[220:223], v[74:77]
	v_mfma_f32_16x16x32_bf16 v[78:81], v[150:153], v[220:223], v[78:81]
	v_mfma_f32_16x16x32_bf16 v[78:81], v[146:149], v[216:219], v[78:81]
	s_barrier
	s_add_i32 s0, s0, s20
	s_mov_b32 m0, s0
	ds_read_b128 v[182:185], v177 offset:16384
	ds_read_b128 v[186:189], v177 offset:17408
	ds_read_b128 v[190:193], v177 offset:18432
	ds_read_b128 v[204:207], v177 offset:19456
	ds_read_b128 v[208:211], v177 offset:20480
	ds_read_b128 v[212:215], v177 offset:21504
	ds_read_b128 v[216:219], v177 offset:22528
	ds_read_b128 v[220:223], v177 offset:23552
	global_load_lds_dwordx4 v132, s[84:85] sc1
	s_add_i32 m0, s0, 0x2000
	s_add_u32 s94, s84, 0x80000
	s_addc_u32 s95, s85, 0
	s_add_i32 s0, s1, s20
	global_load_lds_dwordx4 v130, s[84:85] sc1
	s_mov_b32 m0, s0
	s_nop 0
	global_load_lds_dwordx4 v132, s[94:95] sc1
	s_add_i32 m0, s0, 0x2000
	s_nop 0
	global_load_lds_dwordx4 v130, s[94:95] sc1
	s_mov_b32 m0, s21
	s_nop 0
	global_load_lds_dwordx4 v132, vcc sc1
	s_mov_b32 m0, s26
	s_nop 0
	global_load_lds_dwordx4 v130, vcc sc1
	s_waitcnt vmcnt(8)
	s_waitcnt lgkmcnt(0)
	s_barrier
	s_waitcnt lgkmcnt(0)
	v_mfma_f32_16x16x32_bf16 v[62:65], v[146:149], v[182:185], v[62:65]
	v_mfma_f32_16x16x32_bf16 v[62:65], v[150:153], v[186:189], v[62:65]
	v_mfma_f32_16x16x32_bf16 v[58:61], v[158:161], v[186:189], v[58:61]
	v_mfma_f32_16x16x32_bf16 v[58:61], v[154:157], v[182:185], v[58:61]
	v_mfma_f32_16x16x32_bf16 v[54:57], v[162:165], v[182:185], v[54:57]
	v_mfma_f32_16x16x32_bf16 v[54:57], v[166:169], v[186:189], v[54:57]
	v_mfma_f32_16x16x32_bf16 v[50:53], v[178:181], v[186:189], v[50:53]
	v_mfma_f32_16x16x32_bf16 v[50:53], v[170:173], v[182:185], v[50:53]
	v_mfma_f32_16x16x32_bf16 v[34:37], v[170:173], v[190:193], v[34:37]
	v_mfma_f32_16x16x32_bf16 v[34:37], v[178:181], v[204:207], v[34:37]
	v_mfma_f32_16x16x32_bf16 v[38:41], v[166:169], v[204:207], v[38:41]
	v_mfma_f32_16x16x32_bf16 v[38:41], v[162:165], v[190:193], v[38:41]
	v_mfma_f32_16x16x32_bf16 v[42:45], v[154:157], v[190:193], v[42:45]
	v_mfma_f32_16x16x32_bf16 v[42:45], v[158:161], v[204:207], v[42:45]
	v_mfma_f32_16x16x32_bf16 v[46:49], v[150:153], v[204:207], v[46:49]
	v_mfma_f32_16x16x32_bf16 v[46:49], v[146:149], v[190:193], v[46:49]
	v_mfma_f32_16x16x32_bf16 v[30:33], v[146:149], v[208:211], v[30:33]
	v_mfma_f32_16x16x32_bf16 v[30:33], v[150:153], v[212:215], v[30:33]
	v_mfma_f32_16x16x32_bf16 v[26:29], v[158:161], v[212:215], v[26:29]
	v_mfma_f32_16x16x32_bf16 v[26:29], v[154:157], v[208:211], v[26:29]
	v_mfma_f32_16x16x32_bf16 v[22:25], v[162:165], v[208:211], v[22:25]
	v_mfma_f32_16x16x32_bf16 v[22:25], v[166:169], v[212:215], v[22:25]
	v_mfma_f32_16x16x32_bf16 v[18:21], v[178:181], v[212:215], v[18:21]
	v_mfma_f32_16x16x32_bf16 v[18:21], v[170:173], v[208:211], v[18:21]
	v_mfma_f32_16x16x32_bf16 v[2:5], v[170:173], v[216:219], v[2:5]
	v_mfma_f32_16x16x32_bf16 v[2:5], v[178:181], v[220:223], v[2:5]
	v_mfma_f32_16x16x32_bf16 v[6:9], v[166:169], v[220:223], v[6:9]
	v_mfma_f32_16x16x32_bf16 v[6:9], v[162:165], v[216:219], v[6:9]
	v_mfma_f32_16x16x32_bf16 v[10:13], v[154:157], v[216:219], v[10:13]
	v_mfma_f32_16x16x32_bf16 v[10:13], v[158:161], v[220:223], v[10:13]
	v_mfma_f32_16x16x32_bf16 v[14:17], v[150:153], v[220:223], v[14:17]
	v_mfma_f32_16x16x32_bf16 v[14:17], v[146:149], v[216:219], v[14:17]
	s_barrier
	s_add_i32 s0, 0, 0x18000
	s_add_i32 s1, 0, 0x1c000
	v_add_u32_e32 v158, s0, v176
	v_add_u32_e32 v178, s1, v176
	ds_read_b128 v[146:149], v158
	ds_read_b128 v[150:153], v158 offset:1024
	ds_read_b128 v[154:157], v158 offset:2048
	ds_read_b128 v[158:161], v158 offset:3072
	ds_read_b128 v[162:165], v178
	ds_read_b128 v[166:169], v178 offset:1024
	ds_read_b128 v[170:173], v178 offset:2048
	ds_read_b128 v[178:181], v178 offset:3072
	s_add_u32 s94, vcc_lo, 0x80000
	s_addc_u32 s95, vcc_hi, 0
	s_mov_b32 m0, s27
	ds_read_b128 v[182:185], v177 offset:32768
	ds_read_b128 v[186:189], v177 offset:33792
	ds_read_b128 v[190:193], v177 offset:34816
	ds_read_b128 v[204:207], v177 offset:35840
	ds_read_b128 v[208:211], v177 offset:36864
	ds_read_b128 v[212:215], v177 offset:37888
	ds_read_b128 v[216:219], v177 offset:38912
	ds_read_b128 v[220:223], v177 offset:39936
	global_load_lds_dwordx4 v132, s[94:95] sc1
	s_mov_b32 m0, s29
	s_nop 0
	global_load_lds_dwordx4 v130, s[94:95] sc1
	s_waitcnt vmcnt(8)
	s_waitcnt lgkmcnt(0)
	s_barrier
	s_waitcnt lgkmcnt(0)
	v_mfma_f32_16x16x32_bf16 v[126:129], v[146:149], v[182:185], v[126:129]
	v_mfma_f32_16x16x32_bf16 v[126:129], v[150:153], v[186:189], v[126:129]
	v_mfma_f32_16x16x32_bf16 v[122:125], v[158:161], v[186:189], v[122:125]
	v_mfma_f32_16x16x32_bf16 v[122:125], v[154:157], v[182:185], v[122:125]
	v_mfma_f32_16x16x32_bf16 v[118:121], v[162:165], v[182:185], v[118:121]
	v_mfma_f32_16x16x32_bf16 v[118:121], v[166:169], v[186:189], v[118:121]
	v_mfma_f32_16x16x32_bf16 v[114:117], v[178:181], v[186:189], v[114:117]
	v_mfma_f32_16x16x32_bf16 v[114:117], v[170:173], v[182:185], v[114:117]
	v_mfma_f32_16x16x32_bf16 v[98:101], v[170:173], v[190:193], v[98:101]
	v_mfma_f32_16x16x32_bf16 v[98:101], v[178:181], v[204:207], v[98:101]
	v_mfma_f32_16x16x32_bf16 v[102:105], v[166:169], v[204:207], v[102:105]
	v_mfma_f32_16x16x32_bf16 v[102:105], v[162:165], v[190:193], v[102:105]
	v_mfma_f32_16x16x32_bf16 v[106:109], v[154:157], v[190:193], v[106:109]
	v_mfma_f32_16x16x32_bf16 v[106:109], v[158:161], v[204:207], v[106:109]
	v_mfma_f32_16x16x32_bf16 v[110:113], v[150:153], v[204:207], v[110:113]
	v_mfma_f32_16x16x32_bf16 v[110:113], v[146:149], v[190:193], v[110:113]
	v_mfma_f32_16x16x32_bf16 v[94:97], v[146:149], v[208:211], v[94:97]
	v_mfma_f32_16x16x32_bf16 v[94:97], v[150:153], v[212:215], v[94:97]
	v_mfma_f32_16x16x32_bf16 v[90:93], v[158:161], v[212:215], v[90:93]
	v_mfma_f32_16x16x32_bf16 v[90:93], v[154:157], v[208:211], v[90:93]
	v_mfma_f32_16x16x32_bf16 v[86:89], v[162:165], v[208:211], v[86:89]
	v_mfma_f32_16x16x32_bf16 v[86:89], v[166:169], v[212:215], v[86:89]
	v_mfma_f32_16x16x32_bf16 v[82:85], v[178:181], v[212:215], v[82:85]
	v_mfma_f32_16x16x32_bf16 v[82:85], v[170:173], v[208:211], v[82:85]
	v_mfma_f32_16x16x32_bf16 v[66:69], v[170:173], v[216:219], v[66:69]
	v_mfma_f32_16x16x32_bf16 v[66:69], v[178:181], v[220:223], v[66:69]
	v_mfma_f32_16x16x32_bf16 v[70:73], v[166:169], v[220:223], v[70:73]
	v_mfma_f32_16x16x32_bf16 v[70:73], v[162:165], v[216:219], v[70:73]
	v_mfma_f32_16x16x32_bf16 v[74:77], v[154:157], v[216:219], v[74:77]
	v_mfma_f32_16x16x32_bf16 v[74:77], v[158:161], v[220:223], v[74:77]
	v_mfma_f32_16x16x32_bf16 v[78:81], v[150:153], v[220:223], v[78:81]
	v_mfma_f32_16x16x32_bf16 v[78:81], v[146:149], v[216:219], v[78:81]
	s_barrier
	s_add_u32 s98, s84, 0x80
	s_addc_u32 s99, s85, 0
	s_add_u32 s100, vcc_lo, 0x80
	s_addc_u32 s101, vcc_hi, 0
	s_add_i32 s0, s0, s20
	s_mov_b32 m0, s0
	ds_read_b128 v[182:185], v177 offset:49152
	ds_read_b128 v[186:189], v177 offset:50176
	ds_read_b128 v[190:193], v177 offset:51200
	ds_read_b128 v[204:207], v177 offset:52224
	ds_read_b128 v[208:211], v177 offset:53248
	ds_read_b128 v[212:215], v177 offset:54272
	ds_read_b128 v[216:219], v177 offset:55296
	ds_read_b128 v[220:223], v177 offset:56320
	global_load_lds_dwordx4 v132, s[98:99] sc1
	s_add_i32 m0, s0, 0x2000
	s_add_u32 s84, s84, 0x80080
	s_addc_u32 s85, s85, 0
	s_add_i32 s0, s1, s20
	global_load_lds_dwordx4 v130, s[98:99] sc1
	s_mov_b32 m0, s0
	s_nop 0
	global_load_lds_dwordx4 v132, s[84:85] sc1
	s_add_i32 m0, s0, 0x2000
	s_nop 0
	global_load_lds_dwordx4 v130, s[84:85] sc1
	s_mov_b32 m0, s40
	s_nop 0
	global_load_lds_dwordx4 v132, s[100:101] sc1
	s_mov_b32 m0, s41
	s_nop 0
	global_load_lds_dwordx4 v130, s[100:101] sc1
	s_waitcnt vmcnt(8)
	s_waitcnt lgkmcnt(0)
	s_barrier
	s_waitcnt lgkmcnt(0)
	v_mfma_f32_16x16x32_bf16 v[62:65], v[146:149], v[182:185], v[62:65]
	v_mfma_f32_16x16x32_bf16 v[62:65], v[150:153], v[186:189], v[62:65]
	v_mfma_f32_16x16x32_bf16 v[58:61], v[158:161], v[186:189], v[58:61]
	v_mfma_f32_16x16x32_bf16 v[58:61], v[154:157], v[182:185], v[58:61]
	v_mfma_f32_16x16x32_bf16 v[54:57], v[162:165], v[182:185], v[54:57]
	v_mfma_f32_16x16x32_bf16 v[54:57], v[166:169], v[186:189], v[54:57]
	v_mfma_f32_16x16x32_bf16 v[50:53], v[178:181], v[186:189], v[50:53]
	v_mfma_f32_16x16x32_bf16 v[50:53], v[170:173], v[182:185], v[50:53]
	v_mfma_f32_16x16x32_bf16 v[34:37], v[170:173], v[190:193], v[34:37]
	v_mfma_f32_16x16x32_bf16 v[34:37], v[178:181], v[204:207], v[34:37]
	v_mfma_f32_16x16x32_bf16 v[38:41], v[166:169], v[204:207], v[38:41]
	v_mfma_f32_16x16x32_bf16 v[38:41], v[162:165], v[190:193], v[38:41]
	v_mfma_f32_16x16x32_bf16 v[42:45], v[154:157], v[190:193], v[42:45]
	v_mfma_f32_16x16x32_bf16 v[42:45], v[158:161], v[204:207], v[42:45]
	v_mfma_f32_16x16x32_bf16 v[46:49], v[150:153], v[204:207], v[46:49]
	v_mfma_f32_16x16x32_bf16 v[46:49], v[146:149], v[190:193], v[46:49]
	v_mfma_f32_16x16x32_bf16 v[30:33], v[146:149], v[208:211], v[30:33]
	v_mfma_f32_16x16x32_bf16 v[30:33], v[150:153], v[212:215], v[30:33]
	v_mfma_f32_16x16x32_bf16 v[26:29], v[158:161], v[212:215], v[26:29]
	v_mfma_f32_16x16x32_bf16 v[26:29], v[154:157], v[208:211], v[26:29]
	v_mfma_f32_16x16x32_bf16 v[22:25], v[162:165], v[208:211], v[22:25]
	v_mfma_f32_16x16x32_bf16 v[22:25], v[166:169], v[212:215], v[22:25]
	v_mfma_f32_16x16x32_bf16 v[18:21], v[178:181], v[212:215], v[18:21]
	v_mfma_f32_16x16x32_bf16 v[18:21], v[170:173], v[208:211], v[18:21]
	v_mfma_f32_16x16x32_bf16 v[2:5], v[170:173], v[216:219], v[2:5]
	v_mfma_f32_16x16x32_bf16 v[2:5], v[178:181], v[220:223], v[2:5]
	v_mfma_f32_16x16x32_bf16 v[6:9], v[166:169], v[220:223], v[6:9]
	v_mfma_f32_16x16x32_bf16 v[6:9], v[162:165], v[216:219], v[6:9]
	v_mfma_f32_16x16x32_bf16 v[10:13], v[154:157], v[216:219], v[10:13]
	v_mfma_f32_16x16x32_bf16 v[10:13], v[158:161], v[220:223], v[10:13]
	v_mfma_f32_16x16x32_bf16 v[14:17], v[150:153], v[220:223], v[14:17]
	v_mfma_f32_16x16x32_bf16 v[14:17], v[146:149], v[216:219], v[14:17]
	s_barrier
	s_add_i32 s65, s65, 2
	s_add_u32 s76, s76, 0x100
	s_addc_u32 s77, s77, 0
	s_add_u32 s51, s51, 0x100
	s_addc_u32 s58, s58, 0
	s_cmp_gt_u32 s65, 29
	s_cbranch_scc1 .LBB0_264

.Lpeel_disp_ine:
	s_cmp_lg_u32 s65, -2
	s_cbranch_scc1 .LBB0_261
	s_add_u32 s0, s76, 0xfff80080
	s_addc_u32 s1, s77, -1
	s_and_b64 s[84:85], s[84:85], exec
	s_cselect_b32 vcc_hi, s22, s1
	s_cselect_b32 vcc_lo, s23, s0
	s_cselect_b32 s85, s49, s58
	s_cselect_b32 s84, s57, s51
	s_add_i32 s0, 0, 0x10000
	s_add_i32 s1, 0, 0x14000
	v_add_u32_e32 v158, s0, v176
	v_add_u32_e32 v174, s1, v176
	ds_read_b128 v[146:149], v158
	ds_read_b128 v[150:153], v158 offset:1024
	ds_read_b128 v[154:157], v158 offset:2048
	ds_read_b128 v[158:161], v158 offset:3072
	ds_read_b128 v[162:165], v174
	ds_read_b128 v[166:169], v174 offset:1024
	ds_read_b128 v[170:173], v174 offset:2048
	ds_read_b128 v[178:181], v174 offset:3072
	s_add_i32 m0, s21, 0xc000
	ds_read_b128 v[182:185], v177
	ds_read_b128 v[186:189], v177 offset:1024
	ds_read_b128 v[190:193], v177 offset:2048
	ds_read_b128 v[204:207], v177 offset:3072
	ds_read_b128 v[208:211], v177 offset:4096
	ds_read_b128 v[212:215], v177 offset:5120
	ds_read_b128 v[216:219], v177 offset:6144
	ds_read_b128 v[220:223], v177 offset:7168
	global_load_lds_dwordx4 v138, s[76:77] sc1
	s_add_i32 m0, s21, 0xe000
	s_nop 0
	global_load_lds_dwordx4 v140, s[76:77] sc1
	s_waitcnt vmcnt(8)
	s_waitcnt lgkmcnt(0)
	s_barrier
	s_waitcnt lgkmcnt(0)
	v_mfma_f32_16x16x32_bf16 v[126:129], v[146:149], v[182:185], 0
	v_mfma_f32_16x16x32_bf16 v[126:129], v[150:153], v[186:189], v[126:129]
	v_mfma_f32_16x16x32_bf16 v[122:125], v[158:161], v[186:189], 0
	v_mfma_f32_16x16x32_bf16 v[122:125], v[154:157], v[182:185], v[122:125]
	v_mfma_f32_16x16x32_bf16 v[118:121], v[162:165], v[182:185], 0
	v_mfma_f32_16x16x32_bf16 v[118:121], v[166:169], v[186:189], v[118:121]
	v_mfma_f32_16x16x32_bf16 v[114:117], v[178:181], v[186:189], 0
	v_mfma_f32_16x16x32_bf16 v[114:117], v[170:173], v[182:185], v[114:117]
	v_mfma_f32_16x16x32_bf16 v[98:101], v[170:173], v[190:193], 0
	v_mfma_f32_16x16x32_bf16 v[98:101], v[178:181], v[204:207], v[98:101]
	v_mfma_f32_16x16x32_bf16 v[102:105], v[166:169], v[204:207], 0
	v_mfma_f32_16x16x32_bf16 v[102:105], v[162:165], v[190:193], v[102:105]
	v_mfma_f32_16x16x32_bf16 v[106:109], v[154:157], v[190:193], 0
	v_mfma_f32_16x16x32_bf16 v[106:109], v[158:161], v[204:207], v[106:109]
	v_mfma_f32_16x16x32_bf16 v[110:113], v[150:153], v[204:207], 0
	v_mfma_f32_16x16x32_bf16 v[110:113], v[146:149], v[190:193], v[110:113]
	v_mfma_f32_16x16x32_bf16 v[94:97], v[146:149], v[208:211], 0
	v_mfma_f32_16x16x32_bf16 v[94:97], v[150:153], v[212:215], v[94:97]
	v_mfma_f32_16x16x32_bf16 v[90:93], v[158:161], v[212:215], 0
	v_mfma_f32_16x16x32_bf16 v[90:93], v[154:157], v[208:211], v[90:93]
	v_mfma_f32_16x16x32_bf16 v[86:89], v[162:165], v[208:211], 0
	v_mfma_f32_16x16x32_bf16 v[86:89], v[166:169], v[212:215], v[86:89]
	v_mfma_f32_16x16x32_bf16 v[82:85], v[178:181], v[212:215], 0
	v_mfma_f32_16x16x32_bf16 v[82:85], v[170:173], v[208:211], v[82:85]
	v_mfma_f32_16x16x32_bf16 v[66:69], v[170:173], v[216:219], 0
	v_mfma_f32_16x16x32_bf16 v[66:69], v[178:181], v[220:223], v[66:69]
	v_mfma_f32_16x16x32_bf16 v[70:73], v[166:169], v[220:223], 0
	v_mfma_f32_16x16x32_bf16 v[70:73], v[162:165], v[216:219], v[70:73]
	v_mfma_f32_16x16x32_bf16 v[74:77], v[154:157], v[216:219], 0
	v_mfma_f32_16x16x32_bf16 v[74:77], v[158:161], v[220:223], v[74:77]
	v_mfma_f32_16x16x32_bf16 v[78:81], v[150:153], v[220:223], 0
	v_mfma_f32_16x16x32_bf16 v[78:81], v[146:149], v[216:219], v[78:81]
	s_barrier
	s_add_i32 s0, s0, s20
	s_mov_b32 m0, s0
	ds_read_b128 v[182:185], v177 offset:16384
	ds_read_b128 v[186:189], v177 offset:17408
	ds_read_b128 v[190:193], v177 offset:18432
	ds_read_b128 v[204:207], v177 offset:19456
	ds_read_b128 v[208:211], v177 offset:20480
	ds_read_b128 v[212:215], v177 offset:21504
	ds_read_b128 v[216:219], v177 offset:22528
	ds_read_b128 v[220:223], v177 offset:23552
	global_load_lds_dwordx4 v132, s[84:85] sc1
	s_add_i32 m0, s0, 0x2000
	s_add_u32 s94, s84, 0x80000
	s_addc_u32 s95, s85, 0
	s_add_i32 s0, s1, s20
	global_load_lds_dwordx4 v130, s[84:85] sc1
	s_mov_b32 m0, s0
	s_nop 0
	global_load_lds_dwordx4 v132, s[94:95] sc1
	s_add_i32 m0, s0, 0x2000
	s_nop 0
	global_load_lds_dwordx4 v130, s[94:95] sc1
	s_mov_b32 m0, s21
	s_nop 0
	global_load_lds_dwordx4 v132, vcc sc1
	s_mov_b32 m0, s26
	s_nop 0
	global_load_lds_dwordx4 v130, vcc sc1
	s_waitcnt vmcnt(8)
	s_waitcnt lgkmcnt(0)
	s_barrier
	s_waitcnt lgkmcnt(0)
	v_mfma_f32_16x16x32_bf16 v[62:65], v[146:149], v[182:185], 0
	v_mfma_f32_16x16x32_bf16 v[62:65], v[150:153], v[186:189], v[62:65]
	v_mfma_f32_16x16x32_bf16 v[58:61], v[158:161], v[186:189], 0
	v_mfma_f32_16x16x32_bf16 v[58:61], v[154:157], v[182:185], v[58:61]
	v_mfma_f32_16x16x32_bf16 v[54:57], v[162:165], v[182:185], 0
	v_mfma_f32_16x16x32_bf16 v[54:57], v[166:169], v[186:189], v[54:57]
	v_mfma_f32_16x16x32_bf16 v[50:53], v[178:181], v[186:189], 0
	v_mfma_f32_16x16x32_bf16 v[50:53], v[170:173], v[182:185], v[50:53]
	v_mfma_f32_16x16x32_bf16 v[34:37], v[170:173], v[190:193], 0
	v_mfma_f32_16x16x32_bf16 v[34:37], v[178:181], v[204:207], v[34:37]
	v_mfma_f32_16x16x32_bf16 v[38:41], v[166:169], v[204:207], 0
	v_mfma_f32_16x16x32_bf16 v[38:41], v[162:165], v[190:193], v[38:41]
	v_mfma_f32_16x16x32_bf16 v[42:45], v[154:157], v[190:193], 0
	v_mfma_f32_16x16x32_bf16 v[42:45], v[158:161], v[204:207], v[42:45]
	v_mfma_f32_16x16x32_bf16 v[46:49], v[150:153], v[204:207], 0
	v_mfma_f32_16x16x32_bf16 v[46:49], v[146:149], v[190:193], v[46:49]
	v_mfma_f32_16x16x32_bf16 v[30:33], v[146:149], v[208:211], 0
	v_mfma_f32_16x16x32_bf16 v[30:33], v[150:153], v[212:215], v[30:33]
	v_mfma_f32_16x16x32_bf16 v[26:29], v[158:161], v[212:215], 0
	v_mfma_f32_16x16x32_bf16 v[26:29], v[154:157], v[208:211], v[26:29]
	v_mfma_f32_16x16x32_bf16 v[22:25], v[162:165], v[208:211], 0
	v_mfma_f32_16x16x32_bf16 v[22:25], v[166:169], v[212:215], v[22:25]
	v_mfma_f32_16x16x32_bf16 v[18:21], v[178:181], v[212:215], 0
	v_mfma_f32_16x16x32_bf16 v[18:21], v[170:173], v[208:211], v[18:21]
	v_mfma_f32_16x16x32_bf16 v[2:5], v[170:173], v[216:219], 0
	v_mfma_f32_16x16x32_bf16 v[2:5], v[178:181], v[220:223], v[2:5]
	v_mfma_f32_16x16x32_bf16 v[6:9], v[166:169], v[220:223], 0
	v_mfma_f32_16x16x32_bf16 v[6:9], v[162:165], v[216:219], v[6:9]
	v_mfma_f32_16x16x32_bf16 v[10:13], v[154:157], v[216:219], 0
	v_mfma_f32_16x16x32_bf16 v[10:13], v[158:161], v[220:223], v[10:13]
	v_mfma_f32_16x16x32_bf16 v[14:17], v[150:153], v[220:223], 0
	v_mfma_f32_16x16x32_bf16 v[14:17], v[146:149], v[216:219], v[14:17]
	s_barrier
	s_add_i32 s0, 0, 0x18000
	s_add_i32 s1, 0, 0x1c000
	v_add_u32_e32 v158, s0, v176
	v_add_u32_e32 v178, s1, v176
	ds_read_b128 v[146:149], v158
	ds_read_b128 v[150:153], v158 offset:1024
	ds_read_b128 v[154:157], v158 offset:2048
	ds_read_b128 v[158:161], v158 offset:3072
	ds_read_b128 v[162:165], v178
	ds_read_b128 v[166:169], v178 offset:1024
	ds_read_b128 v[170:173], v178 offset:2048
	ds_read_b128 v[178:181], v178 offset:3072
	s_add_u32 s94, vcc_lo, 0x80000
	s_addc_u32 s95, vcc_hi, 0
	s_mov_b32 m0, s27
	ds_read_b128 v[182:185], v177 offset:32768
	ds_read_b128 v[186:189], v177 offset:33792
	ds_read_b128 v[190:193], v177 offset:34816
	ds_read_b128 v[204:207], v177 offset:35840
	ds_read_b128 v[208:211], v177 offset:36864
	ds_read_b128 v[212:215], v177 offset:37888
	ds_read_b128 v[216:219], v177 offset:38912
	ds_read_b128 v[220:223], v177 offset:39936
	global_load_lds_dwordx4 v132, s[94:95] sc1
	s_mov_b32 m0, s29
	s_nop 0
	global_load_lds_dwordx4 v130, s[94:95] sc1
	s_waitcnt vmcnt(8)
	s_waitcnt lgkmcnt(0)
	s_barrier
	s_waitcnt lgkmcnt(0)
	v_mfma_f32_16x16x32_bf16 v[126:129], v[146:149], v[182:185], v[126:129]
	v_mfma_f32_16x16x32_bf16 v[126:129], v[150:153], v[186:189], v[126:129]
	v_mfma_f32_16x16x32_bf16 v[122:125], v[158:161], v[186:189], v[122:125]
	v_mfma_f32_16x16x32_bf16 v[122:125], v[154:157], v[182:185], v[122:125]
	v_mfma_f32_16x16x32_bf16 v[118:121], v[162:165], v[182:185], v[118:121]
	v_mfma_f32_16x16x32_bf16 v[118:121], v[166:169], v[186:189], v[118:121]
	v_mfma_f32_16x16x32_bf16 v[114:117], v[178:181], v[186:189], v[114:117]
	v_mfma_f32_16x16x32_bf16 v[114:117], v[170:173], v[182:185], v[114:117]
	v_mfma_f32_16x16x32_bf16 v[98:101], v[170:173], v[190:193], v[98:101]
	v_mfma_f32_16x16x32_bf16 v[98:101], v[178:181], v[204:207], v[98:101]
	v_mfma_f32_16x16x32_bf16 v[102:105], v[166:169], v[204:207], v[102:105]
	v_mfma_f32_16x16x32_bf16 v[102:105], v[162:165], v[190:193], v[102:105]
	v_mfma_f32_16x16x32_bf16 v[106:109], v[154:157], v[190:193], v[106:109]
	v_mfma_f32_16x16x32_bf16 v[106:109], v[158:161], v[204:207], v[106:109]
	v_mfma_f32_16x16x32_bf16 v[110:113], v[150:153], v[204:207], v[110:113]
	v_mfma_f32_16x16x32_bf16 v[110:113], v[146:149], v[190:193], v[110:113]
	v_mfma_f32_16x16x32_bf16 v[94:97], v[146:149], v[208:211], v[94:97]
	v_mfma_f32_16x16x32_bf16 v[94:97], v[150:153], v[212:215], v[94:97]
	v_mfma_f32_16x16x32_bf16 v[90:93], v[158:161], v[212:215], v[90:93]
	v_mfma_f32_16x16x32_bf16 v[90:93], v[154:157], v[208:211], v[90:93]
	v_mfma_f32_16x16x32_bf16 v[86:89], v[162:165], v[208:211], v[86:89]
	v_mfma_f32_16x16x32_bf16 v[86:89], v[166:169], v[212:215], v[86:89]
	v_mfma_f32_16x16x32_bf16 v[82:85], v[178:181], v[212:215], v[82:85]
	v_mfma_f32_16x16x32_bf16 v[82:85], v[170:173], v[208:211], v[82:85]
	v_mfma_f32_16x16x32_bf16 v[66:69], v[170:173], v[216:219], v[66:69]
	v_mfma_f32_16x16x32_bf16 v[66:69], v[178:181], v[220:223], v[66:69]
	v_mfma_f32_16x16x32_bf16 v[70:73], v[166:169], v[220:223], v[70:73]
	v_mfma_f32_16x16x32_bf16 v[70:73], v[162:165], v[216:219], v[70:73]
	v_mfma_f32_16x16x32_bf16 v[74:77], v[154:157], v[216:219], v[74:77]
	v_mfma_f32_16x16x32_bf16 v[74:77], v[158:161], v[220:223], v[74:77]
	v_mfma_f32_16x16x32_bf16 v[78:81], v[150:153], v[220:223], v[78:81]
	v_mfma_f32_16x16x32_bf16 v[78:81], v[146:149], v[216:219], v[78:81]
	s_barrier
	s_add_u32 s98, s84, 0x80
	s_addc_u32 s99, s85, 0
	s_add_u32 s100, vcc_lo, 0x80
	s_addc_u32 s101, vcc_hi, 0
	s_add_i32 s0, s0, s20
	s_mov_b32 m0, s0
	ds_read_b128 v[182:185], v177 offset:49152
	ds_read_b128 v[186:189], v177 offset:50176
	ds_read_b128 v[190:193], v177 offset:51200
	ds_read_b128 v[204:207], v177 offset:52224
	ds_read_b128 v[208:211], v177 offset:53248
	ds_read_b128 v[212:215], v177 offset:54272
	ds_read_b128 v[216:219], v177 offset:55296
	ds_read_b128 v[220:223], v177 offset:56320
	global_load_lds_dwordx4 v132, s[98:99] sc1
	s_add_i32 m0, s0, 0x2000
	s_add_u32 s84, s84, 0x80080
	s_addc_u32 s85, s85, 0
	s_add_i32 s0, s1, s20
	global_load_lds_dwordx4 v130, s[98:99] sc1
	s_mov_b32 m0, s0
	s_nop 0
	global_load_lds_dwordx4 v132, s[84:85] sc1
	s_add_i32 m0, s0, 0x2000
	s_nop 0
	global_load_lds_dwordx4 v130, s[84:85] sc1
	s_mov_b32 m0, s40
	s_nop 0
	global_load_lds_dwordx4 v132, s[100:101] sc1
	s_mov_b32 m0, s41
	s_nop 0
	global_load_lds_dwordx4 v130, s[100:101] sc1
	s_waitcnt vmcnt(8)
	s_waitcnt lgkmcnt(0)
	s_barrier
	s_waitcnt lgkmcnt(0)
	v_mfma_f32_16x16x32_bf16 v[62:65], v[146:149], v[182:185], v[62:65]
	v_mfma_f32_16x16x32_bf16 v[62:65], v[150:153], v[186:189], v[62:65]
	v_mfma_f32_16x16x32_bf16 v[58:61], v[158:161], v[186:189], v[58:61]
	v_mfma_f32_16x16x32_bf16 v[58:61], v[154:157], v[182:185], v[58:61]
	v_mfma_f32_16x16x32_bf16 v[54:57], v[162:165], v[182:185], v[54:57]
	v_mfma_f32_16x16x32_bf16 v[54:57], v[166:169], v[186:189], v[54:57]
	v_mfma_f32_16x16x32_bf16 v[50:53], v[178:181], v[186:189], v[50:53]
	v_mfma_f32_16x16x32_bf16 v[50:53], v[170:173], v[182:185], v[50:53]
	v_mfma_f32_16x16x32_bf16 v[34:37], v[170:173], v[190:193], v[34:37]
	v_mfma_f32_16x16x32_bf16 v[34:37], v[178:181], v[204:207], v[34:37]
	v_mfma_f32_16x16x32_bf16 v[38:41], v[166:169], v[204:207], v[38:41]
	v_mfma_f32_16x16x32_bf16 v[38:41], v[162:165], v[190:193], v[38:41]
	v_mfma_f32_16x16x32_bf16 v[42:45], v[154:157], v[190:193], v[42:45]
	v_mfma_f32_16x16x32_bf16 v[42:45], v[158:161], v[204:207], v[42:45]
	v_mfma_f32_16x16x32_bf16 v[46:49], v[150:153], v[204:207], v[46:49]
	v_mfma_f32_16x16x32_bf16 v[46:49], v[146:149], v[190:193], v[46:49]
	v_mfma_f32_16x16x32_bf16 v[30:33], v[146:149], v[208:211], v[30:33]
	v_mfma_f32_16x16x32_bf16 v[30:33], v[150:153], v[212:215], v[30:33]
	v_mfma_f32_16x16x32_bf16 v[26:29], v[158:161], v[212:215], v[26:29]
	v_mfma_f32_16x16x32_bf16 v[26:29], v[154:157], v[208:211], v[26:29]
	v_mfma_f32_16x16x32_bf16 v[22:25], v[162:165], v[208:211], v[22:25]
	v_mfma_f32_16x16x32_bf16 v[22:25], v[166:169], v[212:215], v[22:25]
	v_mfma_f32_16x16x32_bf16 v[18:21], v[178:181], v[212:215], v[18:21]
	v_mfma_f32_16x16x32_bf16 v[18:21], v[170:173], v[208:211], v[18:21]
	v_mfma_f32_16x16x32_bf16 v[2:5], v[170:173], v[216:219], v[2:5]
	v_mfma_f32_16x16x32_bf16 v[2:5], v[178:181], v[220:223], v[2:5]
	v_mfma_f32_16x16x32_bf16 v[6:9], v[166:169], v[220:223], v[6:9]
	v_mfma_f32_16x16x32_bf16 v[6:9], v[162:165], v[216:219], v[6:9]
	v_mfma_f32_16x16x32_bf16 v[10:13], v[154:157], v[216:219], v[10:13]
	v_mfma_f32_16x16x32_bf16 v[10:13], v[158:161], v[220:223], v[10:13]
	v_mfma_f32_16x16x32_bf16 v[14:17], v[150:153], v[220:223], v[14:17]
	v_mfma_f32_16x16x32_bf16 v[14:17], v[146:149], v[216:219], v[14:17]
	s_barrier
	s_add_i32 s65, s65, 2
	s_add_u32 s76, s76, 0x100
	s_addc_u32 s77, s77, 0
	s_add_u32 s51, s51, 0x100
	s_addc_u32 s58, s58, 0
	s_cmp_gt_u32 s65, 29
	s_cbranch_scc1 .LBB0_264
	s_branch .LBB0_262

.LBB0_285:
	s_add_u32 s0, s76, 0xfff80080
	s_addc_u32 s1, s77, -1
	s_and_b64 s[70:71], s[70:71], exec
	s_cselect_b32 vcc_hi, s21, s1
	s_cselect_b32 vcc_lo, s22, s0
	s_cselect_b32 s71, s23, s41
	s_cselect_b32 s70, s39, s7
	s_add_i32 s0, 0, 0x10000
	s_add_i32 s1, 0, 0x14000
	v_add_u32_e32 v146, s0, v1
	v_add_u32_e32 v174, s1, v1
	ds_read_b128 v[134:137], v146
	ds_read_b128 v[138:141], v146 offset:1024
	ds_read_b128 v[142:145], v146 offset:2048
	ds_read_b128 v[146:149], v146 offset:3072
	ds_read_b128 v[150:153], v174
	ds_read_b128 v[154:157], v174 offset:1024
	ds_read_b128 v[158:161], v174 offset:2048
	ds_read_b128 v[174:177], v174 offset:3072
	s_add_i32 m0, s67, 0xc000
	ds_read_b128 v[178:181], v222
	ds_read_b128 v[182:185], v222 offset:1024
	ds_read_b128 v[186:189], v222 offset:2048
	ds_read_b128 v[190:193], v222 offset:3072
	ds_read_b128 v[204:207], v222 offset:4096
	ds_read_b128 v[208:211], v222 offset:5120
	ds_read_b128 v[212:215], v222 offset:6144
	ds_read_b128 v[216:219], v222 offset:7168
	global_load_lds_dwordx4 v170, s[76:77] sc1
	s_add_i32 m0, s67, 0xe000
	s_nop 0
	global_load_lds_dwordx4 v172, s[76:77] sc1
	s_waitcnt vmcnt(8)
	s_waitcnt lgkmcnt(0)
	s_barrier
	s_waitcnt lgkmcnt(0)
	v_mfma_f32_16x16x32_bf16 v[126:129], v[134:137], v[178:181], v[126:129]
	v_mfma_f32_16x16x32_bf16 v[126:129], v[138:141], v[182:185], v[126:129]
	v_mfma_f32_16x16x32_bf16 v[122:125], v[146:149], v[182:185], v[122:125]
	v_mfma_f32_16x16x32_bf16 v[122:125], v[142:145], v[178:181], v[122:125]
	v_mfma_f32_16x16x32_bf16 v[118:121], v[150:153], v[178:181], v[118:121]
	v_mfma_f32_16x16x32_bf16 v[118:121], v[154:157], v[182:185], v[118:121]
	v_mfma_f32_16x16x32_bf16 v[114:117], v[174:177], v[182:185], v[114:117]
	v_mfma_f32_16x16x32_bf16 v[114:117], v[158:161], v[178:181], v[114:117]
	v_mfma_f32_16x16x32_bf16 v[98:101], v[158:161], v[186:189], v[98:101]
	v_mfma_f32_16x16x32_bf16 v[98:101], v[174:177], v[190:193], v[98:101]
	v_mfma_f32_16x16x32_bf16 v[102:105], v[154:157], v[190:193], v[102:105]
	v_mfma_f32_16x16x32_bf16 v[102:105], v[150:153], v[186:189], v[102:105]
	v_mfma_f32_16x16x32_bf16 v[106:109], v[142:145], v[186:189], v[106:109]
	v_mfma_f32_16x16x32_bf16 v[106:109], v[146:149], v[190:193], v[106:109]
	v_mfma_f32_16x16x32_bf16 v[110:113], v[138:141], v[190:193], v[110:113]
	v_mfma_f32_16x16x32_bf16 v[110:113], v[134:137], v[186:189], v[110:113]
	v_mfma_f32_16x16x32_bf16 v[94:97], v[134:137], v[204:207], v[94:97]
	v_mfma_f32_16x16x32_bf16 v[94:97], v[138:141], v[208:211], v[94:97]
	v_mfma_f32_16x16x32_bf16 v[90:93], v[146:149], v[208:211], v[90:93]
	v_mfma_f32_16x16x32_bf16 v[90:93], v[142:145], v[204:207], v[90:93]
	v_mfma_f32_16x16x32_bf16 v[86:89], v[150:153], v[204:207], v[86:89]
	v_mfma_f32_16x16x32_bf16 v[86:89], v[154:157], v[208:211], v[86:89]
	v_mfma_f32_16x16x32_bf16 v[82:85], v[174:177], v[208:211], v[82:85]
	v_mfma_f32_16x16x32_bf16 v[82:85], v[158:161], v[204:207], v[82:85]
	v_mfma_f32_16x16x32_bf16 v[66:69], v[158:161], v[212:215], v[66:69]
	v_mfma_f32_16x16x32_bf16 v[66:69], v[174:177], v[216:219], v[66:69]
	v_mfma_f32_16x16x32_bf16 v[70:73], v[154:157], v[216:219], v[70:73]
	v_mfma_f32_16x16x32_bf16 v[70:73], v[150:153], v[212:215], v[70:73]
	v_mfma_f32_16x16x32_bf16 v[74:77], v[142:145], v[212:215], v[74:77]
	v_mfma_f32_16x16x32_bf16 v[74:77], v[146:149], v[216:219], v[74:77]
	v_mfma_f32_16x16x32_bf16 v[78:81], v[138:141], v[216:219], v[78:81]
	v_mfma_f32_16x16x32_bf16 v[78:81], v[134:137], v[212:215], v[78:81]
	s_barrier
	s_add_i32 s0, s0, s54
	s_mov_b32 m0, s0
	ds_read_b128 v[178:181], v222 offset:16384
	ds_read_b128 v[182:185], v222 offset:17408
	ds_read_b128 v[186:189], v222 offset:18432
	ds_read_b128 v[190:193], v222 offset:19456
	ds_read_b128 v[204:207], v222 offset:20480
	ds_read_b128 v[208:211], v222 offset:21504
	ds_read_b128 v[212:215], v222 offset:22528
	ds_read_b128 v[216:219], v222 offset:23552
	global_load_lds_dwordx4 v164, s[70:71] sc1
	s_add_i32 m0, s0, 0x2000
	s_add_u32 s44, s70, 0x80000
	s_addc_u32 s45, s71, 0
	s_add_i32 s0, s1, s54
	global_load_lds_dwordx4 v162, s[70:71] sc1
	s_mov_b32 m0, s0
	s_nop 0
	global_load_lds_dwordx4 v164, s[44:45] sc1
	s_add_i32 m0, s0, 0x2000
	s_nop 0
	global_load_lds_dwordx4 v162, s[44:45] sc1
	s_mov_b32 m0, s67
	s_nop 0
	global_load_lds_dwordx4 v164, vcc sc1
	s_mov_b32 m0, s68
	s_nop 0
	global_load_lds_dwordx4 v162, vcc sc1
	s_waitcnt vmcnt(8)
	s_waitcnt lgkmcnt(0)
	s_barrier
	s_waitcnt lgkmcnt(0)
	v_mfma_f32_16x16x32_bf16 v[62:65], v[134:137], v[178:181], v[62:65]
	v_mfma_f32_16x16x32_bf16 v[62:65], v[138:141], v[182:185], v[62:65]
	v_mfma_f32_16x16x32_bf16 v[58:61], v[146:149], v[182:185], v[58:61]
	v_mfma_f32_16x16x32_bf16 v[58:61], v[142:145], v[178:181], v[58:61]
	v_mfma_f32_16x16x32_bf16 v[54:57], v[150:153], v[178:181], v[54:57]
	v_mfma_f32_16x16x32_bf16 v[54:57], v[154:157], v[182:185], v[54:57]
	v_mfma_f32_16x16x32_bf16 v[50:53], v[174:177], v[182:185], v[50:53]
	v_mfma_f32_16x16x32_bf16 v[50:53], v[158:161], v[178:181], v[50:53]
	v_mfma_f32_16x16x32_bf16 v[34:37], v[158:161], v[186:189], v[34:37]
	v_mfma_f32_16x16x32_bf16 v[34:37], v[174:177], v[190:193], v[34:37]
	v_mfma_f32_16x16x32_bf16 v[38:41], v[154:157], v[190:193], v[38:41]
	v_mfma_f32_16x16x32_bf16 v[38:41], v[150:153], v[186:189], v[38:41]
	v_mfma_f32_16x16x32_bf16 v[42:45], v[142:145], v[186:189], v[42:45]
	v_mfma_f32_16x16x32_bf16 v[42:45], v[146:149], v[190:193], v[42:45]
	v_mfma_f32_16x16x32_bf16 v[46:49], v[138:141], v[190:193], v[46:49]
	v_mfma_f32_16x16x32_bf16 v[46:49], v[134:137], v[186:189], v[46:49]
	v_mfma_f32_16x16x32_bf16 v[30:33], v[134:137], v[204:207], v[30:33]
	v_mfma_f32_16x16x32_bf16 v[30:33], v[138:141], v[208:211], v[30:33]
	v_mfma_f32_16x16x32_bf16 v[26:29], v[146:149], v[208:211], v[26:29]
	v_mfma_f32_16x16x32_bf16 v[26:29], v[142:145], v[204:207], v[26:29]
	v_mfma_f32_16x16x32_bf16 v[22:25], v[150:153], v[204:207], v[22:25]
	v_mfma_f32_16x16x32_bf16 v[22:25], v[154:157], v[208:211], v[22:25]
	v_mfma_f32_16x16x32_bf16 v[18:21], v[174:177], v[208:211], v[18:21]
	v_mfma_f32_16x16x32_bf16 v[18:21], v[158:161], v[204:207], v[18:21]
	v_mfma_f32_16x16x32_bf16 v[2:5], v[158:161], v[212:215], v[2:5]
	v_mfma_f32_16x16x32_bf16 v[2:5], v[174:177], v[216:219], v[2:5]
	v_mfma_f32_16x16x32_bf16 v[6:9], v[154:157], v[216:219], v[6:9]
	v_mfma_f32_16x16x32_bf16 v[6:9], v[150:153], v[212:215], v[6:9]
	v_mfma_f32_16x16x32_bf16 v[10:13], v[142:145], v[212:215], v[10:13]
	v_mfma_f32_16x16x32_bf16 v[10:13], v[146:149], v[216:219], v[10:13]
	v_mfma_f32_16x16x32_bf16 v[14:17], v[138:141], v[216:219], v[14:17]
	v_mfma_f32_16x16x32_bf16 v[14:17], v[134:137], v[212:215], v[14:17]
	s_barrier
	s_add_i32 s0, 0, 0x18000
	s_add_i32 s1, 0, 0x1c000
	v_add_u32_e32 v146, s0, v1
	v_add_u32_e32 v174, s1, v1
	ds_read_b128 v[134:137], v146
	ds_read_b128 v[138:141], v146 offset:1024
	ds_read_b128 v[142:145], v146 offset:2048
	ds_read_b128 v[146:149], v146 offset:3072
	ds_read_b128 v[150:153], v174
	ds_read_b128 v[154:157], v174 offset:1024
	ds_read_b128 v[158:161], v174 offset:2048
	ds_read_b128 v[174:177], v174 offset:3072
	s_add_u32 s44, vcc_lo, 0x80000
	s_addc_u32 s45, vcc_hi, 0
	s_mov_b32 m0, s8
	ds_read_b128 v[178:181], v222 offset:32768
	ds_read_b128 v[182:185], v222 offset:33792
	ds_read_b128 v[186:189], v222 offset:34816
	ds_read_b128 v[190:193], v222 offset:35840
	ds_read_b128 v[204:207], v222 offset:36864
	ds_read_b128 v[208:211], v222 offset:37888
	ds_read_b128 v[212:215], v222 offset:38912
	ds_read_b128 v[216:219], v222 offset:39936
	global_load_lds_dwordx4 v164, s[44:45] sc1
	s_mov_b32 m0, s9
	s_nop 0
	global_load_lds_dwordx4 v162, s[44:45] sc1
	s_waitcnt vmcnt(8)
	s_waitcnt lgkmcnt(0)
	s_barrier
	s_waitcnt lgkmcnt(0)
	v_mfma_f32_16x16x32_bf16 v[126:129], v[134:137], v[178:181], v[126:129]
	v_mfma_f32_16x16x32_bf16 v[126:129], v[138:141], v[182:185], v[126:129]
	v_mfma_f32_16x16x32_bf16 v[122:125], v[146:149], v[182:185], v[122:125]
	v_mfma_f32_16x16x32_bf16 v[122:125], v[142:145], v[178:181], v[122:125]
	v_mfma_f32_16x16x32_bf16 v[118:121], v[150:153], v[178:181], v[118:121]
	v_mfma_f32_16x16x32_bf16 v[118:121], v[154:157], v[182:185], v[118:121]
	v_mfma_f32_16x16x32_bf16 v[114:117], v[174:177], v[182:185], v[114:117]
	v_mfma_f32_16x16x32_bf16 v[114:117], v[158:161], v[178:181], v[114:117]
	v_mfma_f32_16x16x32_bf16 v[98:101], v[158:161], v[186:189], v[98:101]
	v_mfma_f32_16x16x32_bf16 v[98:101], v[174:177], v[190:193], v[98:101]
	v_mfma_f32_16x16x32_bf16 v[102:105], v[154:157], v[190:193], v[102:105]
	v_mfma_f32_16x16x32_bf16 v[102:105], v[150:153], v[186:189], v[102:105]
	v_mfma_f32_16x16x32_bf16 v[106:109], v[142:145], v[186:189], v[106:109]
	v_mfma_f32_16x16x32_bf16 v[106:109], v[146:149], v[190:193], v[106:109]
	v_mfma_f32_16x16x32_bf16 v[110:113], v[138:141], v[190:193], v[110:113]
	v_mfma_f32_16x16x32_bf16 v[110:113], v[134:137], v[186:189], v[110:113]
	v_mfma_f32_16x16x32_bf16 v[94:97], v[134:137], v[204:207], v[94:97]
	v_mfma_f32_16x16x32_bf16 v[94:97], v[138:141], v[208:211], v[94:97]
	v_mfma_f32_16x16x32_bf16 v[90:93], v[146:149], v[208:211], v[90:93]
	v_mfma_f32_16x16x32_bf16 v[90:93], v[142:145], v[204:207], v[90:93]
	v_mfma_f32_16x16x32_bf16 v[86:89], v[150:153], v[204:207], v[86:89]
	v_mfma_f32_16x16x32_bf16 v[86:89], v[154:157], v[208:211], v[86:89]
	v_mfma_f32_16x16x32_bf16 v[82:85], v[174:177], v[208:211], v[82:85]
	v_mfma_f32_16x16x32_bf16 v[82:85], v[158:161], v[204:207], v[82:85]
	v_mfma_f32_16x16x32_bf16 v[66:69], v[158:161], v[212:215], v[66:69]
	v_mfma_f32_16x16x32_bf16 v[66:69], v[174:177], v[216:219], v[66:69]
	v_mfma_f32_16x16x32_bf16 v[70:73], v[154:157], v[216:219], v[70:73]
	v_mfma_f32_16x16x32_bf16 v[70:73], v[150:153], v[212:215], v[70:73]
	v_mfma_f32_16x16x32_bf16 v[74:77], v[142:145], v[212:215], v[74:77]
	v_mfma_f32_16x16x32_bf16 v[74:77], v[146:149], v[216:219], v[74:77]
	v_mfma_f32_16x16x32_bf16 v[78:81], v[138:141], v[216:219], v[78:81]
	v_mfma_f32_16x16x32_bf16 v[78:81], v[134:137], v[212:215], v[78:81]
	s_barrier
	s_add_u32 s98, s70, 0x80
	s_addc_u32 s99, s71, 0
	s_add_u32 s100, vcc_lo, 0x80
	s_addc_u32 s101, vcc_hi, 0
	s_add_i32 s0, s0, s54
	s_mov_b32 m0, s0
	ds_read_b128 v[178:181], v222 offset:49152
	ds_read_b128 v[182:185], v222 offset:50176
	ds_read_b128 v[186:189], v222 offset:51200
	ds_read_b128 v[190:193], v222 offset:52224
	ds_read_b128 v[204:207], v222 offset:53248
	ds_read_b128 v[208:211], v222 offset:54272
	ds_read_b128 v[212:215], v222 offset:55296
	ds_read_b128 v[216:219], v222 offset:56320
	global_load_lds_dwordx4 v164, s[98:99] sc1
	s_add_i32 m0, s0, 0x2000
	s_add_u32 s44, s70, 0x80080
	s_addc_u32 s45, s71, 0
	s_add_i32 s0, s1, s54
	global_load_lds_dwordx4 v162, s[98:99] sc1
	s_mov_b32 m0, s0
	s_nop 0
	global_load_lds_dwordx4 v164, s[44:45] sc1
	s_add_i32 m0, s0, 0x2000
	s_nop 0
	global_load_lds_dwordx4 v162, s[44:45] sc1
	s_mov_b32 m0, s27
	s_nop 0
	global_load_lds_dwordx4 v164, s[100:101] sc1
	s_mov_b32 m0, s26
	s_nop 0
	global_load_lds_dwordx4 v162, s[100:101] sc1
	s_waitcnt vmcnt(8)
	s_waitcnt lgkmcnt(0)
	s_barrier
	s_waitcnt lgkmcnt(0)
	v_mfma_f32_16x16x32_bf16 v[62:65], v[134:137], v[178:181], v[62:65]
	v_mfma_f32_16x16x32_bf16 v[62:65], v[138:141], v[182:185], v[62:65]
	v_mfma_f32_16x16x32_bf16 v[58:61], v[146:149], v[182:185], v[58:61]
	v_mfma_f32_16x16x32_bf16 v[58:61], v[142:145], v[178:181], v[58:61]
	v_mfma_f32_16x16x32_bf16 v[54:57], v[150:153], v[178:181], v[54:57]
	v_mfma_f32_16x16x32_bf16 v[54:57], v[154:157], v[182:185], v[54:57]
	v_mfma_f32_16x16x32_bf16 v[50:53], v[174:177], v[182:185], v[50:53]
	v_mfma_f32_16x16x32_bf16 v[50:53], v[158:161], v[178:181], v[50:53]
	v_mfma_f32_16x16x32_bf16 v[34:37], v[158:161], v[186:189], v[34:37]
	v_mfma_f32_16x16x32_bf16 v[34:37], v[174:177], v[190:193], v[34:37]
	v_mfma_f32_16x16x32_bf16 v[38:41], v[154:157], v[190:193], v[38:41]
	v_mfma_f32_16x16x32_bf16 v[38:41], v[150:153], v[186:189], v[38:41]
	v_mfma_f32_16x16x32_bf16 v[42:45], v[142:145], v[186:189], v[42:45]
	v_mfma_f32_16x16x32_bf16 v[42:45], v[146:149], v[190:193], v[42:45]
	v_mfma_f32_16x16x32_bf16 v[46:49], v[138:141], v[190:193], v[46:49]
	v_mfma_f32_16x16x32_bf16 v[46:49], v[134:137], v[186:189], v[46:49]
	v_mfma_f32_16x16x32_bf16 v[30:33], v[134:137], v[204:207], v[30:33]
	v_mfma_f32_16x16x32_bf16 v[30:33], v[138:141], v[208:211], v[30:33]
	v_mfma_f32_16x16x32_bf16 v[26:29], v[146:149], v[208:211], v[26:29]
	v_mfma_f32_16x16x32_bf16 v[26:29], v[142:145], v[204:207], v[26:29]
	v_mfma_f32_16x16x32_bf16 v[22:25], v[150:153], v[204:207], v[22:25]
	v_mfma_f32_16x16x32_bf16 v[22:25], v[154:157], v[208:211], v[22:25]
	v_mfma_f32_16x16x32_bf16 v[18:21], v[174:177], v[208:211], v[18:21]
	v_mfma_f32_16x16x32_bf16 v[18:21], v[158:161], v[204:207], v[18:21]
	v_mfma_f32_16x16x32_bf16 v[2:5], v[158:161], v[212:215], v[2:5]
	v_mfma_f32_16x16x32_bf16 v[2:5], v[174:177], v[216:219], v[2:5]
	v_mfma_f32_16x16x32_bf16 v[6:9], v[154:157], v[216:219], v[6:9]
	v_mfma_f32_16x16x32_bf16 v[6:9], v[150:153], v[212:215], v[6:9]
	v_mfma_f32_16x16x32_bf16 v[10:13], v[142:145], v[212:215], v[10:13]
	v_mfma_f32_16x16x32_bf16 v[10:13], v[146:149], v[216:219], v[10:13]
	v_mfma_f32_16x16x32_bf16 v[14:17], v[138:141], v[216:219], v[14:17]
	v_mfma_f32_16x16x32_bf16 v[14:17], v[134:137], v[212:215], v[14:17]
	s_barrier
	s_add_i32 s43, s43, 2
	s_add_u32 s76, s76, 0x100
	s_addc_u32 s77, s77, 0
	s_add_u32 s7, s7, 0x100
	s_addc_u32 s41, s41, 0
	s_cmp_gt_u32 s43, 29
	s_cbranch_scc1 .LBB0_288

.Lpeel_disp_ino:
	s_cmp_lg_u32 s43, -2
	s_cbranch_scc1 .LBB0_285
	s_add_u32 s0, s76, 0xfff80080
	s_addc_u32 s1, s77, -1
	s_and_b64 s[70:71], s[70:71], exec
	s_cselect_b32 vcc_hi, s21, s1
	s_cselect_b32 vcc_lo, s22, s0
	s_cselect_b32 s71, s23, s41
	s_cselect_b32 s70, s39, s7
	s_add_i32 s0, 0, 0x10000
	s_add_i32 s1, 0, 0x14000
	v_add_u32_e32 v146, s0, v1
	v_add_u32_e32 v174, s1, v1
	ds_read_b128 v[134:137], v146
	ds_read_b128 v[138:141], v146 offset:1024
	ds_read_b128 v[142:145], v146 offset:2048
	ds_read_b128 v[146:149], v146 offset:3072
	ds_read_b128 v[150:153], v174
	ds_read_b128 v[154:157], v174 offset:1024
	ds_read_b128 v[158:161], v174 offset:2048
	ds_read_b128 v[174:177], v174 offset:3072
	s_add_i32 m0, s67, 0xc000
	ds_read_b128 v[178:181], v222
	ds_read_b128 v[182:185], v222 offset:1024
	ds_read_b128 v[186:189], v222 offset:2048
	ds_read_b128 v[190:193], v222 offset:3072
	ds_read_b128 v[204:207], v222 offset:4096
	ds_read_b128 v[208:211], v222 offset:5120
	ds_read_b128 v[212:215], v222 offset:6144
	ds_read_b128 v[216:219], v222 offset:7168
	global_load_lds_dwordx4 v170, s[76:77] sc1
	s_add_i32 m0, s67, 0xe000
	s_nop 0
	global_load_lds_dwordx4 v172, s[76:77] sc1
	s_waitcnt vmcnt(8)
	s_waitcnt lgkmcnt(0)
	s_barrier
	s_waitcnt lgkmcnt(0)
	v_mfma_f32_16x16x32_bf16 v[126:129], v[134:137], v[178:181], 0
	v_mfma_f32_16x16x32_bf16 v[126:129], v[138:141], v[182:185], v[126:129]
	v_mfma_f32_16x16x32_bf16 v[122:125], v[146:149], v[182:185], 0
	v_mfma_f32_16x16x32_bf16 v[122:125], v[142:145], v[178:181], v[122:125]
	v_mfma_f32_16x16x32_bf16 v[118:121], v[150:153], v[178:181], 0
	v_mfma_f32_16x16x32_bf16 v[118:121], v[154:157], v[182:185], v[118:121]
	v_mfma_f32_16x16x32_bf16 v[114:117], v[174:177], v[182:185], 0
	v_mfma_f32_16x16x32_bf16 v[114:117], v[158:161], v[178:181], v[114:117]
	v_mfma_f32_16x16x32_bf16 v[98:101], v[158:161], v[186:189], 0
	v_mfma_f32_16x16x32_bf16 v[98:101], v[174:177], v[190:193], v[98:101]
	v_mfma_f32_16x16x32_bf16 v[102:105], v[154:157], v[190:193], 0
	v_mfma_f32_16x16x32_bf16 v[102:105], v[150:153], v[186:189], v[102:105]
	v_mfma_f32_16x16x32_bf16 v[106:109], v[142:145], v[186:189], 0
	v_mfma_f32_16x16x32_bf16 v[106:109], v[146:149], v[190:193], v[106:109]
	v_mfma_f32_16x16x32_bf16 v[110:113], v[138:141], v[190:193], 0
	v_mfma_f32_16x16x32_bf16 v[110:113], v[134:137], v[186:189], v[110:113]
	v_mfma_f32_16x16x32_bf16 v[94:97], v[134:137], v[204:207], 0
	v_mfma_f32_16x16x32_bf16 v[94:97], v[138:141], v[208:211], v[94:97]
	v_mfma_f32_16x16x32_bf16 v[90:93], v[146:149], v[208:211], 0
	v_mfma_f32_16x16x32_bf16 v[90:93], v[142:145], v[204:207], v[90:93]
	v_mfma_f32_16x16x32_bf16 v[86:89], v[150:153], v[204:207], 0
	v_mfma_f32_16x16x32_bf16 v[86:89], v[154:157], v[208:211], v[86:89]
	v_mfma_f32_16x16x32_bf16 v[82:85], v[174:177], v[208:211], 0
	v_mfma_f32_16x16x32_bf16 v[82:85], v[158:161], v[204:207], v[82:85]
	v_mfma_f32_16x16x32_bf16 v[66:69], v[158:161], v[212:215], 0
	v_mfma_f32_16x16x32_bf16 v[66:69], v[174:177], v[216:219], v[66:69]
	v_mfma_f32_16x16x32_bf16 v[70:73], v[154:157], v[216:219], 0
	v_mfma_f32_16x16x32_bf16 v[70:73], v[150:153], v[212:215], v[70:73]
	v_mfma_f32_16x16x32_bf16 v[74:77], v[142:145], v[212:215], 0
	v_mfma_f32_16x16x32_bf16 v[74:77], v[146:149], v[216:219], v[74:77]
	v_mfma_f32_16x16x32_bf16 v[78:81], v[138:141], v[216:219], 0
	v_mfma_f32_16x16x32_bf16 v[78:81], v[134:137], v[212:215], v[78:81]
	s_barrier
	s_add_i32 s0, s0, s54
	s_mov_b32 m0, s0
	ds_read_b128 v[178:181], v222 offset:16384
	ds_read_b128 v[182:185], v222 offset:17408
	ds_read_b128 v[186:189], v222 offset:18432
	ds_read_b128 v[190:193], v222 offset:19456
	ds_read_b128 v[204:207], v222 offset:20480
	ds_read_b128 v[208:211], v222 offset:21504
	ds_read_b128 v[212:215], v222 offset:22528
	ds_read_b128 v[216:219], v222 offset:23552
	global_load_lds_dwordx4 v164, s[70:71] sc1
	s_add_i32 m0, s0, 0x2000
	s_add_u32 s44, s70, 0x80000
	s_addc_u32 s45, s71, 0
	s_add_i32 s0, s1, s54
	global_load_lds_dwordx4 v162, s[70:71] sc1
	s_mov_b32 m0, s0
	s_nop 0
	global_load_lds_dwordx4 v164, s[44:45] sc1
	s_add_i32 m0, s0, 0x2000
	s_nop 0
	global_load_lds_dwordx4 v162, s[44:45] sc1
	s_mov_b32 m0, s67
	s_nop 0
	global_load_lds_dwordx4 v164, vcc sc1
	s_mov_b32 m0, s68
	s_nop 0
	global_load_lds_dwordx4 v162, vcc sc1
	s_waitcnt vmcnt(8)
	s_waitcnt lgkmcnt(0)
	s_barrier
	s_waitcnt lgkmcnt(0)
	v_mfma_f32_16x16x32_bf16 v[62:65], v[134:137], v[178:181], 0
	v_mfma_f32_16x16x32_bf16 v[62:65], v[138:141], v[182:185], v[62:65]
	v_mfma_f32_16x16x32_bf16 v[58:61], v[146:149], v[182:185], 0
	v_mfma_f32_16x16x32_bf16 v[58:61], v[142:145], v[178:181], v[58:61]
	v_mfma_f32_16x16x32_bf16 v[54:57], v[150:153], v[178:181], 0
	v_mfma_f32_16x16x32_bf16 v[54:57], v[154:157], v[182:185], v[54:57]
	v_mfma_f32_16x16x32_bf16 v[50:53], v[174:177], v[182:185], 0
	v_mfma_f32_16x16x32_bf16 v[50:53], v[158:161], v[178:181], v[50:53]
	v_mfma_f32_16x16x32_bf16 v[34:37], v[158:161], v[186:189], 0
	v_mfma_f32_16x16x32_bf16 v[34:37], v[174:177], v[190:193], v[34:37]
	v_mfma_f32_16x16x32_bf16 v[38:41], v[154:157], v[190:193], 0
	v_mfma_f32_16x16x32_bf16 v[38:41], v[150:153], v[186:189], v[38:41]
	v_mfma_f32_16x16x32_bf16 v[42:45], v[142:145], v[186:189], 0
	v_mfma_f32_16x16x32_bf16 v[42:45], v[146:149], v[190:193], v[42:45]
	v_mfma_f32_16x16x32_bf16 v[46:49], v[138:141], v[190:193], 0
	v_mfma_f32_16x16x32_bf16 v[46:49], v[134:137], v[186:189], v[46:49]
	v_mfma_f32_16x16x32_bf16 v[30:33], v[134:137], v[204:207], 0
	v_mfma_f32_16x16x32_bf16 v[30:33], v[138:141], v[208:211], v[30:33]
	v_mfma_f32_16x16x32_bf16 v[26:29], v[146:149], v[208:211], 0
	v_mfma_f32_16x16x32_bf16 v[26:29], v[142:145], v[204:207], v[26:29]
	v_mfma_f32_16x16x32_bf16 v[22:25], v[150:153], v[204:207], 0
	v_mfma_f32_16x16x32_bf16 v[22:25], v[154:157], v[208:211], v[22:25]
	v_mfma_f32_16x16x32_bf16 v[18:21], v[174:177], v[208:211], 0
	v_mfma_f32_16x16x32_bf16 v[18:21], v[158:161], v[204:207], v[18:21]
	v_mfma_f32_16x16x32_bf16 v[2:5], v[158:161], v[212:215], 0
	v_mfma_f32_16x16x32_bf16 v[2:5], v[174:177], v[216:219], v[2:5]
	v_mfma_f32_16x16x32_bf16 v[6:9], v[154:157], v[216:219], 0
	v_mfma_f32_16x16x32_bf16 v[6:9], v[150:153], v[212:215], v[6:9]
	v_mfma_f32_16x16x32_bf16 v[10:13], v[142:145], v[212:215], 0
	v_mfma_f32_16x16x32_bf16 v[10:13], v[146:149], v[216:219], v[10:13]
	v_mfma_f32_16x16x32_bf16 v[14:17], v[138:141], v[216:219], 0
	v_mfma_f32_16x16x32_bf16 v[14:17], v[134:137], v[212:215], v[14:17]
	s_barrier
	s_add_i32 s0, 0, 0x18000
	s_add_i32 s1, 0, 0x1c000
	v_add_u32_e32 v146, s0, v1
	v_add_u32_e32 v174, s1, v1
	ds_read_b128 v[134:137], v146
	ds_read_b128 v[138:141], v146 offset:1024
	ds_read_b128 v[142:145], v146 offset:2048
	ds_read_b128 v[146:149], v146 offset:3072
	ds_read_b128 v[150:153], v174
	ds_read_b128 v[154:157], v174 offset:1024
	ds_read_b128 v[158:161], v174 offset:2048
	ds_read_b128 v[174:177], v174 offset:3072
	s_add_u32 s44, vcc_lo, 0x80000
	s_addc_u32 s45, vcc_hi, 0
	s_mov_b32 m0, s8
	ds_read_b128 v[178:181], v222 offset:32768
	ds_read_b128 v[182:185], v222 offset:33792
	ds_read_b128 v[186:189], v222 offset:34816
	ds_read_b128 v[190:193], v222 offset:35840
	ds_read_b128 v[204:207], v222 offset:36864
	ds_read_b128 v[208:211], v222 offset:37888
	ds_read_b128 v[212:215], v222 offset:38912
	ds_read_b128 v[216:219], v222 offset:39936
	global_load_lds_dwordx4 v164, s[44:45] sc1
	s_mov_b32 m0, s9
	s_nop 0
	global_load_lds_dwordx4 v162, s[44:45] sc1
	s_waitcnt vmcnt(8)
	s_waitcnt lgkmcnt(0)
	s_barrier
	s_waitcnt lgkmcnt(0)
	v_mfma_f32_16x16x32_bf16 v[126:129], v[134:137], v[178:181], v[126:129]
	v_mfma_f32_16x16x32_bf16 v[126:129], v[138:141], v[182:185], v[126:129]
	v_mfma_f32_16x16x32_bf16 v[122:125], v[146:149], v[182:185], v[122:125]
	v_mfma_f32_16x16x32_bf16 v[122:125], v[142:145], v[178:181], v[122:125]
	v_mfma_f32_16x16x32_bf16 v[118:121], v[150:153], v[178:181], v[118:121]
	v_mfma_f32_16x16x32_bf16 v[118:121], v[154:157], v[182:185], v[118:121]
	v_mfma_f32_16x16x32_bf16 v[114:117], v[174:177], v[182:185], v[114:117]
	v_mfma_f32_16x16x32_bf16 v[114:117], v[158:161], v[178:181], v[114:117]
	v_mfma_f32_16x16x32_bf16 v[98:101], v[158:161], v[186:189], v[98:101]
	v_mfma_f32_16x16x32_bf16 v[98:101], v[174:177], v[190:193], v[98:101]
	v_mfma_f32_16x16x32_bf16 v[102:105], v[154:157], v[190:193], v[102:105]
	v_mfma_f32_16x16x32_bf16 v[102:105], v[150:153], v[186:189], v[102:105]
	v_mfma_f32_16x16x32_bf16 v[106:109], v[142:145], v[186:189], v[106:109]
	v_mfma_f32_16x16x32_bf16 v[106:109], v[146:149], v[190:193], v[106:109]
	v_mfma_f32_16x16x32_bf16 v[110:113], v[138:141], v[190:193], v[110:113]
	v_mfma_f32_16x16x32_bf16 v[110:113], v[134:137], v[186:189], v[110:113]
	v_mfma_f32_16x16x32_bf16 v[94:97], v[134:137], v[204:207], v[94:97]
	v_mfma_f32_16x16x32_bf16 v[94:97], v[138:141], v[208:211], v[94:97]
	v_mfma_f32_16x16x32_bf16 v[90:93], v[146:149], v[208:211], v[90:93]
	v_mfma_f32_16x16x32_bf16 v[90:93], v[142:145], v[204:207], v[90:93]
	v_mfma_f32_16x16x32_bf16 v[86:89], v[150:153], v[204:207], v[86:89]
	v_mfma_f32_16x16x32_bf16 v[86:89], v[154:157], v[208:211], v[86:89]
	v_mfma_f32_16x16x32_bf16 v[82:85], v[174:177], v[208:211], v[82:85]
	v_mfma_f32_16x16x32_bf16 v[82:85], v[158:161], v[204:207], v[82:85]
	v_mfma_f32_16x16x32_bf16 v[66:69], v[158:161], v[212:215], v[66:69]
	v_mfma_f32_16x16x32_bf16 v[66:69], v[174:177], v[216:219], v[66:69]
	v_mfma_f32_16x16x32_bf16 v[70:73], v[154:157], v[216:219], v[70:73]
	v_mfma_f32_16x16x32_bf16 v[70:73], v[150:153], v[212:215], v[70:73]
	v_mfma_f32_16x16x32_bf16 v[74:77], v[142:145], v[212:215], v[74:77]
	v_mfma_f32_16x16x32_bf16 v[74:77], v[146:149], v[216:219], v[74:77]
	v_mfma_f32_16x16x32_bf16 v[78:81], v[138:141], v[216:219], v[78:81]
	v_mfma_f32_16x16x32_bf16 v[78:81], v[134:137], v[212:215], v[78:81]
	s_barrier
	s_add_u32 s98, s70, 0x80
	s_addc_u32 s99, s71, 0
	s_add_u32 s100, vcc_lo, 0x80
	s_addc_u32 s101, vcc_hi, 0
	s_add_i32 s0, s0, s54
	s_mov_b32 m0, s0
	ds_read_b128 v[178:181], v222 offset:49152
	ds_read_b128 v[182:185], v222 offset:50176
	ds_read_b128 v[186:189], v222 offset:51200
	ds_read_b128 v[190:193], v222 offset:52224
	ds_read_b128 v[204:207], v222 offset:53248
	ds_read_b128 v[208:211], v222 offset:54272
	ds_read_b128 v[212:215], v222 offset:55296
	ds_read_b128 v[216:219], v222 offset:56320
	global_load_lds_dwordx4 v164, s[98:99] sc1
	s_add_i32 m0, s0, 0x2000
	s_add_u32 s44, s70, 0x80080
	s_addc_u32 s45, s71, 0
	s_add_i32 s0, s1, s54
	global_load_lds_dwordx4 v162, s[98:99] sc1
	s_mov_b32 m0, s0
	s_nop 0
	global_load_lds_dwordx4 v164, s[44:45] sc1
	s_add_i32 m0, s0, 0x2000
	s_nop 0
	global_load_lds_dwordx4 v162, s[44:45] sc1
	s_mov_b32 m0, s27
	s_nop 0
	global_load_lds_dwordx4 v164, s[100:101] sc1
	s_mov_b32 m0, s26
	s_nop 0
	global_load_lds_dwordx4 v162, s[100:101] sc1
	s_waitcnt vmcnt(8)
	s_waitcnt lgkmcnt(0)
	s_barrier
	s_waitcnt lgkmcnt(0)
	v_mfma_f32_16x16x32_bf16 v[62:65], v[134:137], v[178:181], v[62:65]
	v_mfma_f32_16x16x32_bf16 v[62:65], v[138:141], v[182:185], v[62:65]
	v_mfma_f32_16x16x32_bf16 v[58:61], v[146:149], v[182:185], v[58:61]
	v_mfma_f32_16x16x32_bf16 v[58:61], v[142:145], v[178:181], v[58:61]
	v_mfma_f32_16x16x32_bf16 v[54:57], v[150:153], v[178:181], v[54:57]
	v_mfma_f32_16x16x32_bf16 v[54:57], v[154:157], v[182:185], v[54:57]
	v_mfma_f32_16x16x32_bf16 v[50:53], v[174:177], v[182:185], v[50:53]
	v_mfma_f32_16x16x32_bf16 v[50:53], v[158:161], v[178:181], v[50:53]
	v_mfma_f32_16x16x32_bf16 v[34:37], v[158:161], v[186:189], v[34:37]
	v_mfma_f32_16x16x32_bf16 v[34:37], v[174:177], v[190:193], v[34:37]
	v_mfma_f32_16x16x32_bf16 v[38:41], v[154:157], v[190:193], v[38:41]
	v_mfma_f32_16x16x32_bf16 v[38:41], v[150:153], v[186:189], v[38:41]
	v_mfma_f32_16x16x32_bf16 v[42:45], v[142:145], v[186:189], v[42:45]
	v_mfma_f32_16x16x32_bf16 v[42:45], v[146:149], v[190:193], v[42:45]
	v_mfma_f32_16x16x32_bf16 v[46:49], v[138:141], v[190:193], v[46:49]
	v_mfma_f32_16x16x32_bf16 v[46:49], v[134:137], v[186:189], v[46:49]
	v_mfma_f32_16x16x32_bf16 v[30:33], v[134:137], v[204:207], v[30:33]
	v_mfma_f32_16x16x32_bf16 v[30:33], v[138:141], v[208:211], v[30:33]
	v_mfma_f32_16x16x32_bf16 v[26:29], v[146:149], v[208:211], v[26:29]
	v_mfma_f32_16x16x32_bf16 v[26:29], v[142:145], v[204:207], v[26:29]
	v_mfma_f32_16x16x32_bf16 v[22:25], v[150:153], v[204:207], v[22:25]
	v_mfma_f32_16x16x32_bf16 v[22:25], v[154:157], v[208:211], v[22:25]
	v_mfma_f32_16x16x32_bf16 v[18:21], v[174:177], v[208:211], v[18:21]
	v_mfma_f32_16x16x32_bf16 v[18:21], v[158:161], v[204:207], v[18:21]
	v_mfma_f32_16x16x32_bf16 v[2:5], v[158:161], v[212:215], v[2:5]
	v_mfma_f32_16x16x32_bf16 v[2:5], v[174:177], v[216:219], v[2:5]
	v_mfma_f32_16x16x32_bf16 v[6:9], v[154:157], v[216:219], v[6:9]
	v_mfma_f32_16x16x32_bf16 v[6:9], v[150:153], v[212:215], v[6:9]
	v_mfma_f32_16x16x32_bf16 v[10:13], v[142:145], v[212:215], v[10:13]
	v_mfma_f32_16x16x32_bf16 v[10:13], v[146:149], v[216:219], v[10:13]
	v_mfma_f32_16x16x32_bf16 v[14:17], v[138:141], v[216:219], v[14:17]
	v_mfma_f32_16x16x32_bf16 v[14:17], v[134:137], v[212:215], v[14:17]
	s_barrier
	s_add_i32 s43, s43, 2
	s_add_u32 s76, s76, 0x100
	s_addc_u32 s77, s77, 0
	s_add_u32 s7, s7, 0x100
	s_addc_u32 s41, s41, 0
	s_cmp_gt_u32 s43, 29
	s_cbranch_scc1 .LBB0_288
	s_branch .LBB0_286

.LBB0_509:
	s_add_u32 s90, s76, 0x100
	s_addc_u32 s91, s77, 0
	s_and_b64 s[0:1], s[70:71], exec
	s_cselect_b32 vcc_hi, s22, s91
	s_cselect_b32 vcc_lo, s23, s90
	s_cselect_b32 s71, s41, s53
	s_cselect_b32 s70, s44, s51
	s_add_i32 s0, 0, 0x10000
	s_add_i32 s18, 0, 0x14000
	v_add_u32_e32 v114, s0, v1
	v_add_u32_e32 v154, s18, v1
	ds_read_b128 v[78:81], v114
	ds_read_b128 v[90:93], v114 offset:1024
	ds_read_b128 v[102:105], v114 offset:2048
	ds_read_b128 v[114:117], v114 offset:3072
	ds_read_b128 v[126:129], v154
	ds_read_b128 v[134:137], v154 offset:1024
	ds_read_b128 v[142:145], v154 offset:2048
	ds_read_b128 v[154:157], v154 offset:3072
	s_add_i32 m0, s29, 0xc000
	ds_read_b128 v[158:161], v237
	ds_read_b128 v[162:165], v237 offset:1024
	ds_read_b128 v[166:169], v237 offset:2048
	ds_read_b128 v[178:181], v237 offset:3072
	ds_read_b128 v[182:185], v237 offset:4096
	ds_read_b128 v[186:189], v237 offset:5120
	ds_read_b128 v[190:193], v237 offset:6144
	ds_read_b128 v[214:217], v237 offset:7168
	global_load_lds_dwordx4 v210, s[76:77] sc1
	s_add_i32 m0, s29, 0xe000
	s_nop 0
	global_load_lds_dwordx4 v212, s[76:77] sc1
	s_waitcnt vmcnt(8)
	s_waitcnt lgkmcnt(0)
	s_barrier
	s_waitcnt lgkmcnt(0)
	v_mfma_f32_16x16x32_bf16 v[174:177], v[78:81], v[158:161], v[174:177]
	v_mfma_f32_16x16x32_bf16 v[174:177], v[90:93], v[162:165], v[174:177]
	v_mfma_f32_16x16x32_bf16 v[170:173], v[114:117], v[162:165], v[170:173]
	v_mfma_f32_16x16x32_bf16 v[170:173], v[102:105], v[158:161], v[170:173]
	v_mfma_f32_16x16x32_bf16 v[150:153], v[126:129], v[158:161], v[150:153]
	v_mfma_f32_16x16x32_bf16 v[150:153], v[134:137], v[162:165], v[150:153]
	v_mfma_f32_16x16x32_bf16 v[146:149], v[154:157], v[162:165], v[146:149]
	v_mfma_f32_16x16x32_bf16 v[146:149], v[142:145], v[158:161], v[146:149]
	v_mfma_f32_16x16x32_bf16 v[118:121], v[142:145], v[166:169], v[118:121]
	v_mfma_f32_16x16x32_bf16 v[118:121], v[154:157], v[178:181], v[118:121]
	v_mfma_f32_16x16x32_bf16 v[122:125], v[134:137], v[178:181], v[122:125]
	v_mfma_f32_16x16x32_bf16 v[122:125], v[126:129], v[166:169], v[122:125]
	v_mfma_f32_16x16x32_bf16 v[130:133], v[102:105], v[166:169], v[130:133]
	v_mfma_f32_16x16x32_bf16 v[130:133], v[114:117], v[178:181], v[130:133]
	v_mfma_f32_16x16x32_bf16 v[138:141], v[90:93], v[178:181], v[138:141]
	v_mfma_f32_16x16x32_bf16 v[138:141], v[78:81], v[166:169], v[138:141]
	v_mfma_f32_16x16x32_bf16 v[110:113], v[78:81], v[182:185], v[110:113]
	v_mfma_f32_16x16x32_bf16 v[110:113], v[90:93], v[186:189], v[110:113]
	v_mfma_f32_16x16x32_bf16 v[106:109], v[114:117], v[186:189], v[106:109]
	v_mfma_f32_16x16x32_bf16 v[106:109], v[102:105], v[182:185], v[106:109]
	v_mfma_f32_16x16x32_bf16 v[98:101], v[126:129], v[182:185], v[98:101]
	v_mfma_f32_16x16x32_bf16 v[98:101], v[134:137], v[186:189], v[98:101]
	v_mfma_f32_16x16x32_bf16 v[94:97], v[154:157], v[186:189], v[94:97]
	v_mfma_f32_16x16x32_bf16 v[94:97], v[142:145], v[182:185], v[94:97]
	v_mfma_f32_16x16x32_bf16 v[66:69], v[142:145], v[190:193], v[66:69]
	v_mfma_f32_16x16x32_bf16 v[66:69], v[154:157], v[214:217], v[66:69]
	v_mfma_f32_16x16x32_bf16 v[74:77], v[134:137], v[214:217], v[74:77]
	v_mfma_f32_16x16x32_bf16 v[74:77], v[126:129], v[190:193], v[74:77]
	v_mfma_f32_16x16x32_bf16 v[82:85], v[102:105], v[190:193], v[82:85]
	v_mfma_f32_16x16x32_bf16 v[82:85], v[114:117], v[214:217], v[82:85]
	v_mfma_f32_16x16x32_bf16 v[86:89], v[90:93], v[214:217], v[86:89]
	v_mfma_f32_16x16x32_bf16 v[86:89], v[78:81], v[190:193], v[86:89]
	s_barrier
	s_add_i32 s0, s0, s28
	s_mov_b32 m0, s0
	ds_read_b128 v[158:161], v237 offset:16384
	ds_read_b128 v[162:165], v237 offset:17408
	ds_read_b128 v[166:169], v237 offset:18432
	ds_read_b128 v[178:181], v237 offset:19456
	ds_read_b128 v[182:185], v237 offset:20480
	ds_read_b128 v[186:189], v237 offset:21504
	ds_read_b128 v[190:193], v237 offset:22528
	ds_read_b128 v[214:217], v237 offset:23552
	global_load_lds_dwordx4 v194, s[70:71] sc1
	s_add_i32 m0, s0, 0x2000
	s_add_u32 s0, s70, 0x80000
	s_addc_u32 s1, s71, 0
	s_add_i32 s18, s18, s28
	global_load_lds_dwordx4 v204, s[70:71] sc1
	s_mov_b32 m0, s18
	s_nop 0
	global_load_lds_dwordx4 v194, s[0:1] sc1
	s_add_i32 m0, s18, 0x2000
	s_nop 0
	global_load_lds_dwordx4 v204, s[0:1] sc1
	s_mov_b32 m0, s29
	s_nop 0
	global_load_lds_dwordx4 v194, vcc sc1
	s_mov_b32 m0, s31
	s_nop 0
	global_load_lds_dwordx4 v204, vcc sc1
	s_waitcnt vmcnt(8)
	s_waitcnt lgkmcnt(0)
	s_barrier
	s_waitcnt lgkmcnt(0)
	v_mfma_f32_16x16x32_bf16 v[62:65], v[78:81], v[158:161], v[62:65]
	v_mfma_f32_16x16x32_bf16 v[62:65], v[90:93], v[162:165], v[62:65]
	v_mfma_f32_16x16x32_bf16 v[58:61], v[114:117], v[162:165], v[58:61]
	v_mfma_f32_16x16x32_bf16 v[58:61], v[102:105], v[158:161], v[58:61]
	v_mfma_f32_16x16x32_bf16 v[54:57], v[126:129], v[158:161], v[54:57]
	v_mfma_f32_16x16x32_bf16 v[54:57], v[134:137], v[162:165], v[54:57]
	v_mfma_f32_16x16x32_bf16 v[50:53], v[154:157], v[162:165], v[50:53]
	v_mfma_f32_16x16x32_bf16 v[50:53], v[142:145], v[158:161], v[50:53]
	v_mfma_f32_16x16x32_bf16 v[34:37], v[142:145], v[166:169], v[34:37]
	v_mfma_f32_16x16x32_bf16 v[34:37], v[154:157], v[178:181], v[34:37]
	v_mfma_f32_16x16x32_bf16 v[38:41], v[134:137], v[178:181], v[38:41]
	v_mfma_f32_16x16x32_bf16 v[38:41], v[126:129], v[166:169], v[38:41]
	v_mfma_f32_16x16x32_bf16 v[42:45], v[102:105], v[166:169], v[42:45]
	v_mfma_f32_16x16x32_bf16 v[42:45], v[114:117], v[178:181], v[42:45]
	v_mfma_f32_16x16x32_bf16 v[46:49], v[90:93], v[178:181], v[46:49]
	v_mfma_f32_16x16x32_bf16 v[46:49], v[78:81], v[166:169], v[46:49]
	v_mfma_f32_16x16x32_bf16 v[30:33], v[78:81], v[182:185], v[30:33]
	v_mfma_f32_16x16x32_bf16 v[30:33], v[90:93], v[186:189], v[30:33]
	v_mfma_f32_16x16x32_bf16 v[26:29], v[114:117], v[186:189], v[26:29]
	v_mfma_f32_16x16x32_bf16 v[26:29], v[102:105], v[182:185], v[26:29]
	v_mfma_f32_16x16x32_bf16 v[22:25], v[126:129], v[182:185], v[22:25]
	v_mfma_f32_16x16x32_bf16 v[22:25], v[134:137], v[186:189], v[22:25]
	v_mfma_f32_16x16x32_bf16 v[18:21], v[154:157], v[186:189], v[18:21]
	v_mfma_f32_16x16x32_bf16 v[18:21], v[142:145], v[182:185], v[18:21]
	v_mfma_f32_16x16x32_bf16 v[2:5], v[142:145], v[190:193], v[2:5]
	v_mfma_f32_16x16x32_bf16 v[2:5], v[154:157], v[214:217], v[2:5]
	v_mfma_f32_16x16x32_bf16 v[6:9], v[134:137], v[214:217], v[6:9]
	v_mfma_f32_16x16x32_bf16 v[6:9], v[126:129], v[190:193], v[6:9]
	v_mfma_f32_16x16x32_bf16 v[10:13], v[102:105], v[190:193], v[10:13]
	v_mfma_f32_16x16x32_bf16 v[10:13], v[114:117], v[214:217], v[10:13]
	v_mfma_f32_16x16x32_bf16 v[14:17], v[90:93], v[214:217], v[14:17]
	v_mfma_f32_16x16x32_bf16 v[14:17], v[78:81], v[190:193], v[14:17]
	s_barrier
	s_add_i32 s18, 0, 0x18000
	s_add_i32 s19, 0, 0x1c000
	v_add_u32_e32 v114, s18, v1
	v_add_u32_e32 v154, s19, v1
	ds_read_b128 v[78:81], v114
	ds_read_b128 v[90:93], v114 offset:1024
	ds_read_b128 v[102:105], v114 offset:2048
	ds_read_b128 v[114:117], v114 offset:3072
	ds_read_b128 v[126:129], v154
	ds_read_b128 v[134:137], v154 offset:1024
	ds_read_b128 v[142:145], v154 offset:2048
	ds_read_b128 v[154:157], v154 offset:3072
	s_add_u32 s0, vcc_lo, 0x80000
	s_addc_u32 s1, vcc_hi, 0
	s_mov_b32 m0, s33
	ds_read_b128 v[158:161], v237 offset:32768
	ds_read_b128 v[162:165], v237 offset:33792
	ds_read_b128 v[166:169], v237 offset:34816
	ds_read_b128 v[178:181], v237 offset:35840
	ds_read_b128 v[182:185], v237 offset:36864
	ds_read_b128 v[186:189], v237 offset:37888
	ds_read_b128 v[190:193], v237 offset:38912
	ds_read_b128 v[214:217], v237 offset:39936
	global_load_lds_dwordx4 v194, s[0:1] sc1
	s_mov_b32 m0, s43
	s_nop 0
	global_load_lds_dwordx4 v204, s[0:1] sc1
	s_waitcnt vmcnt(8)
	s_waitcnt lgkmcnt(0)
	s_barrier
	s_waitcnt lgkmcnt(0)
	v_mfma_f32_16x16x32_bf16 v[174:177], v[78:81], v[158:161], v[174:177]
	v_mfma_f32_16x16x32_bf16 v[174:177], v[90:93], v[162:165], v[174:177]
	v_mfma_f32_16x16x32_bf16 v[170:173], v[114:117], v[162:165], v[170:173]
	v_mfma_f32_16x16x32_bf16 v[170:173], v[102:105], v[158:161], v[170:173]
	v_mfma_f32_16x16x32_bf16 v[150:153], v[126:129], v[158:161], v[150:153]
	v_mfma_f32_16x16x32_bf16 v[150:153], v[134:137], v[162:165], v[150:153]
	v_mfma_f32_16x16x32_bf16 v[146:149], v[154:157], v[162:165], v[146:149]
	v_mfma_f32_16x16x32_bf16 v[146:149], v[142:145], v[158:161], v[146:149]
	v_mfma_f32_16x16x32_bf16 v[118:121], v[142:145], v[166:169], v[118:121]
	v_mfma_f32_16x16x32_bf16 v[118:121], v[154:157], v[178:181], v[118:121]
	v_mfma_f32_16x16x32_bf16 v[122:125], v[134:137], v[178:181], v[122:125]
	v_mfma_f32_16x16x32_bf16 v[122:125], v[126:129], v[166:169], v[122:125]
	v_mfma_f32_16x16x32_bf16 v[130:133], v[102:105], v[166:169], v[130:133]
	v_mfma_f32_16x16x32_bf16 v[130:133], v[114:117], v[178:181], v[130:133]
	v_mfma_f32_16x16x32_bf16 v[138:141], v[90:93], v[178:181], v[138:141]
	v_mfma_f32_16x16x32_bf16 v[138:141], v[78:81], v[166:169], v[138:141]
	v_mfma_f32_16x16x32_bf16 v[110:113], v[78:81], v[182:185], v[110:113]
	v_mfma_f32_16x16x32_bf16 v[110:113], v[90:93], v[186:189], v[110:113]
	v_mfma_f32_16x16x32_bf16 v[106:109], v[114:117], v[186:189], v[106:109]
	v_mfma_f32_16x16x32_bf16 v[106:109], v[102:105], v[182:185], v[106:109]
	v_mfma_f32_16x16x32_bf16 v[98:101], v[126:129], v[182:185], v[98:101]
	v_mfma_f32_16x16x32_bf16 v[98:101], v[134:137], v[186:189], v[98:101]
	v_mfma_f32_16x16x32_bf16 v[94:97], v[154:157], v[186:189], v[94:97]
	v_mfma_f32_16x16x32_bf16 v[94:97], v[142:145], v[182:185], v[94:97]
	v_mfma_f32_16x16x32_bf16 v[66:69], v[142:145], v[190:193], v[66:69]
	v_mfma_f32_16x16x32_bf16 v[66:69], v[154:157], v[214:217], v[66:69]
	v_mfma_f32_16x16x32_bf16 v[74:77], v[134:137], v[214:217], v[74:77]
	v_mfma_f32_16x16x32_bf16 v[74:77], v[126:129], v[190:193], v[74:77]
	v_mfma_f32_16x16x32_bf16 v[82:85], v[102:105], v[190:193], v[82:85]
	v_mfma_f32_16x16x32_bf16 v[82:85], v[114:117], v[214:217], v[82:85]
	v_mfma_f32_16x16x32_bf16 v[86:89], v[90:93], v[214:217], v[86:89]
	v_mfma_f32_16x16x32_bf16 v[86:89], v[78:81], v[190:193], v[86:89]
	s_barrier
	s_add_u32 s98, s70, 0x80
	s_addc_u32 s99, s71, 0
	s_add_u32 s100, vcc_lo, 0x80
	s_addc_u32 s101, vcc_hi, 0
	s_add_i32 s0, s18, s28
	s_mov_b32 m0, s0
	ds_read_b128 v[158:161], v237 offset:49152
	ds_read_b128 v[162:165], v237 offset:50176
	ds_read_b128 v[166:169], v237 offset:51200
	ds_read_b128 v[178:181], v237 offset:52224
	ds_read_b128 v[182:185], v237 offset:53248
	ds_read_b128 v[186:189], v237 offset:54272
	ds_read_b128 v[190:193], v237 offset:55296
	ds_read_b128 v[214:217], v237 offset:56320
	global_load_lds_dwordx4 v194, s[98:99] sc1
	s_add_i32 m0, s0, 0x2000
	s_add_u32 s0, s70, 0x80080
	s_addc_u32 s1, s71, 0
	s_add_i32 s18, s19, s28
	global_load_lds_dwordx4 v204, s[98:99] sc1
	s_mov_b32 m0, s18
	s_nop 0
	global_load_lds_dwordx4 v194, s[0:1] sc1
	s_add_i32 m0, s18, 0x2000
	s_nop 0
	global_load_lds_dwordx4 v204, s[0:1] sc1
	s_mov_b32 m0, s68
	s_nop 0
	global_load_lds_dwordx4 v194, s[100:101] sc1
	s_mov_b32 m0, s79
	s_nop 0
	global_load_lds_dwordx4 v204, s[100:101] sc1
	s_waitcnt vmcnt(8)
	s_waitcnt lgkmcnt(0)
	s_barrier
	s_waitcnt lgkmcnt(0)
	v_mfma_f32_16x16x32_bf16 v[62:65], v[78:81], v[158:161], v[62:65]
	v_mfma_f32_16x16x32_bf16 v[62:65], v[90:93], v[162:165], v[62:65]
	v_mfma_f32_16x16x32_bf16 v[58:61], v[114:117], v[162:165], v[58:61]
	v_mfma_f32_16x16x32_bf16 v[58:61], v[102:105], v[158:161], v[58:61]
	v_mfma_f32_16x16x32_bf16 v[54:57], v[126:129], v[158:161], v[54:57]
	v_mfma_f32_16x16x32_bf16 v[54:57], v[134:137], v[162:165], v[54:57]
	v_mfma_f32_16x16x32_bf16 v[50:53], v[154:157], v[162:165], v[50:53]
	v_mfma_f32_16x16x32_bf16 v[50:53], v[142:145], v[158:161], v[50:53]
	v_mfma_f32_16x16x32_bf16 v[34:37], v[142:145], v[166:169], v[34:37]
	v_mfma_f32_16x16x32_bf16 v[34:37], v[154:157], v[178:181], v[34:37]
	v_mfma_f32_16x16x32_bf16 v[38:41], v[134:137], v[178:181], v[38:41]
	v_mfma_f32_16x16x32_bf16 v[38:41], v[126:129], v[166:169], v[38:41]
	v_mfma_f32_16x16x32_bf16 v[42:45], v[102:105], v[166:169], v[42:45]
	v_mfma_f32_16x16x32_bf16 v[42:45], v[114:117], v[178:181], v[42:45]
	v_mfma_f32_16x16x32_bf16 v[46:49], v[90:93], v[178:181], v[46:49]
	v_mfma_f32_16x16x32_bf16 v[46:49], v[78:81], v[166:169], v[46:49]
	v_mfma_f32_16x16x32_bf16 v[30:33], v[78:81], v[182:185], v[30:33]
	v_mfma_f32_16x16x32_bf16 v[30:33], v[90:93], v[186:189], v[30:33]
	v_mfma_f32_16x16x32_bf16 v[26:29], v[114:117], v[186:189], v[26:29]
	v_mfma_f32_16x16x32_bf16 v[26:29], v[102:105], v[182:185], v[26:29]
	v_mfma_f32_16x16x32_bf16 v[22:25], v[126:129], v[182:185], v[22:25]
	v_mfma_f32_16x16x32_bf16 v[22:25], v[134:137], v[186:189], v[22:25]
	v_mfma_f32_16x16x32_bf16 v[18:21], v[154:157], v[186:189], v[18:21]
	v_mfma_f32_16x16x32_bf16 v[18:21], v[142:145], v[182:185], v[18:21]
	v_mfma_f32_16x16x32_bf16 v[2:5], v[142:145], v[190:193], v[2:5]
	v_mfma_f32_16x16x32_bf16 v[2:5], v[154:157], v[214:217], v[2:5]
	v_mfma_f32_16x16x32_bf16 v[6:9], v[134:137], v[214:217], v[6:9]
	v_mfma_f32_16x16x32_bf16 v[6:9], v[126:129], v[190:193], v[6:9]
	v_mfma_f32_16x16x32_bf16 v[10:13], v[102:105], v[190:193], v[10:13]
	v_mfma_f32_16x16x32_bf16 v[10:13], v[114:117], v[214:217], v[10:13]
	v_mfma_f32_16x16x32_bf16 v[14:17], v[90:93], v[214:217], v[14:17]
	v_mfma_f32_16x16x32_bf16 v[14:17], v[78:81], v[190:193], v[14:17]
	s_barrier
	s_add_i32 s57, s57, 2
	s_add_u32 s51, s51, 0x100
	s_addc_u32 s53, s53, 0
	s_cmp_gt_u32 s57, 29
	s_mov_b64 s[76:77], s[90:91]
	s_cbranch_scc1 .LBB0_512

.Lpeel_disp_out:
	s_cmp_lg_u32 s57, -2
	s_cbranch_scc1 .LBB0_509
	s_add_u32 s90, s76, 0x100
	s_addc_u32 s91, s77, 0
	s_and_b64 s[0:1], s[70:71], exec
	s_cselect_b32 vcc_hi, s22, s91
	s_cselect_b32 vcc_lo, s23, s90
	s_cselect_b32 s71, s41, s53
	s_cselect_b32 s70, s44, s51
	s_add_i32 s0, 0, 0x10000
	s_add_i32 s18, 0, 0x14000
	v_add_u32_e32 v114, s0, v1
	v_add_u32_e32 v154, s18, v1
	ds_read_b128 v[78:81], v114
	ds_read_b128 v[90:93], v114 offset:1024
	ds_read_b128 v[102:105], v114 offset:2048
	ds_read_b128 v[114:117], v114 offset:3072
	ds_read_b128 v[126:129], v154
	ds_read_b128 v[134:137], v154 offset:1024
	ds_read_b128 v[142:145], v154 offset:2048
	ds_read_b128 v[154:157], v154 offset:3072
	s_add_i32 m0, s29, 0xc000
	ds_read_b128 v[158:161], v237
	ds_read_b128 v[162:165], v237 offset:1024
	ds_read_b128 v[166:169], v237 offset:2048
	ds_read_b128 v[178:181], v237 offset:3072
	ds_read_b128 v[182:185], v237 offset:4096
	ds_read_b128 v[186:189], v237 offset:5120
	ds_read_b128 v[190:193], v237 offset:6144
	ds_read_b128 v[214:217], v237 offset:7168
	global_load_lds_dwordx4 v210, s[76:77] sc1
	s_add_i32 m0, s29, 0xe000
	s_nop 0
	global_load_lds_dwordx4 v212, s[76:77] sc1
	s_waitcnt vmcnt(8)
	s_waitcnt lgkmcnt(0)
	s_barrier
	s_waitcnt lgkmcnt(0)
	v_mfma_f32_16x16x32_bf16 v[174:177], v[78:81], v[158:161], 0
	v_mfma_f32_16x16x32_bf16 v[174:177], v[90:93], v[162:165], v[174:177]
	v_mfma_f32_16x16x32_bf16 v[170:173], v[114:117], v[162:165], 0
	v_mfma_f32_16x16x32_bf16 v[170:173], v[102:105], v[158:161], v[170:173]
	v_mfma_f32_16x16x32_bf16 v[150:153], v[126:129], v[158:161], 0
	v_mfma_f32_16x16x32_bf16 v[150:153], v[134:137], v[162:165], v[150:153]
	v_mfma_f32_16x16x32_bf16 v[146:149], v[154:157], v[162:165], 0
	v_mfma_f32_16x16x32_bf16 v[146:149], v[142:145], v[158:161], v[146:149]
	v_mfma_f32_16x16x32_bf16 v[118:121], v[142:145], v[166:169], 0
	v_mfma_f32_16x16x32_bf16 v[118:121], v[154:157], v[178:181], v[118:121]
	v_mfma_f32_16x16x32_bf16 v[122:125], v[134:137], v[178:181], 0
	v_mfma_f32_16x16x32_bf16 v[122:125], v[126:129], v[166:169], v[122:125]
	v_mfma_f32_16x16x32_bf16 v[130:133], v[102:105], v[166:169], 0
	v_mfma_f32_16x16x32_bf16 v[130:133], v[114:117], v[178:181], v[130:133]
	v_mfma_f32_16x16x32_bf16 v[138:141], v[90:93], v[178:181], 0
	v_mfma_f32_16x16x32_bf16 v[138:141], v[78:81], v[166:169], v[138:141]
	v_mfma_f32_16x16x32_bf16 v[110:113], v[78:81], v[182:185], 0
	v_mfma_f32_16x16x32_bf16 v[110:113], v[90:93], v[186:189], v[110:113]
	v_mfma_f32_16x16x32_bf16 v[106:109], v[114:117], v[186:189], 0
	v_mfma_f32_16x16x32_bf16 v[106:109], v[102:105], v[182:185], v[106:109]
	v_mfma_f32_16x16x32_bf16 v[98:101], v[126:129], v[182:185], 0
	v_mfma_f32_16x16x32_bf16 v[98:101], v[134:137], v[186:189], v[98:101]
	v_mfma_f32_16x16x32_bf16 v[94:97], v[154:157], v[186:189], 0
	v_mfma_f32_16x16x32_bf16 v[94:97], v[142:145], v[182:185], v[94:97]
	v_mfma_f32_16x16x32_bf16 v[66:69], v[142:145], v[190:193], 0
	v_mfma_f32_16x16x32_bf16 v[66:69], v[154:157], v[214:217], v[66:69]
	v_mfma_f32_16x16x32_bf16 v[74:77], v[134:137], v[214:217], 0
	v_mfma_f32_16x16x32_bf16 v[74:77], v[126:129], v[190:193], v[74:77]
	v_mfma_f32_16x16x32_bf16 v[82:85], v[102:105], v[190:193], 0
	v_mfma_f32_16x16x32_bf16 v[82:85], v[114:117], v[214:217], v[82:85]
	v_mfma_f32_16x16x32_bf16 v[86:89], v[90:93], v[214:217], 0
	v_mfma_f32_16x16x32_bf16 v[86:89], v[78:81], v[190:193], v[86:89]
	s_barrier
	s_add_i32 s0, s0, s28
	s_mov_b32 m0, s0
	ds_read_b128 v[158:161], v237 offset:16384
	ds_read_b128 v[162:165], v237 offset:17408
	ds_read_b128 v[166:169], v237 offset:18432
	ds_read_b128 v[178:181], v237 offset:19456
	ds_read_b128 v[182:185], v237 offset:20480
	ds_read_b128 v[186:189], v237 offset:21504
	ds_read_b128 v[190:193], v237 offset:22528
	ds_read_b128 v[214:217], v237 offset:23552
	global_load_lds_dwordx4 v194, s[70:71] sc1
	s_add_i32 m0, s0, 0x2000
	s_add_u32 s0, s70, 0x80000
	s_addc_u32 s1, s71, 0
	s_add_i32 s18, s18, s28
	global_load_lds_dwordx4 v204, s[70:71] sc1
	s_mov_b32 m0, s18
	s_nop 0
	global_load_lds_dwordx4 v194, s[0:1] sc1
	s_add_i32 m0, s18, 0x2000
	s_nop 0
	global_load_lds_dwordx4 v204, s[0:1] sc1
	s_mov_b32 m0, s29
	s_nop 0
	global_load_lds_dwordx4 v194, vcc sc1
	s_mov_b32 m0, s31
	s_nop 0
	global_load_lds_dwordx4 v204, vcc sc1
	s_waitcnt vmcnt(8)
	s_waitcnt lgkmcnt(0)
	s_barrier
	s_waitcnt lgkmcnt(0)
	v_mfma_f32_16x16x32_bf16 v[62:65], v[78:81], v[158:161], 0
	v_mfma_f32_16x16x32_bf16 v[62:65], v[90:93], v[162:165], v[62:65]
	v_mfma_f32_16x16x32_bf16 v[58:61], v[114:117], v[162:165], 0
	v_mfma_f32_16x16x32_bf16 v[58:61], v[102:105], v[158:161], v[58:61]
	v_mfma_f32_16x16x32_bf16 v[54:57], v[126:129], v[158:161], 0
	v_mfma_f32_16x16x32_bf16 v[54:57], v[134:137], v[162:165], v[54:57]
	v_mfma_f32_16x16x32_bf16 v[50:53], v[154:157], v[162:165], 0
	v_mfma_f32_16x16x32_bf16 v[50:53], v[142:145], v[158:161], v[50:53]
	v_mfma_f32_16x16x32_bf16 v[34:37], v[142:145], v[166:169], 0
	v_mfma_f32_16x16x32_bf16 v[34:37], v[154:157], v[178:181], v[34:37]
	v_mfma_f32_16x16x32_bf16 v[38:41], v[134:137], v[178:181], 0
	v_mfma_f32_16x16x32_bf16 v[38:41], v[126:129], v[166:169], v[38:41]
	v_mfma_f32_16x16x32_bf16 v[42:45], v[102:105], v[166:169], 0
	v_mfma_f32_16x16x32_bf16 v[42:45], v[114:117], v[178:181], v[42:45]
	v_mfma_f32_16x16x32_bf16 v[46:49], v[90:93], v[178:181], 0
	v_mfma_f32_16x16x32_bf16 v[46:49], v[78:81], v[166:169], v[46:49]
	v_mfma_f32_16x16x32_bf16 v[30:33], v[78:81], v[182:185], 0
	v_mfma_f32_16x16x32_bf16 v[30:33], v[90:93], v[186:189], v[30:33]
	v_mfma_f32_16x16x32_bf16 v[26:29], v[114:117], v[186:189], 0
	v_mfma_f32_16x16x32_bf16 v[26:29], v[102:105], v[182:185], v[26:29]
	v_mfma_f32_16x16x32_bf16 v[22:25], v[126:129], v[182:185], 0
	v_mfma_f32_16x16x32_bf16 v[22:25], v[134:137], v[186:189], v[22:25]
	v_mfma_f32_16x16x32_bf16 v[18:21], v[154:157], v[186:189], 0
	v_mfma_f32_16x16x32_bf16 v[18:21], v[142:145], v[182:185], v[18:21]
	v_mfma_f32_16x16x32_bf16 v[2:5], v[142:145], v[190:193], 0
	v_mfma_f32_16x16x32_bf16 v[2:5], v[154:157], v[214:217], v[2:5]
	v_mfma_f32_16x16x32_bf16 v[6:9], v[134:137], v[214:217], 0
	v_mfma_f32_16x16x32_bf16 v[6:9], v[126:129], v[190:193], v[6:9]
	v_mfma_f32_16x16x32_bf16 v[10:13], v[102:105], v[190:193], 0
	v_mfma_f32_16x16x32_bf16 v[10:13], v[114:117], v[214:217], v[10:13]
	v_mfma_f32_16x16x32_bf16 v[14:17], v[90:93], v[214:217], 0
	v_mfma_f32_16x16x32_bf16 v[14:17], v[78:81], v[190:193], v[14:17]
	s_barrier
	s_add_i32 s18, 0, 0x18000
	s_add_i32 s19, 0, 0x1c000
	v_add_u32_e32 v114, s18, v1
	v_add_u32_e32 v154, s19, v1
	ds_read_b128 v[78:81], v114
	ds_read_b128 v[90:93], v114 offset:1024
	ds_read_b128 v[102:105], v114 offset:2048
	ds_read_b128 v[114:117], v114 offset:3072
	ds_read_b128 v[126:129], v154
	ds_read_b128 v[134:137], v154 offset:1024
	ds_read_b128 v[142:145], v154 offset:2048
	ds_read_b128 v[154:157], v154 offset:3072
	s_add_u32 s0, vcc_lo, 0x80000
	s_addc_u32 s1, vcc_hi, 0
	s_mov_b32 m0, s33
	ds_read_b128 v[158:161], v237 offset:32768
	ds_read_b128 v[162:165], v237 offset:33792
	ds_read_b128 v[166:169], v237 offset:34816
	ds_read_b128 v[178:181], v237 offset:35840
	ds_read_b128 v[182:185], v237 offset:36864
	ds_read_b128 v[186:189], v237 offset:37888
	ds_read_b128 v[190:193], v237 offset:38912
	ds_read_b128 v[214:217], v237 offset:39936
	global_load_lds_dwordx4 v194, s[0:1] sc1
	s_mov_b32 m0, s43
	s_nop 0
	global_load_lds_dwordx4 v204, s[0:1] sc1
	s_waitcnt vmcnt(8)
	s_waitcnt lgkmcnt(0)
	s_barrier
	s_waitcnt lgkmcnt(0)
	v_mfma_f32_16x16x32_bf16 v[174:177], v[78:81], v[158:161], v[174:177]
	v_mfma_f32_16x16x32_bf16 v[174:177], v[90:93], v[162:165], v[174:177]
	v_mfma_f32_16x16x32_bf16 v[170:173], v[114:117], v[162:165], v[170:173]
	v_mfma_f32_16x16x32_bf16 v[170:173], v[102:105], v[158:161], v[170:173]
	v_mfma_f32_16x16x32_bf16 v[150:153], v[126:129], v[158:161], v[150:153]
	v_mfma_f32_16x16x32_bf16 v[150:153], v[134:137], v[162:165], v[150:153]
	v_mfma_f32_16x16x32_bf16 v[146:149], v[154:157], v[162:165], v[146:149]
	v_mfma_f32_16x16x32_bf16 v[146:149], v[142:145], v[158:161], v[146:149]
	v_mfma_f32_16x16x32_bf16 v[118:121], v[142:145], v[166:169], v[118:121]
	v_mfma_f32_16x16x32_bf16 v[118:121], v[154:157], v[178:181], v[118:121]
	v_mfma_f32_16x16x32_bf16 v[122:125], v[134:137], v[178:181], v[122:125]
	v_mfma_f32_16x16x32_bf16 v[122:125], v[126:129], v[166:169], v[122:125]
	v_mfma_f32_16x16x32_bf16 v[130:133], v[102:105], v[166:169], v[130:133]
	v_mfma_f32_16x16x32_bf16 v[130:133], v[114:117], v[178:181], v[130:133]
	v_mfma_f32_16x16x32_bf16 v[138:141], v[90:93], v[178:181], v[138:141]
	v_mfma_f32_16x16x32_bf16 v[138:141], v[78:81], v[166:169], v[138:141]
	v_mfma_f32_16x16x32_bf16 v[110:113], v[78:81], v[182:185], v[110:113]
	v_mfma_f32_16x16x32_bf16 v[110:113], v[90:93], v[186:189], v[110:113]
	v_mfma_f32_16x16x32_bf16 v[106:109], v[114:117], v[186:189], v[106:109]
	v_mfma_f32_16x16x32_bf16 v[106:109], v[102:105], v[182:185], v[106:109]
	v_mfma_f32_16x16x32_bf16 v[98:101], v[126:129], v[182:185], v[98:101]
	v_mfma_f32_16x16x32_bf16 v[98:101], v[134:137], v[186:189], v[98:101]
	v_mfma_f32_16x16x32_bf16 v[94:97], v[154:157], v[186:189], v[94:97]
	v_mfma_f32_16x16x32_bf16 v[94:97], v[142:145], v[182:185], v[94:97]
	v_mfma_f32_16x16x32_bf16 v[66:69], v[142:145], v[190:193], v[66:69]
	v_mfma_f32_16x16x32_bf16 v[66:69], v[154:157], v[214:217], v[66:69]
	v_mfma_f32_16x16x32_bf16 v[74:77], v[134:137], v[214:217], v[74:77]
	v_mfma_f32_16x16x32_bf16 v[74:77], v[126:129], v[190:193], v[74:77]
	v_mfma_f32_16x16x32_bf16 v[82:85], v[102:105], v[190:193], v[82:85]
	v_mfma_f32_16x16x32_bf16 v[82:85], v[114:117], v[214:217], v[82:85]
	v_mfma_f32_16x16x32_bf16 v[86:89], v[90:93], v[214:217], v[86:89]
	v_mfma_f32_16x16x32_bf16 v[86:89], v[78:81], v[190:193], v[86:89]
	s_barrier
	s_add_u32 s98, s70, 0x80
	s_addc_u32 s99, s71, 0
	s_add_u32 s100, vcc_lo, 0x80
	s_addc_u32 s101, vcc_hi, 0
	s_add_i32 s0, s18, s28
	s_mov_b32 m0, s0
	ds_read_b128 v[158:161], v237 offset:49152
	ds_read_b128 v[162:165], v237 offset:50176
	ds_read_b128 v[166:169], v237 offset:51200
	ds_read_b128 v[178:181], v237 offset:52224
	ds_read_b128 v[182:185], v237 offset:53248
	ds_read_b128 v[186:189], v237 offset:54272
	ds_read_b128 v[190:193], v237 offset:55296
	ds_read_b128 v[214:217], v237 offset:56320
	global_load_lds_dwordx4 v194, s[98:99] sc1
	s_add_i32 m0, s0, 0x2000
	s_add_u32 s0, s70, 0x80080
	s_addc_u32 s1, s71, 0
	s_add_i32 s18, s19, s28
	global_load_lds_dwordx4 v204, s[98:99] sc1
	s_mov_b32 m0, s18
	s_nop 0
	global_load_lds_dwordx4 v194, s[0:1] sc1
	s_add_i32 m0, s18, 0x2000
	s_nop 0
	global_load_lds_dwordx4 v204, s[0:1] sc1
	s_mov_b32 m0, s68
	s_nop 0
	global_load_lds_dwordx4 v194, s[100:101] sc1
	s_mov_b32 m0, s79
	s_nop 0
	global_load_lds_dwordx4 v204, s[100:101] sc1
	s_waitcnt vmcnt(8)
	s_waitcnt lgkmcnt(0)
	s_barrier
	s_waitcnt lgkmcnt(0)
	v_mfma_f32_16x16x32_bf16 v[62:65], v[78:81], v[158:161], v[62:65]
	v_mfma_f32_16x16x32_bf16 v[62:65], v[90:93], v[162:165], v[62:65]
	v_mfma_f32_16x16x32_bf16 v[58:61], v[114:117], v[162:165], v[58:61]
	v_mfma_f32_16x16x32_bf16 v[58:61], v[102:105], v[158:161], v[58:61]
	v_mfma_f32_16x16x32_bf16 v[54:57], v[126:129], v[158:161], v[54:57]
	v_mfma_f32_16x16x32_bf16 v[54:57], v[134:137], v[162:165], v[54:57]
	v_mfma_f32_16x16x32_bf16 v[50:53], v[154:157], v[162:165], v[50:53]
	v_mfma_f32_16x16x32_bf16 v[50:53], v[142:145], v[158:161], v[50:53]
	v_mfma_f32_16x16x32_bf16 v[34:37], v[142:145], v[166:169], v[34:37]
	v_mfma_f32_16x16x32_bf16 v[34:37], v[154:157], v[178:181], v[34:37]
	v_mfma_f32_16x16x32_bf16 v[38:41], v[134:137], v[178:181], v[38:41]
	v_mfma_f32_16x16x32_bf16 v[38:41], v[126:129], v[166:169], v[38:41]
	v_mfma_f32_16x16x32_bf16 v[42:45], v[102:105], v[166:169], v[42:45]
	v_mfma_f32_16x16x32_bf16 v[42:45], v[114:117], v[178:181], v[42:45]
	v_mfma_f32_16x16x32_bf16 v[46:49], v[90:93], v[178:181], v[46:49]
	v_mfma_f32_16x16x32_bf16 v[46:49], v[78:81], v[166:169], v[46:49]
	v_mfma_f32_16x16x32_bf16 v[30:33], v[78:81], v[182:185], v[30:33]
	v_mfma_f32_16x16x32_bf16 v[30:33], v[90:93], v[186:189], v[30:33]
	v_mfma_f32_16x16x32_bf16 v[26:29], v[114:117], v[186:189], v[26:29]
	v_mfma_f32_16x16x32_bf16 v[26:29], v[102:105], v[182:185], v[26:29]
	v_mfma_f32_16x16x32_bf16 v[22:25], v[126:129], v[182:185], v[22:25]
	v_mfma_f32_16x16x32_bf16 v[22:25], v[134:137], v[186:189], v[22:25]
	v_mfma_f32_16x16x32_bf16 v[18:21], v[154:157], v[186:189], v[18:21]
	v_mfma_f32_16x16x32_bf16 v[18:21], v[142:145], v[182:185], v[18:21]
	v_mfma_f32_16x16x32_bf16 v[2:5], v[142:145], v[190:193], v[2:5]
	v_mfma_f32_16x16x32_bf16 v[2:5], v[154:157], v[214:217], v[2:5]
	v_mfma_f32_16x16x32_bf16 v[6:9], v[134:137], v[214:217], v[6:9]
	v_mfma_f32_16x16x32_bf16 v[6:9], v[126:129], v[190:193], v[6:9]
	v_mfma_f32_16x16x32_bf16 v[10:13], v[102:105], v[190:193], v[10:13]
	v_mfma_f32_16x16x32_bf16 v[10:13], v[114:117], v[214:217], v[10:13]
	v_mfma_f32_16x16x32_bf16 v[14:17], v[90:93], v[214:217], v[14:17]
	v_mfma_f32_16x16x32_bf16 v[14:17], v[78:81], v[190:193], v[14:17]
	s_barrier
	s_add_i32 s57, s57, 2
	s_add_u32 s51, s51, 0x100
	s_addc_u32 s53, s53, 0
	s_cmp_gt_u32 s57, 29
	s_mov_b64 s[76:77], s[90:91]
	s_cbranch_scc1 .LBB0_512
	s_branch .LBB0_510

.LBB0_581:
	s_add_u32 s18, s62, 0xfff80080
	s_addc_u32 s19, s63, -1
	s_and_b64 s[0:1], s[64:65], exec
	s_cselect_b32 s71, s22, s19
	s_cselect_b32 s70, s23, s18
	s_cselect_b32 s65, s39, s58
	s_cselect_b32 s64, s47, s53
	s_add_i32 s0, 0, 0x10000
	v_add_u32_e32 v153, s0, v1
	s_add_i32 s18, 0, 0x14000
	ds_read_b128 v[144:147], v153
	ds_read_b128 v[148:151], v153 offset:1024
	ds_read_b128 v[154:157], v153 offset:2048
	ds_read_b128 v[158:161], v153 offset:3072
	v_add_u32_e32 v153, s18, v1
	ds_read_b128 v[162:165], v153
	ds_read_b128 v[166:169], v153 offset:1024
	ds_read_b128 v[170:173], v153 offset:2048
	ds_read_b128 v[174:177], v153 offset:3072
	s_add_i32 m0, s29, 0xc000
	ds_read_b128 v[178:181], v152
	ds_read_b128 v[182:185], v152 offset:1024
	ds_read_b128 v[186:189], v152 offset:2048
	ds_read_b128 v[190:193], v152 offset:3072
	ds_read_b128 v[204:207], v152 offset:4096
	ds_read_b128 v[208:211], v152 offset:5120
	ds_read_b128 v[212:215], v152 offset:6144
	ds_read_b128 v[216:219], v152 offset:7168
	global_load_lds_dwordx4 v136, s[62:63] sc1
	s_add_i32 m0, s29, 0xe000
	s_nop 0
	global_load_lds_dwordx4 v138, s[62:63] sc1
	s_waitcnt vmcnt(8)
	s_waitcnt lgkmcnt(0)
	s_barrier
	s_waitcnt lgkmcnt(0)
	v_mfma_f32_16x16x32_bf16 v[126:129], v[144:147], v[178:181], v[126:129]
	v_mfma_f32_16x16x32_bf16 v[126:129], v[148:151], v[182:185], v[126:129]
	v_mfma_f32_16x16x32_bf16 v[122:125], v[158:161], v[182:185], v[122:125]
	v_mfma_f32_16x16x32_bf16 v[122:125], v[154:157], v[178:181], v[122:125]
	v_mfma_f32_16x16x32_bf16 v[118:121], v[162:165], v[178:181], v[118:121]
	v_mfma_f32_16x16x32_bf16 v[118:121], v[166:169], v[182:185], v[118:121]
	v_mfma_f32_16x16x32_bf16 v[114:117], v[174:177], v[182:185], v[114:117]
	v_mfma_f32_16x16x32_bf16 v[114:117], v[170:173], v[178:181], v[114:117]
	v_mfma_f32_16x16x32_bf16 v[98:101], v[170:173], v[186:189], v[98:101]
	v_mfma_f32_16x16x32_bf16 v[98:101], v[174:177], v[190:193], v[98:101]
	v_mfma_f32_16x16x32_bf16 v[102:105], v[166:169], v[190:193], v[102:105]
	v_mfma_f32_16x16x32_bf16 v[102:105], v[162:165], v[186:189], v[102:105]
	v_mfma_f32_16x16x32_bf16 v[106:109], v[154:157], v[186:189], v[106:109]
	v_mfma_f32_16x16x32_bf16 v[106:109], v[158:161], v[190:193], v[106:109]
	v_mfma_f32_16x16x32_bf16 v[110:113], v[148:151], v[190:193], v[110:113]
	v_mfma_f32_16x16x32_bf16 v[110:113], v[144:147], v[186:189], v[110:113]
	v_mfma_f32_16x16x32_bf16 v[94:97], v[144:147], v[204:207], v[94:97]
	v_mfma_f32_16x16x32_bf16 v[94:97], v[148:151], v[208:211], v[94:97]
	v_mfma_f32_16x16x32_bf16 v[90:93], v[158:161], v[208:211], v[90:93]
	v_mfma_f32_16x16x32_bf16 v[90:93], v[154:157], v[204:207], v[90:93]
	v_mfma_f32_16x16x32_bf16 v[86:89], v[162:165], v[204:207], v[86:89]
	v_mfma_f32_16x16x32_bf16 v[86:89], v[166:169], v[208:211], v[86:89]
	v_mfma_f32_16x16x32_bf16 v[82:85], v[174:177], v[208:211], v[82:85]
	v_mfma_f32_16x16x32_bf16 v[82:85], v[170:173], v[204:207], v[82:85]
	v_mfma_f32_16x16x32_bf16 v[66:69], v[170:173], v[212:215], v[66:69]
	v_mfma_f32_16x16x32_bf16 v[66:69], v[174:177], v[216:219], v[66:69]
	v_mfma_f32_16x16x32_bf16 v[70:73], v[166:169], v[216:219], v[70:73]
	v_mfma_f32_16x16x32_bf16 v[70:73], v[162:165], v[212:215], v[70:73]
	v_mfma_f32_16x16x32_bf16 v[74:77], v[154:157], v[212:215], v[74:77]
	v_mfma_f32_16x16x32_bf16 v[74:77], v[158:161], v[216:219], v[74:77]
	v_mfma_f32_16x16x32_bf16 v[78:81], v[148:151], v[216:219], v[78:81]
	v_mfma_f32_16x16x32_bf16 v[78:81], v[144:147], v[212:215], v[78:81]
	s_barrier
	s_add_i32 s0, s0, s28
	s_mov_b32 m0, s0
	ds_read_b128 v[178:181], v152 offset:16384
	ds_read_b128 v[182:185], v152 offset:17408
	ds_read_b128 v[186:189], v152 offset:18432
	ds_read_b128 v[190:193], v152 offset:19456
	ds_read_b128 v[204:207], v152 offset:20480
	ds_read_b128 v[208:211], v152 offset:21504
	ds_read_b128 v[212:215], v152 offset:22528
	ds_read_b128 v[216:219], v152 offset:23552
	global_load_lds_dwordx4 v194, s[64:65] sc1
	s_add_i32 m0, s0, 0x2000
	s_add_u32 s0, s64, 0x80000
	s_addc_u32 s1, s65, 0
	s_add_i32 s18, s18, s28
	global_load_lds_dwordx4 v130, s[64:65] sc1
	s_mov_b32 m0, s18
	s_nop 0
	global_load_lds_dwordx4 v194, s[0:1] sc1
	s_add_i32 m0, s18, 0x2000
	s_nop 0
	global_load_lds_dwordx4 v130, s[0:1] sc1
	s_mov_b32 m0, s29
	s_nop 0
	global_load_lds_dwordx4 v194, s[70:71] sc1
	s_mov_b32 m0, s31
	s_nop 0
	global_load_lds_dwordx4 v130, s[70:71] sc1
	s_waitcnt vmcnt(8)
	s_waitcnt lgkmcnt(0)
	s_barrier
	s_waitcnt lgkmcnt(0)
	v_mfma_f32_16x16x32_bf16 v[62:65], v[144:147], v[178:181], v[62:65]
	v_mfma_f32_16x16x32_bf16 v[62:65], v[148:151], v[182:185], v[62:65]
	v_mfma_f32_16x16x32_bf16 v[58:61], v[158:161], v[182:185], v[58:61]
	v_mfma_f32_16x16x32_bf16 v[58:61], v[154:157], v[178:181], v[58:61]
	v_mfma_f32_16x16x32_bf16 v[54:57], v[162:165], v[178:181], v[54:57]
	v_mfma_f32_16x16x32_bf16 v[54:57], v[166:169], v[182:185], v[54:57]
	v_mfma_f32_16x16x32_bf16 v[50:53], v[174:177], v[182:185], v[50:53]
	v_mfma_f32_16x16x32_bf16 v[50:53], v[170:173], v[178:181], v[50:53]
	v_mfma_f32_16x16x32_bf16 v[34:37], v[170:173], v[186:189], v[34:37]
	v_mfma_f32_16x16x32_bf16 v[34:37], v[174:177], v[190:193], v[34:37]
	v_mfma_f32_16x16x32_bf16 v[38:41], v[166:169], v[190:193], v[38:41]
	v_mfma_f32_16x16x32_bf16 v[38:41], v[162:165], v[186:189], v[38:41]
	v_mfma_f32_16x16x32_bf16 v[42:45], v[154:157], v[186:189], v[42:45]
	v_mfma_f32_16x16x32_bf16 v[42:45], v[158:161], v[190:193], v[42:45]
	v_mfma_f32_16x16x32_bf16 v[46:49], v[148:151], v[190:193], v[46:49]
	v_mfma_f32_16x16x32_bf16 v[46:49], v[144:147], v[186:189], v[46:49]
	v_mfma_f32_16x16x32_bf16 v[30:33], v[144:147], v[204:207], v[30:33]
	v_mfma_f32_16x16x32_bf16 v[30:33], v[148:151], v[208:211], v[30:33]
	v_mfma_f32_16x16x32_bf16 v[26:29], v[158:161], v[208:211], v[26:29]
	v_mfma_f32_16x16x32_bf16 v[26:29], v[154:157], v[204:207], v[26:29]
	v_mfma_f32_16x16x32_bf16 v[22:25], v[162:165], v[204:207], v[22:25]
	v_mfma_f32_16x16x32_bf16 v[22:25], v[166:169], v[208:211], v[22:25]
	v_mfma_f32_16x16x32_bf16 v[18:21], v[174:177], v[208:211], v[18:21]
	v_mfma_f32_16x16x32_bf16 v[18:21], v[170:173], v[204:207], v[18:21]
	v_mfma_f32_16x16x32_bf16 v[2:5], v[170:173], v[212:215], v[2:5]
	v_mfma_f32_16x16x32_bf16 v[2:5], v[174:177], v[216:219], v[2:5]
	v_mfma_f32_16x16x32_bf16 v[6:9], v[166:169], v[216:219], v[6:9]
	v_mfma_f32_16x16x32_bf16 v[6:9], v[162:165], v[212:215], v[6:9]
	v_mfma_f32_16x16x32_bf16 v[10:13], v[154:157], v[212:215], v[10:13]
	v_mfma_f32_16x16x32_bf16 v[10:13], v[158:161], v[216:219], v[10:13]
	v_mfma_f32_16x16x32_bf16 v[14:17], v[148:151], v[216:219], v[14:17]
	v_mfma_f32_16x16x32_bf16 v[14:17], v[144:147], v[212:215], v[14:17]
	s_barrier
	s_add_i32 s18, 0, 0x18000
	v_add_u32_e32 v153, s18, v1
	s_add_i32 s19, 0, 0x1c000
	ds_read_b128 v[144:147], v153
	ds_read_b128 v[148:151], v153 offset:1024
	ds_read_b128 v[154:157], v153 offset:2048
	ds_read_b128 v[158:161], v153 offset:3072
	v_add_u32_e32 v153, s19, v1
	ds_read_b128 v[162:165], v153
	ds_read_b128 v[166:169], v153 offset:1024
	ds_read_b128 v[170:173], v153 offset:2048
	ds_read_b128 v[174:177], v153 offset:3072
	s_add_u32 s0, s70, 0x80000
	s_addc_u32 s1, s71, 0
	s_mov_b32 m0, s33
	ds_read_b128 v[178:181], v152 offset:32768
	ds_read_b128 v[182:185], v152 offset:33792
	ds_read_b128 v[186:189], v152 offset:34816
	ds_read_b128 v[190:193], v152 offset:35840
	ds_read_b128 v[204:207], v152 offset:36864
	ds_read_b128 v[208:211], v152 offset:37888
	ds_read_b128 v[212:215], v152 offset:38912
	ds_read_b128 v[216:219], v152 offset:39936
	global_load_lds_dwordx4 v194, s[0:1] sc1
	s_mov_b32 m0, s40
	s_nop 0
	global_load_lds_dwordx4 v130, s[0:1] sc1
	s_waitcnt vmcnt(8)
	s_waitcnt lgkmcnt(0)
	s_barrier
	s_waitcnt lgkmcnt(0)
	v_mfma_f32_16x16x32_bf16 v[126:129], v[144:147], v[178:181], v[126:129]
	v_mfma_f32_16x16x32_bf16 v[126:129], v[148:151], v[182:185], v[126:129]
	v_mfma_f32_16x16x32_bf16 v[122:125], v[158:161], v[182:185], v[122:125]
	v_mfma_f32_16x16x32_bf16 v[122:125], v[154:157], v[178:181], v[122:125]
	v_mfma_f32_16x16x32_bf16 v[118:121], v[162:165], v[178:181], v[118:121]
	v_mfma_f32_16x16x32_bf16 v[118:121], v[166:169], v[182:185], v[118:121]
	v_mfma_f32_16x16x32_bf16 v[114:117], v[174:177], v[182:185], v[114:117]
	v_mfma_f32_16x16x32_bf16 v[114:117], v[170:173], v[178:181], v[114:117]
	v_mfma_f32_16x16x32_bf16 v[98:101], v[170:173], v[186:189], v[98:101]
	v_mfma_f32_16x16x32_bf16 v[98:101], v[174:177], v[190:193], v[98:101]
	v_mfma_f32_16x16x32_bf16 v[102:105], v[166:169], v[190:193], v[102:105]
	v_mfma_f32_16x16x32_bf16 v[102:105], v[162:165], v[186:189], v[102:105]
	v_mfma_f32_16x16x32_bf16 v[106:109], v[154:157], v[186:189], v[106:109]
	v_mfma_f32_16x16x32_bf16 v[106:109], v[158:161], v[190:193], v[106:109]
	v_mfma_f32_16x16x32_bf16 v[110:113], v[148:151], v[190:193], v[110:113]
	v_mfma_f32_16x16x32_bf16 v[110:113], v[144:147], v[186:189], v[110:113]
	v_mfma_f32_16x16x32_bf16 v[94:97], v[144:147], v[204:207], v[94:97]
	v_mfma_f32_16x16x32_bf16 v[94:97], v[148:151], v[208:211], v[94:97]
	v_mfma_f32_16x16x32_bf16 v[90:93], v[158:161], v[208:211], v[90:93]
	v_mfma_f32_16x16x32_bf16 v[90:93], v[154:157], v[204:207], v[90:93]
	v_mfma_f32_16x16x32_bf16 v[86:89], v[162:165], v[204:207], v[86:89]
	v_mfma_f32_16x16x32_bf16 v[86:89], v[166:169], v[208:211], v[86:89]
	v_mfma_f32_16x16x32_bf16 v[82:85], v[174:177], v[208:211], v[82:85]
	v_mfma_f32_16x16x32_bf16 v[82:85], v[170:173], v[204:207], v[82:85]
	v_mfma_f32_16x16x32_bf16 v[66:69], v[170:173], v[212:215], v[66:69]
	v_mfma_f32_16x16x32_bf16 v[66:69], v[174:177], v[216:219], v[66:69]
	v_mfma_f32_16x16x32_bf16 v[70:73], v[166:169], v[216:219], v[70:73]
	v_mfma_f32_16x16x32_bf16 v[70:73], v[162:165], v[212:215], v[70:73]
	v_mfma_f32_16x16x32_bf16 v[74:77], v[154:157], v[212:215], v[74:77]
	v_mfma_f32_16x16x32_bf16 v[74:77], v[158:161], v[216:219], v[74:77]
	v_mfma_f32_16x16x32_bf16 v[78:81], v[148:151], v[216:219], v[78:81]
	v_mfma_f32_16x16x32_bf16 v[78:81], v[144:147], v[212:215], v[78:81]
	s_barrier
	s_add_u32 s98, s64, 0x80
	s_addc_u32 s99, s65, 0
	s_add_u32 s100, s70, 0x80
	s_addc_u32 s101, s71, 0
	s_add_i32 s0, s18, s28
	s_mov_b32 m0, s0
	ds_read_b128 v[178:181], v152 offset:49152
	ds_read_b128 v[182:185], v152 offset:50176
	ds_read_b128 v[186:189], v152 offset:51200
	ds_read_b128 v[190:193], v152 offset:52224
	ds_read_b128 v[204:207], v152 offset:53248
	ds_read_b128 v[208:211], v152 offset:54272
	ds_read_b128 v[212:215], v152 offset:55296
	ds_read_b128 v[216:219], v152 offset:56320
	global_load_lds_dwordx4 v194, s[98:99] sc1
	s_add_i32 m0, s0, 0x2000
	s_add_u32 s0, s64, 0x80080
	s_addc_u32 s1, s65, 0
	s_add_i32 s18, s19, s28
	global_load_lds_dwordx4 v130, s[98:99] sc1
	s_mov_b32 m0, s18
	s_nop 0
	global_load_lds_dwordx4 v194, s[0:1] sc1
	s_add_i32 m0, s18, 0x2000
	s_nop 0
	global_load_lds_dwordx4 v130, s[0:1] sc1
	s_mov_b32 m0, s54
	s_nop 0
	global_load_lds_dwordx4 v194, s[100:101] sc1
	s_mov_b32 m0, s57
	s_nop 0
	global_load_lds_dwordx4 v130, s[100:101] sc1
	s_waitcnt vmcnt(8)
	s_waitcnt lgkmcnt(0)
	s_barrier
	s_waitcnt lgkmcnt(0)
	v_mfma_f32_16x16x32_bf16 v[62:65], v[144:147], v[178:181], v[62:65]
	v_mfma_f32_16x16x32_bf16 v[62:65], v[148:151], v[182:185], v[62:65]
	v_mfma_f32_16x16x32_bf16 v[58:61], v[158:161], v[182:185], v[58:61]
	v_mfma_f32_16x16x32_bf16 v[58:61], v[154:157], v[178:181], v[58:61]
	v_mfma_f32_16x16x32_bf16 v[54:57], v[162:165], v[178:181], v[54:57]
	v_mfma_f32_16x16x32_bf16 v[54:57], v[166:169], v[182:185], v[54:57]
	v_mfma_f32_16x16x32_bf16 v[50:53], v[174:177], v[182:185], v[50:53]
	v_mfma_f32_16x16x32_bf16 v[50:53], v[170:173], v[178:181], v[50:53]
	v_mfma_f32_16x16x32_bf16 v[34:37], v[170:173], v[186:189], v[34:37]
	v_mfma_f32_16x16x32_bf16 v[34:37], v[174:177], v[190:193], v[34:37]
	v_mfma_f32_16x16x32_bf16 v[38:41], v[166:169], v[190:193], v[38:41]
	v_mfma_f32_16x16x32_bf16 v[38:41], v[162:165], v[186:189], v[38:41]
	v_mfma_f32_16x16x32_bf16 v[42:45], v[154:157], v[186:189], v[42:45]
	v_mfma_f32_16x16x32_bf16 v[42:45], v[158:161], v[190:193], v[42:45]
	v_mfma_f32_16x16x32_bf16 v[46:49], v[148:151], v[190:193], v[46:49]
	v_mfma_f32_16x16x32_bf16 v[46:49], v[144:147], v[186:189], v[46:49]
	v_mfma_f32_16x16x32_bf16 v[30:33], v[144:147], v[204:207], v[30:33]
	v_mfma_f32_16x16x32_bf16 v[30:33], v[148:151], v[208:211], v[30:33]
	v_mfma_f32_16x16x32_bf16 v[26:29], v[158:161], v[208:211], v[26:29]
	v_mfma_f32_16x16x32_bf16 v[26:29], v[154:157], v[204:207], v[26:29]
	v_mfma_f32_16x16x32_bf16 v[22:25], v[162:165], v[204:207], v[22:25]
	v_mfma_f32_16x16x32_bf16 v[22:25], v[166:169], v[208:211], v[22:25]
	v_mfma_f32_16x16x32_bf16 v[18:21], v[174:177], v[208:211], v[18:21]
	v_mfma_f32_16x16x32_bf16 v[18:21], v[170:173], v[204:207], v[18:21]
	v_mfma_f32_16x16x32_bf16 v[2:5], v[170:173], v[212:215], v[2:5]
	v_mfma_f32_16x16x32_bf16 v[2:5], v[174:177], v[216:219], v[2:5]
	v_mfma_f32_16x16x32_bf16 v[6:9], v[166:169], v[216:219], v[6:9]
	v_mfma_f32_16x16x32_bf16 v[6:9], v[162:165], v[212:215], v[6:9]
	v_mfma_f32_16x16x32_bf16 v[10:13], v[154:157], v[212:215], v[10:13]
	v_mfma_f32_16x16x32_bf16 v[10:13], v[158:161], v[216:219], v[10:13]
	v_mfma_f32_16x16x32_bf16 v[14:17], v[148:151], v[216:219], v[14:17]
	v_mfma_f32_16x16x32_bf16 v[14:17], v[144:147], v[212:215], v[14:17]
	s_barrier
	s_add_i32 s76, s76, 2
	s_add_u32 s62, s62, 0x100
	s_addc_u32 s63, s63, 0
	s_add_u32 s53, s53, 0x100
	s_addc_u32 s58, s58, 0
	s_cmp_gt_u32 s76, 29
	s_cbranch_scc1 .LBB0_584

.Lpeel_disp_gu:
	s_cmp_lg_u32 s76, -2
	s_cbranch_scc1 .LBB0_581
	s_add_u32 s18, s62, 0xfff80080
	s_addc_u32 s19, s63, -1
	s_and_b64 s[0:1], s[64:65], exec
	s_cselect_b32 s71, s22, s19
	s_cselect_b32 s70, s23, s18
	s_cselect_b32 s65, s39, s58
	s_cselect_b32 s64, s47, s53
	s_add_i32 s0, 0, 0x10000
	v_add_u32_e32 v153, s0, v1
	s_add_i32 s18, 0, 0x14000
	ds_read_b128 v[144:147], v153
	ds_read_b128 v[148:151], v153 offset:1024
	ds_read_b128 v[154:157], v153 offset:2048
	ds_read_b128 v[158:161], v153 offset:3072
	v_add_u32_e32 v153, s18, v1
	ds_read_b128 v[162:165], v153
	ds_read_b128 v[166:169], v153 offset:1024
	ds_read_b128 v[170:173], v153 offset:2048
	ds_read_b128 v[174:177], v153 offset:3072
	s_add_i32 m0, s29, 0xc000
	ds_read_b128 v[178:181], v152
	ds_read_b128 v[182:185], v152 offset:1024
	ds_read_b128 v[186:189], v152 offset:2048
	ds_read_b128 v[190:193], v152 offset:3072
	ds_read_b128 v[204:207], v152 offset:4096
	ds_read_b128 v[208:211], v152 offset:5120
	ds_read_b128 v[212:215], v152 offset:6144
	ds_read_b128 v[216:219], v152 offset:7168
	global_load_lds_dwordx4 v136, s[62:63] sc1
	s_add_i32 m0, s29, 0xe000
	s_nop 0
	global_load_lds_dwordx4 v138, s[62:63] sc1
	s_waitcnt vmcnt(8)
	s_waitcnt lgkmcnt(0)
	s_barrier
	s_waitcnt lgkmcnt(0)
	v_mfma_f32_16x16x32_bf16 v[126:129], v[144:147], v[178:181], 0
	v_mfma_f32_16x16x32_bf16 v[126:129], v[148:151], v[182:185], v[126:129]
	v_mfma_f32_16x16x32_bf16 v[122:125], v[158:161], v[182:185], 0
	v_mfma_f32_16x16x32_bf16 v[122:125], v[154:157], v[178:181], v[122:125]
	v_mfma_f32_16x16x32_bf16 v[118:121], v[162:165], v[178:181], 0
	v_mfma_f32_16x16x32_bf16 v[118:121], v[166:169], v[182:185], v[118:121]
	v_mfma_f32_16x16x32_bf16 v[114:117], v[174:177], v[182:185], 0
	v_mfma_f32_16x16x32_bf16 v[114:117], v[170:173], v[178:181], v[114:117]
	v_mfma_f32_16x16x32_bf16 v[98:101], v[170:173], v[186:189], 0
	v_mfma_f32_16x16x32_bf16 v[98:101], v[174:177], v[190:193], v[98:101]
	v_mfma_f32_16x16x32_bf16 v[102:105], v[166:169], v[190:193], 0
	v_mfma_f32_16x16x32_bf16 v[102:105], v[162:165], v[186:189], v[102:105]
	v_mfma_f32_16x16x32_bf16 v[106:109], v[154:157], v[186:189], 0
	v_mfma_f32_16x16x32_bf16 v[106:109], v[158:161], v[190:193], v[106:109]
	v_mfma_f32_16x16x32_bf16 v[110:113], v[148:151], v[190:193], 0
	v_mfma_f32_16x16x32_bf16 v[110:113], v[144:147], v[186:189], v[110:113]
	v_mfma_f32_16x16x32_bf16 v[94:97], v[144:147], v[204:207], 0
	v_mfma_f32_16x16x32_bf16 v[94:97], v[148:151], v[208:211], v[94:97]
	v_mfma_f32_16x16x32_bf16 v[90:93], v[158:161], v[208:211], 0
	v_mfma_f32_16x16x32_bf16 v[90:93], v[154:157], v[204:207], v[90:93]
	v_mfma_f32_16x16x32_bf16 v[86:89], v[162:165], v[204:207], 0
	v_mfma_f32_16x16x32_bf16 v[86:89], v[166:169], v[208:211], v[86:89]
	v_mfma_f32_16x16x32_bf16 v[82:85], v[174:177], v[208:211], 0
	v_mfma_f32_16x16x32_bf16 v[82:85], v[170:173], v[204:207], v[82:85]
	v_mfma_f32_16x16x32_bf16 v[66:69], v[170:173], v[212:215], 0
	v_mfma_f32_16x16x32_bf16 v[66:69], v[174:177], v[216:219], v[66:69]
	v_mfma_f32_16x16x32_bf16 v[70:73], v[166:169], v[216:219], 0
	v_mfma_f32_16x16x32_bf16 v[70:73], v[162:165], v[212:215], v[70:73]
	v_mfma_f32_16x16x32_bf16 v[74:77], v[154:157], v[212:215], 0
	v_mfma_f32_16x16x32_bf16 v[74:77], v[158:161], v[216:219], v[74:77]
	v_mfma_f32_16x16x32_bf16 v[78:81], v[148:151], v[216:219], 0
	v_mfma_f32_16x16x32_bf16 v[78:81], v[144:147], v[212:215], v[78:81]
	s_barrier
	s_add_i32 s0, s0, s28
	s_mov_b32 m0, s0
	ds_read_b128 v[178:181], v152 offset:16384
	ds_read_b128 v[182:185], v152 offset:17408
	ds_read_b128 v[186:189], v152 offset:18432
	ds_read_b128 v[190:193], v152 offset:19456
	ds_read_b128 v[204:207], v152 offset:20480
	ds_read_b128 v[208:211], v152 offset:21504
	ds_read_b128 v[212:215], v152 offset:22528
	ds_read_b128 v[216:219], v152 offset:23552
	global_load_lds_dwordx4 v194, s[64:65] sc1
	s_add_i32 m0, s0, 0x2000
	s_add_u32 s0, s64, 0x80000
	s_addc_u32 s1, s65, 0
	s_add_i32 s18, s18, s28
	global_load_lds_dwordx4 v130, s[64:65] sc1
	s_mov_b32 m0, s18
	s_nop 0
	global_load_lds_dwordx4 v194, s[0:1] sc1
	s_add_i32 m0, s18, 0x2000
	s_nop 0
	global_load_lds_dwordx4 v130, s[0:1] sc1
	s_mov_b32 m0, s29
	s_nop 0
	global_load_lds_dwordx4 v194, s[70:71] sc1
	s_mov_b32 m0, s31
	s_nop 0
	global_load_lds_dwordx4 v130, s[70:71] sc1
	s_waitcnt vmcnt(8)
	s_waitcnt lgkmcnt(0)
	s_barrier
	s_waitcnt lgkmcnt(0)
	v_mfma_f32_16x16x32_bf16 v[62:65], v[144:147], v[178:181], 0
	v_mfma_f32_16x16x32_bf16 v[62:65], v[148:151], v[182:185], v[62:65]
	v_mfma_f32_16x16x32_bf16 v[58:61], v[158:161], v[182:185], 0
	v_mfma_f32_16x16x32_bf16 v[58:61], v[154:157], v[178:181], v[58:61]
	v_mfma_f32_16x16x32_bf16 v[54:57], v[162:165], v[178:181], 0
	v_mfma_f32_16x16x32_bf16 v[54:57], v[166:169], v[182:185], v[54:57]
	v_mfma_f32_16x16x32_bf16 v[50:53], v[174:177], v[182:185], 0
	v_mfma_f32_16x16x32_bf16 v[50:53], v[170:173], v[178:181], v[50:53]
	v_mfma_f32_16x16x32_bf16 v[34:37], v[170:173], v[186:189], 0
	v_mfma_f32_16x16x32_bf16 v[34:37], v[174:177], v[190:193], v[34:37]
	v_mfma_f32_16x16x32_bf16 v[38:41], v[166:169], v[190:193], 0
	v_mfma_f32_16x16x32_bf16 v[38:41], v[162:165], v[186:189], v[38:41]
	v_mfma_f32_16x16x32_bf16 v[42:45], v[154:157], v[186:189], 0
	v_mfma_f32_16x16x32_bf16 v[42:45], v[158:161], v[190:193], v[42:45]
	v_mfma_f32_16x16x32_bf16 v[46:49], v[148:151], v[190:193], 0
	v_mfma_f32_16x16x32_bf16 v[46:49], v[144:147], v[186:189], v[46:49]
	v_mfma_f32_16x16x32_bf16 v[30:33], v[144:147], v[204:207], 0
	v_mfma_f32_16x16x32_bf16 v[30:33], v[148:151], v[208:211], v[30:33]
	v_mfma_f32_16x16x32_bf16 v[26:29], v[158:161], v[208:211], 0
	v_mfma_f32_16x16x32_bf16 v[26:29], v[154:157], v[204:207], v[26:29]
	v_mfma_f32_16x16x32_bf16 v[22:25], v[162:165], v[204:207], 0
	v_mfma_f32_16x16x32_bf16 v[22:25], v[166:169], v[208:211], v[22:25]
	v_mfma_f32_16x16x32_bf16 v[18:21], v[174:177], v[208:211], 0
	v_mfma_f32_16x16x32_bf16 v[18:21], v[170:173], v[204:207], v[18:21]
	v_mfma_f32_16x16x32_bf16 v[2:5], v[170:173], v[212:215], 0
	v_mfma_f32_16x16x32_bf16 v[2:5], v[174:177], v[216:219], v[2:5]
	v_mfma_f32_16x16x32_bf16 v[6:9], v[166:169], v[216:219], 0
	v_mfma_f32_16x16x32_bf16 v[6:9], v[162:165], v[212:215], v[6:9]
	v_mfma_f32_16x16x32_bf16 v[10:13], v[154:157], v[212:215], 0
	v_mfma_f32_16x16x32_bf16 v[10:13], v[158:161], v[216:219], v[10:13]
	v_mfma_f32_16x16x32_bf16 v[14:17], v[148:151], v[216:219], 0
	v_mfma_f32_16x16x32_bf16 v[14:17], v[144:147], v[212:215], v[14:17]
	s_barrier
	s_add_i32 s18, 0, 0x18000
	v_add_u32_e32 v153, s18, v1
	s_add_i32 s19, 0, 0x1c000
	ds_read_b128 v[144:147], v153
	ds_read_b128 v[148:151], v153 offset:1024
	ds_read_b128 v[154:157], v153 offset:2048
	ds_read_b128 v[158:161], v153 offset:3072
	v_add_u32_e32 v153, s19, v1
	ds_read_b128 v[162:165], v153
	ds_read_b128 v[166:169], v153 offset:1024
	ds_read_b128 v[170:173], v153 offset:2048
	ds_read_b128 v[174:177], v153 offset:3072
	s_add_u32 s0, s70, 0x80000
	s_addc_u32 s1, s71, 0
	s_mov_b32 m0, s33
	ds_read_b128 v[178:181], v152 offset:32768
	ds_read_b128 v[182:185], v152 offset:33792
	ds_read_b128 v[186:189], v152 offset:34816
	ds_read_b128 v[190:193], v152 offset:35840
	ds_read_b128 v[204:207], v152 offset:36864
	ds_read_b128 v[208:211], v152 offset:37888
	ds_read_b128 v[212:215], v152 offset:38912
	ds_read_b128 v[216:219], v152 offset:39936
	global_load_lds_dwordx4 v194, s[0:1] sc1
	s_mov_b32 m0, s40
	s_nop 0
	global_load_lds_dwordx4 v130, s[0:1] sc1
	s_waitcnt vmcnt(8)
	s_waitcnt lgkmcnt(0)
	s_barrier
	s_waitcnt lgkmcnt(0)
	v_mfma_f32_16x16x32_bf16 v[126:129], v[144:147], v[178:181], v[126:129]
	v_mfma_f32_16x16x32_bf16 v[126:129], v[148:151], v[182:185], v[126:129]
	v_mfma_f32_16x16x32_bf16 v[122:125], v[158:161], v[182:185], v[122:125]
	v_mfma_f32_16x16x32_bf16 v[122:125], v[154:157], v[178:181], v[122:125]
	v_mfma_f32_16x16x32_bf16 v[118:121], v[162:165], v[178:181], v[118:121]
	v_mfma_f32_16x16x32_bf16 v[118:121], v[166:169], v[182:185], v[118:121]
	v_mfma_f32_16x16x32_bf16 v[114:117], v[174:177], v[182:185], v[114:117]
	v_mfma_f32_16x16x32_bf16 v[114:117], v[170:173], v[178:181], v[114:117]
	v_mfma_f32_16x16x32_bf16 v[98:101], v[170:173], v[186:189], v[98:101]
	v_mfma_f32_16x16x32_bf16 v[98:101], v[174:177], v[190:193], v[98:101]
	v_mfma_f32_16x16x32_bf16 v[102:105], v[166:169], v[190:193], v[102:105]
	v_mfma_f32_16x16x32_bf16 v[102:105], v[162:165], v[186:189], v[102:105]
	v_mfma_f32_16x16x32_bf16 v[106:109], v[154:157], v[186:189], v[106:109]
	v_mfma_f32_16x16x32_bf16 v[106:109], v[158:161], v[190:193], v[106:109]
	v_mfma_f32_16x16x32_bf16 v[110:113], v[148:151], v[190:193], v[110:113]
	v_mfma_f32_16x16x32_bf16 v[110:113], v[144:147], v[186:189], v[110:113]
	v_mfma_f32_16x16x32_bf16 v[94:97], v[144:147], v[204:207], v[94:97]
	v_mfma_f32_16x16x32_bf16 v[94:97], v[148:151], v[208:211], v[94:97]
	v_mfma_f32_16x16x32_bf16 v[90:93], v[158:161], v[208:211], v[90:93]
	v_mfma_f32_16x16x32_bf16 v[90:93], v[154:157], v[204:207], v[90:93]
	v_mfma_f32_16x16x32_bf16 v[86:89], v[162:165], v[204:207], v[86:89]
	v_mfma_f32_16x16x32_bf16 v[86:89], v[166:169], v[208:211], v[86:89]
	v_mfma_f32_16x16x32_bf16 v[82:85], v[174:177], v[208:211], v[82:85]
	v_mfma_f32_16x16x32_bf16 v[82:85], v[170:173], v[204:207], v[82:85]
	v_mfma_f32_16x16x32_bf16 v[66:69], v[170:173], v[212:215], v[66:69]
	v_mfma_f32_16x16x32_bf16 v[66:69], v[174:177], v[216:219], v[66:69]
	v_mfma_f32_16x16x32_bf16 v[70:73], v[166:169], v[216:219], v[70:73]
	v_mfma_f32_16x16x32_bf16 v[70:73], v[162:165], v[212:215], v[70:73]
	v_mfma_f32_16x16x32_bf16 v[74:77], v[154:157], v[212:215], v[74:77]
	v_mfma_f32_16x16x32_bf16 v[74:77], v[158:161], v[216:219], v[74:77]
	v_mfma_f32_16x16x32_bf16 v[78:81], v[148:151], v[216:219], v[78:81]
	v_mfma_f32_16x16x32_bf16 v[78:81], v[144:147], v[212:215], v[78:81]
	s_barrier
	s_add_u32 s98, s64, 0x80
	s_addc_u32 s99, s65, 0
	s_add_u32 s100, s70, 0x80
	s_addc_u32 s101, s71, 0
	s_add_i32 s0, s18, s28
	s_mov_b32 m0, s0
	ds_read_b128 v[178:181], v152 offset:49152
	ds_read_b128 v[182:185], v152 offset:50176
	ds_read_b128 v[186:189], v152 offset:51200
	ds_read_b128 v[190:193], v152 offset:52224
	ds_read_b128 v[204:207], v152 offset:53248
	ds_read_b128 v[208:211], v152 offset:54272
	ds_read_b128 v[212:215], v152 offset:55296
	ds_read_b128 v[216:219], v152 offset:56320
	global_load_lds_dwordx4 v194, s[98:99] sc1
	s_add_i32 m0, s0, 0x2000
	s_add_u32 s0, s64, 0x80080
	s_addc_u32 s1, s65, 0
	s_add_i32 s18, s19, s28
	global_load_lds_dwordx4 v130, s[98:99] sc1
	s_mov_b32 m0, s18
	s_nop 0
	global_load_lds_dwordx4 v194, s[0:1] sc1
	s_add_i32 m0, s18, 0x2000
	s_nop 0
	global_load_lds_dwordx4 v130, s[0:1] sc1
	s_mov_b32 m0, s54
	s_nop 0
	global_load_lds_dwordx4 v194, s[100:101] sc1
	s_mov_b32 m0, s57
	s_nop 0
	global_load_lds_dwordx4 v130, s[100:101] sc1
	s_waitcnt vmcnt(8)
	s_waitcnt lgkmcnt(0)
	s_barrier
	s_waitcnt lgkmcnt(0)
	v_mfma_f32_16x16x32_bf16 v[62:65], v[144:147], v[178:181], v[62:65]
	v_mfma_f32_16x16x32_bf16 v[62:65], v[148:151], v[182:185], v[62:65]
	v_mfma_f32_16x16x32_bf16 v[58:61], v[158:161], v[182:185], v[58:61]
	v_mfma_f32_16x16x32_bf16 v[58:61], v[154:157], v[178:181], v[58:61]
	v_mfma_f32_16x16x32_bf16 v[54:57], v[162:165], v[178:181], v[54:57]
	v_mfma_f32_16x16x32_bf16 v[54:57], v[166:169], v[182:185], v[54:57]
	v_mfma_f32_16x16x32_bf16 v[50:53], v[174:177], v[182:185], v[50:53]
	v_mfma_f32_16x16x32_bf16 v[50:53], v[170:173], v[178:181], v[50:53]
	v_mfma_f32_16x16x32_bf16 v[34:37], v[170:173], v[186:189], v[34:37]
	v_mfma_f32_16x16x32_bf16 v[34:37], v[174:177], v[190:193], v[34:37]
	v_mfma_f32_16x16x32_bf16 v[38:41], v[166:169], v[190:193], v[38:41]
	v_mfma_f32_16x16x32_bf16 v[38:41], v[162:165], v[186:189], v[38:41]
	v_mfma_f32_16x16x32_bf16 v[42:45], v[154:157], v[186:189], v[42:45]
	v_mfma_f32_16x16x32_bf16 v[42:45], v[158:161], v[190:193], v[42:45]
	v_mfma_f32_16x16x32_bf16 v[46:49], v[148:151], v[190:193], v[46:49]
	v_mfma_f32_16x16x32_bf16 v[46:49], v[144:147], v[186:189], v[46:49]
	v_mfma_f32_16x16x32_bf16 v[30:33], v[144:147], v[204:207], v[30:33]
	v_mfma_f32_16x16x32_bf16 v[30:33], v[148:151], v[208:211], v[30:33]
	v_mfma_f32_16x16x32_bf16 v[26:29], v[158:161], v[208:211], v[26:29]
	v_mfma_f32_16x16x32_bf16 v[26:29], v[154:157], v[204:207], v[26:29]
	v_mfma_f32_16x16x32_bf16 v[22:25], v[162:165], v[204:207], v[22:25]
	v_mfma_f32_16x16x32_bf16 v[22:25], v[166:169], v[208:211], v[22:25]
	v_mfma_f32_16x16x32_bf16 v[18:21], v[174:177], v[208:211], v[18:21]
	v_mfma_f32_16x16x32_bf16 v[18:21], v[170:173], v[204:207], v[18:21]
	v_mfma_f32_16x16x32_bf16 v[2:5], v[170:173], v[212:215], v[2:5]
	v_mfma_f32_16x16x32_bf16 v[2:5], v[174:177], v[216:219], v[2:5]
	v_mfma_f32_16x16x32_bf16 v[6:9], v[166:169], v[216:219], v[6:9]
	v_mfma_f32_16x16x32_bf16 v[6:9], v[162:165], v[212:215], v[6:9]
	v_mfma_f32_16x16x32_bf16 v[10:13], v[154:157], v[212:215], v[10:13]
	v_mfma_f32_16x16x32_bf16 v[10:13], v[158:161], v[216:219], v[10:13]
	v_mfma_f32_16x16x32_bf16 v[14:17], v[148:151], v[216:219], v[14:17]
	v_mfma_f32_16x16x32_bf16 v[14:17], v[144:147], v[212:215], v[14:17]
	s_barrier
	s_add_i32 s76, s76, 2
	s_add_u32 s62, s62, 0x100
	s_addc_u32 s63, s63, 0
	s_add_u32 s53, s53, 0x100
	s_addc_u32 s58, s58, 0
	s_cmp_gt_u32 s76, 29
	s_cbranch_scc1 .LBB0_584
	s_branch .LBB0_582

.LBB0_645:
	s_add_u32 s64, s8, 0x100
	s_addc_u32 s65, s9, 0
	s_and_b64 s[0:1], s[70:71], exec
	s_cselect_b32 s77, s63, s65
	s_cselect_b32 s76, s62, s64
	s_cselect_b32 s71, s85, s23
	s_cselect_b32 s70, s84, s7
	s_add_i32 s0, 0, 0x10000
	s_add_i32 s18, 0, 0x14000
	v_add_u32_e32 v106, s0, v1
	v_add_u32_e32 v154, s18, v1
	ds_read_b128 v[70:73], v106
	ds_read_b128 v[82:85], v106 offset:1024
	ds_read_b128 v[94:97], v106 offset:2048
	ds_read_b128 v[106:109], v106 offset:3072
	ds_read_b128 v[118:121], v154
	ds_read_b128 v[130:133], v154 offset:1024
	ds_read_b128 v[142:145], v154 offset:2048
	ds_read_b128 v[154:157], v154 offset:3072
	s_add_i32 m0, s29, 0xc000
	ds_read_b128 v[158:161], v237
	ds_read_b128 v[170:173], v237 offset:1024
	ds_read_b128 v[174:177], v237 offset:2048
	ds_read_b128 v[178:181], v237 offset:3072
	ds_read_b128 v[182:185], v237 offset:4096
	ds_read_b128 v[186:189], v237 offset:5120
	ds_read_b128 v[210:213], v237 offset:6144
	ds_read_b128 v[214:217], v237 offset:7168
	global_load_lds_dwordx4 v206, s[8:9] sc1
	s_add_i32 m0, s29, 0xe000
	s_nop 0
	global_load_lds_dwordx4 v208, s[8:9] sc1
	s_waitcnt vmcnt(8)
	s_waitcnt lgkmcnt(0)
	s_barrier
	s_waitcnt lgkmcnt(0)
	v_mfma_f32_16x16x32_bf16 v[166:169], v[70:73], v[158:161], v[166:169]
	v_mfma_f32_16x16x32_bf16 v[166:169], v[82:85], v[170:173], v[166:169]
	v_mfma_f32_16x16x32_bf16 v[162:165], v[106:109], v[170:173], v[162:165]
	v_mfma_f32_16x16x32_bf16 v[162:165], v[94:97], v[158:161], v[162:165]
	v_mfma_f32_16x16x32_bf16 v[150:153], v[118:121], v[158:161], v[150:153]
	v_mfma_f32_16x16x32_bf16 v[150:153], v[130:133], v[170:173], v[150:153]
	v_mfma_f32_16x16x32_bf16 v[146:149], v[154:157], v[170:173], v[146:149]
	v_mfma_f32_16x16x32_bf16 v[146:149], v[142:145], v[158:161], v[146:149]
	v_mfma_f32_16x16x32_bf16 v[122:125], v[142:145], v[174:177], v[122:125]
	v_mfma_f32_16x16x32_bf16 v[122:125], v[154:157], v[178:181], v[122:125]
	v_mfma_f32_16x16x32_bf16 v[126:129], v[130:133], v[178:181], v[126:129]
	v_mfma_f32_16x16x32_bf16 v[126:129], v[118:121], v[174:177], v[126:129]
	v_mfma_f32_16x16x32_bf16 v[134:137], v[94:97], v[174:177], v[134:137]
	v_mfma_f32_16x16x32_bf16 v[134:137], v[106:109], v[178:181], v[134:137]
	v_mfma_f32_16x16x32_bf16 v[138:141], v[82:85], v[178:181], v[138:141]
	v_mfma_f32_16x16x32_bf16 v[138:141], v[70:73], v[174:177], v[138:141]
	v_mfma_f32_16x16x32_bf16 v[114:117], v[70:73], v[182:185], v[114:117]
	v_mfma_f32_16x16x32_bf16 v[114:117], v[82:85], v[186:189], v[114:117]
	v_mfma_f32_16x16x32_bf16 v[110:113], v[106:109], v[186:189], v[110:113]
	v_mfma_f32_16x16x32_bf16 v[110:113], v[94:97], v[182:185], v[110:113]
	v_mfma_f32_16x16x32_bf16 v[102:105], v[118:121], v[182:185], v[102:105]
	v_mfma_f32_16x16x32_bf16 v[102:105], v[130:133], v[186:189], v[102:105]
	v_mfma_f32_16x16x32_bf16 v[98:101], v[154:157], v[186:189], v[98:101]
	v_mfma_f32_16x16x32_bf16 v[98:101], v[142:145], v[182:185], v[98:101]
	v_mfma_f32_16x16x32_bf16 v[74:77], v[142:145], v[210:213], v[74:77]
	v_mfma_f32_16x16x32_bf16 v[74:77], v[154:157], v[214:217], v[74:77]
	v_mfma_f32_16x16x32_bf16 v[78:81], v[130:133], v[214:217], v[78:81]
	v_mfma_f32_16x16x32_bf16 v[78:81], v[118:121], v[210:213], v[78:81]
	v_mfma_f32_16x16x32_bf16 v[86:89], v[94:97], v[210:213], v[86:89]
	v_mfma_f32_16x16x32_bf16 v[86:89], v[106:109], v[214:217], v[86:89]
	v_mfma_f32_16x16x32_bf16 v[90:93], v[82:85], v[214:217], v[90:93]
	v_mfma_f32_16x16x32_bf16 v[90:93], v[70:73], v[210:213], v[90:93]
	s_barrier
	s_add_i32 s0, s0, s28
	s_mov_b32 m0, s0
	ds_read_b128 v[158:161], v237 offset:16384
	ds_read_b128 v[170:173], v237 offset:17408
	ds_read_b128 v[174:177], v237 offset:18432
	ds_read_b128 v[178:181], v237 offset:19456
	ds_read_b128 v[182:185], v237 offset:20480
	ds_read_b128 v[186:189], v237 offset:21504
	ds_read_b128 v[210:213], v237 offset:22528
	ds_read_b128 v[214:217], v237 offset:23552
	global_load_lds_dwordx4 v192, s[70:71] sc1
	s_add_i32 m0, s0, 0x2000
	s_add_u32 s0, s70, 0x160000
	s_addc_u32 s1, s71, 0
	s_add_i32 s8, s18, s28
	global_load_lds_dwordx4 v190, s[70:71] sc1
	s_mov_b32 m0, s8
	s_nop 0
	global_load_lds_dwordx4 v192, s[0:1] sc1
	s_add_i32 m0, s8, 0x2000
	s_nop 0
	global_load_lds_dwordx4 v190, s[0:1] sc1
	s_mov_b32 m0, s29
	s_nop 0
	global_load_lds_dwordx4 v192, s[76:77] sc1
	s_mov_b32 m0, s31
	s_nop 0
	global_load_lds_dwordx4 v190, s[76:77] sc1
	s_waitcnt vmcnt(8)
	s_waitcnt lgkmcnt(0)
	s_barrier
	s_waitcnt lgkmcnt(0)
	v_mfma_f32_16x16x32_bf16 v[62:65], v[70:73], v[158:161], v[62:65]
	v_mfma_f32_16x16x32_bf16 v[62:65], v[82:85], v[170:173], v[62:65]
	v_mfma_f32_16x16x32_bf16 v[58:61], v[106:109], v[170:173], v[58:61]
	v_mfma_f32_16x16x32_bf16 v[58:61], v[94:97], v[158:161], v[58:61]
	v_mfma_f32_16x16x32_bf16 v[54:57], v[118:121], v[158:161], v[54:57]
	v_mfma_f32_16x16x32_bf16 v[54:57], v[130:133], v[170:173], v[54:57]
	v_mfma_f32_16x16x32_bf16 v[50:53], v[154:157], v[170:173], v[50:53]
	v_mfma_f32_16x16x32_bf16 v[50:53], v[142:145], v[158:161], v[50:53]
	v_mfma_f32_16x16x32_bf16 v[34:37], v[142:145], v[174:177], v[34:37]
	v_mfma_f32_16x16x32_bf16 v[34:37], v[154:157], v[178:181], v[34:37]
	v_mfma_f32_16x16x32_bf16 v[38:41], v[130:133], v[178:181], v[38:41]
	v_mfma_f32_16x16x32_bf16 v[38:41], v[118:121], v[174:177], v[38:41]
	v_mfma_f32_16x16x32_bf16 v[42:45], v[94:97], v[174:177], v[42:45]
	v_mfma_f32_16x16x32_bf16 v[42:45], v[106:109], v[178:181], v[42:45]
	v_mfma_f32_16x16x32_bf16 v[46:49], v[82:85], v[178:181], v[46:49]
	v_mfma_f32_16x16x32_bf16 v[46:49], v[70:73], v[174:177], v[46:49]
	v_mfma_f32_16x16x32_bf16 v[30:33], v[70:73], v[182:185], v[30:33]
	v_mfma_f32_16x16x32_bf16 v[30:33], v[82:85], v[186:189], v[30:33]
	v_mfma_f32_16x16x32_bf16 v[26:29], v[106:109], v[186:189], v[26:29]
	v_mfma_f32_16x16x32_bf16 v[26:29], v[94:97], v[182:185], v[26:29]
	v_mfma_f32_16x16x32_bf16 v[22:25], v[118:121], v[182:185], v[22:25]
	v_mfma_f32_16x16x32_bf16 v[22:25], v[130:133], v[186:189], v[22:25]
	v_mfma_f32_16x16x32_bf16 v[18:21], v[154:157], v[186:189], v[18:21]
	v_mfma_f32_16x16x32_bf16 v[18:21], v[142:145], v[182:185], v[18:21]
	v_mfma_f32_16x16x32_bf16 v[2:5], v[142:145], v[210:213], v[2:5]
	v_mfma_f32_16x16x32_bf16 v[2:5], v[154:157], v[214:217], v[2:5]
	v_mfma_f32_16x16x32_bf16 v[6:9], v[130:133], v[214:217], v[6:9]
	v_mfma_f32_16x16x32_bf16 v[6:9], v[118:121], v[210:213], v[6:9]
	v_mfma_f32_16x16x32_bf16 v[10:13], v[94:97], v[210:213], v[10:13]
	v_mfma_f32_16x16x32_bf16 v[10:13], v[106:109], v[214:217], v[10:13]
	v_mfma_f32_16x16x32_bf16 v[14:17], v[82:85], v[214:217], v[14:17]
	v_mfma_f32_16x16x32_bf16 v[14:17], v[70:73], v[210:213], v[14:17]
	s_barrier
	s_add_i32 s8, 0, 0x18000
	s_add_i32 s9, 0, 0x1c000
	v_add_u32_e32 v106, s8, v1
	v_add_u32_e32 v154, s9, v1
	ds_read_b128 v[70:73], v106
	ds_read_b128 v[82:85], v106 offset:1024
	ds_read_b128 v[94:97], v106 offset:2048
	ds_read_b128 v[106:109], v106 offset:3072
	ds_read_b128 v[118:121], v154
	ds_read_b128 v[130:133], v154 offset:1024
	ds_read_b128 v[142:145], v154 offset:2048
	ds_read_b128 v[154:157], v154 offset:3072
	s_add_u32 s0, s76, 0x160000
	s_addc_u32 s1, s77, 0
	s_mov_b32 m0, s33
	ds_read_b128 v[158:161], v237 offset:32768
	ds_read_b128 v[170:173], v237 offset:33792
	ds_read_b128 v[174:177], v237 offset:34816
	ds_read_b128 v[178:181], v237 offset:35840
	ds_read_b128 v[182:185], v237 offset:36864
	ds_read_b128 v[186:189], v237 offset:37888
	ds_read_b128 v[210:213], v237 offset:38912
	ds_read_b128 v[214:217], v237 offset:39936
	global_load_lds_dwordx4 v192, s[0:1] sc1
	s_mov_b32 m0, s43
	s_nop 0
	global_load_lds_dwordx4 v190, s[0:1] sc1
	s_waitcnt vmcnt(8)
	s_waitcnt lgkmcnt(0)
	s_barrier
	s_waitcnt lgkmcnt(0)
	v_mfma_f32_16x16x32_bf16 v[166:169], v[70:73], v[158:161], v[166:169]
	v_mfma_f32_16x16x32_bf16 v[166:169], v[82:85], v[170:173], v[166:169]
	v_mfma_f32_16x16x32_bf16 v[162:165], v[106:109], v[170:173], v[162:165]
	v_mfma_f32_16x16x32_bf16 v[162:165], v[94:97], v[158:161], v[162:165]
	v_mfma_f32_16x16x32_bf16 v[150:153], v[118:121], v[158:161], v[150:153]
	v_mfma_f32_16x16x32_bf16 v[150:153], v[130:133], v[170:173], v[150:153]
	v_mfma_f32_16x16x32_bf16 v[146:149], v[154:157], v[170:173], v[146:149]
	v_mfma_f32_16x16x32_bf16 v[146:149], v[142:145], v[158:161], v[146:149]
	v_mfma_f32_16x16x32_bf16 v[122:125], v[142:145], v[174:177], v[122:125]
	v_mfma_f32_16x16x32_bf16 v[122:125], v[154:157], v[178:181], v[122:125]
	v_mfma_f32_16x16x32_bf16 v[126:129], v[130:133], v[178:181], v[126:129]
	v_mfma_f32_16x16x32_bf16 v[126:129], v[118:121], v[174:177], v[126:129]
	v_mfma_f32_16x16x32_bf16 v[134:137], v[94:97], v[174:177], v[134:137]
	v_mfma_f32_16x16x32_bf16 v[134:137], v[106:109], v[178:181], v[134:137]
	v_mfma_f32_16x16x32_bf16 v[138:141], v[82:85], v[178:181], v[138:141]
	v_mfma_f32_16x16x32_bf16 v[138:141], v[70:73], v[174:177], v[138:141]
	v_mfma_f32_16x16x32_bf16 v[114:117], v[70:73], v[182:185], v[114:117]
	v_mfma_f32_16x16x32_bf16 v[114:117], v[82:85], v[186:189], v[114:117]
	v_mfma_f32_16x16x32_bf16 v[110:113], v[106:109], v[186:189], v[110:113]
	v_mfma_f32_16x16x32_bf16 v[110:113], v[94:97], v[182:185], v[110:113]
	v_mfma_f32_16x16x32_bf16 v[102:105], v[118:121], v[182:185], v[102:105]
	v_mfma_f32_16x16x32_bf16 v[102:105], v[130:133], v[186:189], v[102:105]
	v_mfma_f32_16x16x32_bf16 v[98:101], v[154:157], v[186:189], v[98:101]
	v_mfma_f32_16x16x32_bf16 v[98:101], v[142:145], v[182:185], v[98:101]
	v_mfma_f32_16x16x32_bf16 v[74:77], v[142:145], v[210:213], v[74:77]
	v_mfma_f32_16x16x32_bf16 v[74:77], v[154:157], v[214:217], v[74:77]
	v_mfma_f32_16x16x32_bf16 v[78:81], v[130:133], v[214:217], v[78:81]
	v_mfma_f32_16x16x32_bf16 v[78:81], v[118:121], v[210:213], v[78:81]
	v_mfma_f32_16x16x32_bf16 v[86:89], v[94:97], v[210:213], v[86:89]
	v_mfma_f32_16x16x32_bf16 v[86:89], v[106:109], v[214:217], v[86:89]
	v_mfma_f32_16x16x32_bf16 v[90:93], v[82:85], v[214:217], v[90:93]
	v_mfma_f32_16x16x32_bf16 v[90:93], v[70:73], v[210:213], v[90:93]
	s_barrier
	s_add_u32 s98, s70, 0x80
	s_addc_u32 s99, s71, 0
	s_add_u32 s100, s76, 0x80
	s_addc_u32 s101, s77, 0
	s_add_i32 s0, s8, s28
	s_mov_b32 m0, s0
	ds_read_b128 v[158:161], v237 offset:49152
	ds_read_b128 v[170:173], v237 offset:50176
	ds_read_b128 v[174:177], v237 offset:51200
	ds_read_b128 v[178:181], v237 offset:52224
	ds_read_b128 v[182:185], v237 offset:53248
	ds_read_b128 v[186:189], v237 offset:54272
	ds_read_b128 v[210:213], v237 offset:55296
	ds_read_b128 v[214:217], v237 offset:56320
	global_load_lds_dwordx4 v192, s[98:99] sc1
	s_add_i32 m0, s0, 0x2000
	s_add_u32 s0, s70, 0x160080
	s_addc_u32 s1, s71, 0
	s_add_i32 s8, s9, s28
	global_load_lds_dwordx4 v190, s[98:99] sc1
	s_mov_b32 m0, s8
	s_nop 0
	global_load_lds_dwordx4 v192, s[0:1] sc1
	s_add_i32 m0, s8, 0x2000
	s_nop 0
	global_load_lds_dwordx4 v190, s[0:1] sc1
	s_mov_b32 m0, s68
	s_nop 0
	global_load_lds_dwordx4 v192, s[100:101] sc1
	s_mov_b32 m0, s79
	s_nop 0
	global_load_lds_dwordx4 v190, s[100:101] sc1
	s_waitcnt vmcnt(8)
	s_waitcnt lgkmcnt(0)
	s_barrier
	s_waitcnt lgkmcnt(0)
	v_mfma_f32_16x16x32_bf16 v[62:65], v[70:73], v[158:161], v[62:65]
	v_mfma_f32_16x16x32_bf16 v[62:65], v[82:85], v[170:173], v[62:65]
	v_mfma_f32_16x16x32_bf16 v[58:61], v[106:109], v[170:173], v[58:61]
	v_mfma_f32_16x16x32_bf16 v[58:61], v[94:97], v[158:161], v[58:61]
	v_mfma_f32_16x16x32_bf16 v[54:57], v[118:121], v[158:161], v[54:57]
	v_mfma_f32_16x16x32_bf16 v[54:57], v[130:133], v[170:173], v[54:57]
	v_mfma_f32_16x16x32_bf16 v[50:53], v[154:157], v[170:173], v[50:53]
	v_mfma_f32_16x16x32_bf16 v[50:53], v[142:145], v[158:161], v[50:53]
	v_mfma_f32_16x16x32_bf16 v[34:37], v[142:145], v[174:177], v[34:37]
	v_mfma_f32_16x16x32_bf16 v[34:37], v[154:157], v[178:181], v[34:37]
	v_mfma_f32_16x16x32_bf16 v[38:41], v[130:133], v[178:181], v[38:41]
	v_mfma_f32_16x16x32_bf16 v[38:41], v[118:121], v[174:177], v[38:41]
	v_mfma_f32_16x16x32_bf16 v[42:45], v[94:97], v[174:177], v[42:45]
	v_mfma_f32_16x16x32_bf16 v[42:45], v[106:109], v[178:181], v[42:45]
	v_mfma_f32_16x16x32_bf16 v[46:49], v[82:85], v[178:181], v[46:49]
	v_mfma_f32_16x16x32_bf16 v[46:49], v[70:73], v[174:177], v[46:49]
	v_mfma_f32_16x16x32_bf16 v[30:33], v[70:73], v[182:185], v[30:33]
	v_mfma_f32_16x16x32_bf16 v[30:33], v[82:85], v[186:189], v[30:33]
	v_mfma_f32_16x16x32_bf16 v[26:29], v[106:109], v[186:189], v[26:29]
	v_mfma_f32_16x16x32_bf16 v[26:29], v[94:97], v[182:185], v[26:29]
	v_mfma_f32_16x16x32_bf16 v[22:25], v[118:121], v[182:185], v[22:25]
	v_mfma_f32_16x16x32_bf16 v[22:25], v[130:133], v[186:189], v[22:25]
	v_mfma_f32_16x16x32_bf16 v[18:21], v[154:157], v[186:189], v[18:21]
	v_mfma_f32_16x16x32_bf16 v[18:21], v[142:145], v[182:185], v[18:21]
	v_mfma_f32_16x16x32_bf16 v[2:5], v[142:145], v[210:213], v[2:5]
	v_mfma_f32_16x16x32_bf16 v[2:5], v[154:157], v[214:217], v[2:5]
	v_mfma_f32_16x16x32_bf16 v[6:9], v[130:133], v[214:217], v[6:9]
	v_mfma_f32_16x16x32_bf16 v[6:9], v[118:121], v[210:213], v[6:9]
	v_mfma_f32_16x16x32_bf16 v[10:13], v[94:97], v[210:213], v[10:13]
	v_mfma_f32_16x16x32_bf16 v[10:13], v[106:109], v[214:217], v[10:13]
	v_mfma_f32_16x16x32_bf16 v[14:17], v[82:85], v[214:217], v[14:17]
	v_mfma_f32_16x16x32_bf16 v[14:17], v[70:73], v[210:213], v[14:17]
	s_barrier
	s_add_i32 s41, s41, 2
	s_add_u32 s7, s7, 0x100
	s_addc_u32 s23, s23, 0
	s_cmpk_gt_u32 s41, 0x55
	s_mov_b64 s[8:9], s[64:65]
	s_cbranch_scc1 .LBB0_648

.Lpeel_disp_down:
	s_cmp_lg_u32 s41, -2
	s_cbranch_scc1 .LBB0_645
	s_add_u32 s64, s8, 0x100
	s_addc_u32 s65, s9, 0
	s_and_b64 s[0:1], s[70:71], exec
	s_cselect_b32 s77, s63, s65
	s_cselect_b32 s76, s62, s64
	s_cselect_b32 s71, s85, s23
	s_cselect_b32 s70, s84, s7
	s_add_i32 s0, 0, 0x10000
	s_add_i32 s18, 0, 0x14000
	v_add_u32_e32 v106, s0, v1
	v_add_u32_e32 v154, s18, v1
	ds_read_b128 v[70:73], v106
	ds_read_b128 v[82:85], v106 offset:1024
	ds_read_b128 v[94:97], v106 offset:2048
	ds_read_b128 v[106:109], v106 offset:3072
	ds_read_b128 v[118:121], v154
	ds_read_b128 v[130:133], v154 offset:1024
	ds_read_b128 v[142:145], v154 offset:2048
	ds_read_b128 v[154:157], v154 offset:3072
	s_add_i32 m0, s29, 0xc000
	ds_read_b128 v[158:161], v237
	ds_read_b128 v[170:173], v237 offset:1024
	ds_read_b128 v[174:177], v237 offset:2048
	ds_read_b128 v[178:181], v237 offset:3072
	ds_read_b128 v[182:185], v237 offset:4096
	ds_read_b128 v[186:189], v237 offset:5120
	ds_read_b128 v[210:213], v237 offset:6144
	ds_read_b128 v[214:217], v237 offset:7168
	global_load_lds_dwordx4 v206, s[8:9] sc1
	s_add_i32 m0, s29, 0xe000
	s_nop 0
	global_load_lds_dwordx4 v208, s[8:9] sc1
	s_waitcnt vmcnt(8)
	s_waitcnt lgkmcnt(0)
	s_barrier
	s_waitcnt lgkmcnt(0)
	v_mfma_f32_16x16x32_bf16 v[166:169], v[70:73], v[158:161], 0
	v_mfma_f32_16x16x32_bf16 v[166:169], v[82:85], v[170:173], v[166:169]
	v_mfma_f32_16x16x32_bf16 v[162:165], v[106:109], v[170:173], 0
	v_mfma_f32_16x16x32_bf16 v[162:165], v[94:97], v[158:161], v[162:165]
	v_mfma_f32_16x16x32_bf16 v[150:153], v[118:121], v[158:161], 0
	v_mfma_f32_16x16x32_bf16 v[150:153], v[130:133], v[170:173], v[150:153]
	v_mfma_f32_16x16x32_bf16 v[146:149], v[154:157], v[170:173], 0
	v_mfma_f32_16x16x32_bf16 v[146:149], v[142:145], v[158:161], v[146:149]
	v_mfma_f32_16x16x32_bf16 v[122:125], v[142:145], v[174:177], 0
	v_mfma_f32_16x16x32_bf16 v[122:125], v[154:157], v[178:181], v[122:125]
	v_mfma_f32_16x16x32_bf16 v[126:129], v[130:133], v[178:181], 0
	v_mfma_f32_16x16x32_bf16 v[126:129], v[118:121], v[174:177], v[126:129]
	v_mfma_f32_16x16x32_bf16 v[134:137], v[94:97], v[174:177], 0
	v_mfma_f32_16x16x32_bf16 v[134:137], v[106:109], v[178:181], v[134:137]
	v_mfma_f32_16x16x32_bf16 v[138:141], v[82:85], v[178:181], 0
	v_mfma_f32_16x16x32_bf16 v[138:141], v[70:73], v[174:177], v[138:141]
	v_mfma_f32_16x16x32_bf16 v[114:117], v[70:73], v[182:185], 0
	v_mfma_f32_16x16x32_bf16 v[114:117], v[82:85], v[186:189], v[114:117]
	v_mfma_f32_16x16x32_bf16 v[110:113], v[106:109], v[186:189], 0
	v_mfma_f32_16x16x32_bf16 v[110:113], v[94:97], v[182:185], v[110:113]
	v_mfma_f32_16x16x32_bf16 v[102:105], v[118:121], v[182:185], 0
	v_mfma_f32_16x16x32_bf16 v[102:105], v[130:133], v[186:189], v[102:105]
	v_mfma_f32_16x16x32_bf16 v[98:101], v[154:157], v[186:189], 0
	v_mfma_f32_16x16x32_bf16 v[98:101], v[142:145], v[182:185], v[98:101]
	v_mfma_f32_16x16x32_bf16 v[74:77], v[142:145], v[210:213], 0
	v_mfma_f32_16x16x32_bf16 v[74:77], v[154:157], v[214:217], v[74:77]
	v_mfma_f32_16x16x32_bf16 v[78:81], v[130:133], v[214:217], 0
	v_mfma_f32_16x16x32_bf16 v[78:81], v[118:121], v[210:213], v[78:81]
	v_mfma_f32_16x16x32_bf16 v[86:89], v[94:97], v[210:213], 0
	v_mfma_f32_16x16x32_bf16 v[86:89], v[106:109], v[214:217], v[86:89]
	v_mfma_f32_16x16x32_bf16 v[90:93], v[82:85], v[214:217], 0
	v_mfma_f32_16x16x32_bf16 v[90:93], v[70:73], v[210:213], v[90:93]
	s_barrier
	s_add_i32 s0, s0, s28
	s_mov_b32 m0, s0
	ds_read_b128 v[158:161], v237 offset:16384
	ds_read_b128 v[170:173], v237 offset:17408
	ds_read_b128 v[174:177], v237 offset:18432
	ds_read_b128 v[178:181], v237 offset:19456
	ds_read_b128 v[182:185], v237 offset:20480
	ds_read_b128 v[186:189], v237 offset:21504
	ds_read_b128 v[210:213], v237 offset:22528
	ds_read_b128 v[214:217], v237 offset:23552
	global_load_lds_dwordx4 v192, s[70:71] sc1
	s_add_i32 m0, s0, 0x2000
	s_add_u32 s0, s70, 0x160000
	s_addc_u32 s1, s71, 0
	s_add_i32 s8, s18, s28
	global_load_lds_dwordx4 v190, s[70:71] sc1
	s_mov_b32 m0, s8
	s_nop 0
	global_load_lds_dwordx4 v192, s[0:1] sc1
	s_add_i32 m0, s8, 0x2000
	s_nop 0
	global_load_lds_dwordx4 v190, s[0:1] sc1
	s_mov_b32 m0, s29
	s_nop 0
	global_load_lds_dwordx4 v192, s[76:77] sc1
	s_mov_b32 m0, s31
	s_nop 0
	global_load_lds_dwordx4 v190, s[76:77] sc1
	s_waitcnt vmcnt(8)
	s_waitcnt lgkmcnt(0)
	s_barrier
	s_waitcnt lgkmcnt(0)
	v_mfma_f32_16x16x32_bf16 v[62:65], v[70:73], v[158:161], 0
	v_mfma_f32_16x16x32_bf16 v[62:65], v[82:85], v[170:173], v[62:65]
	v_mfma_f32_16x16x32_bf16 v[58:61], v[106:109], v[170:173], 0
	v_mfma_f32_16x16x32_bf16 v[58:61], v[94:97], v[158:161], v[58:61]
	v_mfma_f32_16x16x32_bf16 v[54:57], v[118:121], v[158:161], 0
	v_mfma_f32_16x16x32_bf16 v[54:57], v[130:133], v[170:173], v[54:57]
	v_mfma_f32_16x16x32_bf16 v[50:53], v[154:157], v[170:173], 0
	v_mfma_f32_16x16x32_bf16 v[50:53], v[142:145], v[158:161], v[50:53]
	v_mfma_f32_16x16x32_bf16 v[34:37], v[142:145], v[174:177], 0
	v_mfma_f32_16x16x32_bf16 v[34:37], v[154:157], v[178:181], v[34:37]
	v_mfma_f32_16x16x32_bf16 v[38:41], v[130:133], v[178:181], 0
	v_mfma_f32_16x16x32_bf16 v[38:41], v[118:121], v[174:177], v[38:41]
	v_mfma_f32_16x16x32_bf16 v[42:45], v[94:97], v[174:177], 0
	v_mfma_f32_16x16x32_bf16 v[42:45], v[106:109], v[178:181], v[42:45]
	v_mfma_f32_16x16x32_bf16 v[46:49], v[82:85], v[178:181], 0
	v_mfma_f32_16x16x32_bf16 v[46:49], v[70:73], v[174:177], v[46:49]
	v_mfma_f32_16x16x32_bf16 v[30:33], v[70:73], v[182:185], 0
	v_mfma_f32_16x16x32_bf16 v[30:33], v[82:85], v[186:189], v[30:33]
	v_mfma_f32_16x16x32_bf16 v[26:29], v[106:109], v[186:189], 0
	v_mfma_f32_16x16x32_bf16 v[26:29], v[94:97], v[182:185], v[26:29]
	v_mfma_f32_16x16x32_bf16 v[22:25], v[118:121], v[182:185], 0
	v_mfma_f32_16x16x32_bf16 v[22:25], v[130:133], v[186:189], v[22:25]
	v_mfma_f32_16x16x32_bf16 v[18:21], v[154:157], v[186:189], 0
	v_mfma_f32_16x16x32_bf16 v[18:21], v[142:145], v[182:185], v[18:21]
	v_mfma_f32_16x16x32_bf16 v[2:5], v[142:145], v[210:213], 0
	v_mfma_f32_16x16x32_bf16 v[2:5], v[154:157], v[214:217], v[2:5]
	v_mfma_f32_16x16x32_bf16 v[6:9], v[130:133], v[214:217], 0
	v_mfma_f32_16x16x32_bf16 v[6:9], v[118:121], v[210:213], v[6:9]
	v_mfma_f32_16x16x32_bf16 v[10:13], v[94:97], v[210:213], 0
	v_mfma_f32_16x16x32_bf16 v[10:13], v[106:109], v[214:217], v[10:13]
	v_mfma_f32_16x16x32_bf16 v[14:17], v[82:85], v[214:217], 0
	v_mfma_f32_16x16x32_bf16 v[14:17], v[70:73], v[210:213], v[14:17]
	s_barrier
	s_add_i32 s8, 0, 0x18000
	s_add_i32 s9, 0, 0x1c000
	v_add_u32_e32 v106, s8, v1
	v_add_u32_e32 v154, s9, v1
	ds_read_b128 v[70:73], v106
	ds_read_b128 v[82:85], v106 offset:1024
	ds_read_b128 v[94:97], v106 offset:2048
	ds_read_b128 v[106:109], v106 offset:3072
	ds_read_b128 v[118:121], v154
	ds_read_b128 v[130:133], v154 offset:1024
	ds_read_b128 v[142:145], v154 offset:2048
	ds_read_b128 v[154:157], v154 offset:3072
	s_add_u32 s0, s76, 0x160000
	s_addc_u32 s1, s77, 0
	s_mov_b32 m0, s33
	ds_read_b128 v[158:161], v237 offset:32768
	ds_read_b128 v[170:173], v237 offset:33792
	ds_read_b128 v[174:177], v237 offset:34816
	ds_read_b128 v[178:181], v237 offset:35840
	ds_read_b128 v[182:185], v237 offset:36864
	ds_read_b128 v[186:189], v237 offset:37888
	ds_read_b128 v[210:213], v237 offset:38912
	ds_read_b128 v[214:217], v237 offset:39936
	global_load_lds_dwordx4 v192, s[0:1] sc1
	s_mov_b32 m0, s43
	s_nop 0
	global_load_lds_dwordx4 v190, s[0:1] sc1
	s_waitcnt vmcnt(8)
	s_waitcnt lgkmcnt(0)
	s_barrier
	s_waitcnt lgkmcnt(0)
	v_mfma_f32_16x16x32_bf16 v[166:169], v[70:73], v[158:161], v[166:169]
	v_mfma_f32_16x16x32_bf16 v[166:169], v[82:85], v[170:173], v[166:169]
	v_mfma_f32_16x16x32_bf16 v[162:165], v[106:109], v[170:173], v[162:165]
	v_mfma_f32_16x16x32_bf16 v[162:165], v[94:97], v[158:161], v[162:165]
	v_mfma_f32_16x16x32_bf16 v[150:153], v[118:121], v[158:161], v[150:153]
	v_mfma_f32_16x16x32_bf16 v[150:153], v[130:133], v[170:173], v[150:153]
	v_mfma_f32_16x16x32_bf16 v[146:149], v[154:157], v[170:173], v[146:149]
	v_mfma_f32_16x16x32_bf16 v[146:149], v[142:145], v[158:161], v[146:149]
	v_mfma_f32_16x16x32_bf16 v[122:125], v[142:145], v[174:177], v[122:125]
	v_mfma_f32_16x16x32_bf16 v[122:125], v[154:157], v[178:181], v[122:125]
	v_mfma_f32_16x16x32_bf16 v[126:129], v[130:133], v[178:181], v[126:129]
	v_mfma_f32_16x16x32_bf16 v[126:129], v[118:121], v[174:177], v[126:129]
	v_mfma_f32_16x16x32_bf16 v[134:137], v[94:97], v[174:177], v[134:137]
	v_mfma_f32_16x16x32_bf16 v[134:137], v[106:109], v[178:181], v[134:137]
	v_mfma_f32_16x16x32_bf16 v[138:141], v[82:85], v[178:181], v[138:141]
	v_mfma_f32_16x16x32_bf16 v[138:141], v[70:73], v[174:177], v[138:141]
	v_mfma_f32_16x16x32_bf16 v[114:117], v[70:73], v[182:185], v[114:117]
	v_mfma_f32_16x16x32_bf16 v[114:117], v[82:85], v[186:189], v[114:117]
	v_mfma_f32_16x16x32_bf16 v[110:113], v[106:109], v[186:189], v[110:113]
	v_mfma_f32_16x16x32_bf16 v[110:113], v[94:97], v[182:185], v[110:113]
	v_mfma_f32_16x16x32_bf16 v[102:105], v[118:121], v[182:185], v[102:105]
	v_mfma_f32_16x16x32_bf16 v[102:105], v[130:133], v[186:189], v[102:105]
	v_mfma_f32_16x16x32_bf16 v[98:101], v[154:157], v[186:189], v[98:101]
	v_mfma_f32_16x16x32_bf16 v[98:101], v[142:145], v[182:185], v[98:101]
	v_mfma_f32_16x16x32_bf16 v[74:77], v[142:145], v[210:213], v[74:77]
	v_mfma_f32_16x16x32_bf16 v[74:77], v[154:157], v[214:217], v[74:77]
	v_mfma_f32_16x16x32_bf16 v[78:81], v[130:133], v[214:217], v[78:81]
	v_mfma_f32_16x16x32_bf16 v[78:81], v[118:121], v[210:213], v[78:81]
	v_mfma_f32_16x16x32_bf16 v[86:89], v[94:97], v[210:213], v[86:89]
	v_mfma_f32_16x16x32_bf16 v[86:89], v[106:109], v[214:217], v[86:89]
	v_mfma_f32_16x16x32_bf16 v[90:93], v[82:85], v[214:217], v[90:93]
	v_mfma_f32_16x16x32_bf16 v[90:93], v[70:73], v[210:213], v[90:93]
	s_barrier
	s_add_u32 s98, s70, 0x80
	s_addc_u32 s99, s71, 0
	s_add_u32 s100, s76, 0x80
	s_addc_u32 s101, s77, 0
	s_add_i32 s0, s8, s28
	s_mov_b32 m0, s0
	ds_read_b128 v[158:161], v237 offset:49152
	ds_read_b128 v[170:173], v237 offset:50176
	ds_read_b128 v[174:177], v237 offset:51200
	ds_read_b128 v[178:181], v237 offset:52224
	ds_read_b128 v[182:185], v237 offset:53248
	ds_read_b128 v[186:189], v237 offset:54272
	ds_read_b128 v[210:213], v237 offset:55296
	ds_read_b128 v[214:217], v237 offset:56320
	global_load_lds_dwordx4 v192, s[98:99] sc1
	s_add_i32 m0, s0, 0x2000
	s_add_u32 s0, s70, 0x160080
	s_addc_u32 s1, s71, 0
	s_add_i32 s8, s9, s28
	global_load_lds_dwordx4 v190, s[98:99] sc1
	s_mov_b32 m0, s8
	s_nop 0
	global_load_lds_dwordx4 v192, s[0:1] sc1
	s_add_i32 m0, s8, 0x2000
	s_nop 0
	global_load_lds_dwordx4 v190, s[0:1] sc1
	s_mov_b32 m0, s68
	s_nop 0
	global_load_lds_dwordx4 v192, s[100:101] sc1
	s_mov_b32 m0, s79
	s_nop 0
	global_load_lds_dwordx4 v190, s[100:101] sc1
	s_waitcnt vmcnt(8)
	s_waitcnt lgkmcnt(0)
	s_barrier
	s_waitcnt lgkmcnt(0)
	v_mfma_f32_16x16x32_bf16 v[62:65], v[70:73], v[158:161], v[62:65]
	v_mfma_f32_16x16x32_bf16 v[62:65], v[82:85], v[170:173], v[62:65]
	v_mfma_f32_16x16x32_bf16 v[58:61], v[106:109], v[170:173], v[58:61]
	v_mfma_f32_16x16x32_bf16 v[58:61], v[94:97], v[158:161], v[58:61]
	v_mfma_f32_16x16x32_bf16 v[54:57], v[118:121], v[158:161], v[54:57]
	v_mfma_f32_16x16x32_bf16 v[54:57], v[130:133], v[170:173], v[54:57]
	v_mfma_f32_16x16x32_bf16 v[50:53], v[154:157], v[170:173], v[50:53]
	v_mfma_f32_16x16x32_bf16 v[50:53], v[142:145], v[158:161], v[50:53]
	v_mfma_f32_16x16x32_bf16 v[34:37], v[142:145], v[174:177], v[34:37]
	v_mfma_f32_16x16x32_bf16 v[34:37], v[154:157], v[178:181], v[34:37]
	v_mfma_f32_16x16x32_bf16 v[38:41], v[130:133], v[178:181], v[38:41]
	v_mfma_f32_16x16x32_bf16 v[38:41], v[118:121], v[174:177], v[38:41]
	v_mfma_f32_16x16x32_bf16 v[42:45], v[94:97], v[174:177], v[42:45]
	v_mfma_f32_16x16x32_bf16 v[42:45], v[106:109], v[178:181], v[42:45]
	v_mfma_f32_16x16x32_bf16 v[46:49], v[82:85], v[178:181], v[46:49]
	v_mfma_f32_16x16x32_bf16 v[46:49], v[70:73], v[174:177], v[46:49]
	v_mfma_f32_16x16x32_bf16 v[30:33], v[70:73], v[182:185], v[30:33]
	v_mfma_f32_16x16x32_bf16 v[30:33], v[82:85], v[186:189], v[30:33]
	v_mfma_f32_16x16x32_bf16 v[26:29], v[106:109], v[186:189], v[26:29]
	v_mfma_f32_16x16x32_bf16 v[26:29], v[94:97], v[182:185], v[26:29]
	v_mfma_f32_16x16x32_bf16 v[22:25], v[118:121], v[182:185], v[22:25]
	v_mfma_f32_16x16x32_bf16 v[22:25], v[130:133], v[186:189], v[22:25]
	v_mfma_f32_16x16x32_bf16 v[18:21], v[154:157], v[186:189], v[18:21]
	v_mfma_f32_16x16x32_bf16 v[18:21], v[142:145], v[182:185], v[18:21]
	v_mfma_f32_16x16x32_bf16 v[2:5], v[142:145], v[210:213], v[2:5]
	v_mfma_f32_16x16x32_bf16 v[2:5], v[154:157], v[214:217], v[2:5]
	v_mfma_f32_16x16x32_bf16 v[6:9], v[130:133], v[214:217], v[6:9]
	v_mfma_f32_16x16x32_bf16 v[6:9], v[118:121], v[210:213], v[6:9]
	v_mfma_f32_16x16x32_bf16 v[10:13], v[94:97], v[210:213], v[10:13]
	v_mfma_f32_16x16x32_bf16 v[10:13], v[106:109], v[214:217], v[10:13]
	v_mfma_f32_16x16x32_bf16 v[14:17], v[82:85], v[214:217], v[14:17]
	v_mfma_f32_16x16x32_bf16 v[14:17], v[70:73], v[210:213], v[14:17]
	s_barrier
	s_add_i32 s41, s41, 2
	s_add_u32 s7, s7, 0x100
	s_addc_u32 s23, s23, 0
	s_cmpk_gt_u32 s41, 0x55
	s_mov_b64 s[8:9], s[64:65]
	s_cbranch_scc1 .LBB0_648
	s_branch .LBB0_646
